# long-scan waves no longer raise their priority (the co-resident weight-conversion waves had become the layer-0 critical path)
# baseline (speedup 1.0000x reference)
.Lls3_16_entry:
	v_and_b32_e32 v124, 63, v196
	v_and_b32_e32 v125, 15, v124
	v_lshrrev_b32_e32 v126, 4, v124
	s_min_u32 s29, s0, 4
	s_mul_i32 s29, s29, 0x5600
	v_and_b32_e32 v127, 3, v125
	v_cmp_eq_u32_e64 s[6:7], 1, v127
	v_cmp_eq_u32_e64 s[8:9], 2, v127
	v_cmp_eq_u32_e64 s[10:11], 3, v127
	v_lshl_add_u32 v0, v125, 4, s29
	v_lshl_add_u32 v1, v126, 4, s29
	s_lshl_b32 s37, s16, 11
	v_lshrrev_b32_e32 v125, 3, v124
	v_and_b32_e32 v126, 7, v124
	v_add_u32_e32 v127, s37, v125
	s_lshl_b32 s21, s17, 7
	s_add_u32 s21, s21, 0x10800700
	v_mul_u32_u24_e32 v5, 0xd00, v127
	v_lshl_add_u32 v5, v126, 4, v5
	v_add_u32_e32 v5, s21, v5
	v_lshlrev_b32_e32 v2, 8, v125
	v_lshl_add_u32 v2, v126, 5, v2
	v_add_u32_e32 v2, s29, v2
	v_and_b32_e32 v125, 31, v124
	v_lshrrev_b32_e32 v126, 2, v125
	v_and_b32_e32 v125, 3, v125
	v_add_u32_e32 v127, s37, v126
	s_lshl_b32 s22, s14, 2
	s_lshl_b32 s21, s17, 6
	s_add_u32 s21, s21, s22
	s_lshl_b32 s44, s21, 1
	s_add_u32 s44, s44, 0x10800b00
	v_mul_u32_u24_e32 v6, 0xd00, v127
	s_lshl_b32 s24, s17, 2
	s_add_u32 s24, s24, 0x13e00600
	v_mul_u32_u24_e32 v8, 0x630, v127
	v_lshl_add_u32 v8, v125, 4, v8
	v_add_u32_e32 v8, s24, v8
	v_lshlrev_b32_e32 v4, 6, v126
	v_lshl_add_u32 v4, v125, 4, v4
	v_lshl_add_u32 v6, v125, 1, v6
	v_add_u32_e32 v6, s44, v6
	v_add_u32_e32 v4, s29, v4
	v_and_b32_e32 v125, 15, v124
	v_lshrrev_b32_e32 v126, 4, v124
	v_add_u32_e32 v127, s37, v124
	v_lshlrev_b32_e32 v7, 11, v127
	s_lshl_b32 s44, s21, 1
	s_add_u32 s44, s44, 0x6300600
	v_add_u32_e32 v7, s44, v7
	s_lshl_b32 s44, s28, 3
	s_add_u32 s44, s44, s16
	s_lshl_b32 s44, s44, 2
	s_add_u32 s44, s44, s17
	s_mul_i32 s44, s44, 0x4000
	s_add_u32 s44, s44, 0x4480000
	s_lshl_b32 s24, s22, 2
	s_add_u32 s44, s44, s24
	v_lshlrev_b32_e32 v130, 10, v125
	v_lshl_add_u32 v130, v126, 2, v130
	v_add_u32_e32 v130, s44, v130
	v_readlane_b32 s26, v253, 29
	v_readlane_b32 s27, v253, 30
	v_lshlrev_b32_e32 v131, 3, v125
	v_lshl_add_u32 v131, v126, 1, v131
	v_add_u32_e32 v131, s29, v131
	v_lshl_add_u32 v132, v124, 3, s29
	v_lshl_add_u32 v133, v124, 2, s29
	v_lshl_add_u32 v131, v124, 1, s29
	v_subrev_u32_e32 v131, 0x100, v131
	v_lshrrev_b32_e32 v125, 2, v124
	v_and_b32_e32 v126, 3, v124
	v_lshlrev_b32_e32 v127, 8, v125
	v_lshl_add_u32 v127, v126, 6, v127
	v_add_u32_e32 v127, s29, v127
	v_add_u32_e32 v126, 0, v125
	v_and_b32_e32 v126, 3, v126
	v_lshl_add_u32 v136, v126, 4, v127
	v_add_u32_e32 v126, 1, v125
	v_and_b32_e32 v126, 3, v126
	v_lshl_add_u32 v137, v126, 4, v127
	v_add_u32_e32 v126, 2, v125
	v_and_b32_e32 v126, 3, v126
	v_lshl_add_u32 v138, v126, 4, v127
	v_add_u32_e32 v126, 3, v125
	v_and_b32_e32 v126, 3, v126
	v_lshl_add_u32 v139, v126, 4, v127
	v_mov_b32_e32 v10, 0
	v_mov_b32_e32 v11, 0
	v_mov_b32_e32 v12, 0
	v_mov_b32_e32 v13, 0
	v_mov_b32_e32 v9, 0
	v_mov_b32_e32 v14, 0
	v_mov_b32_e32 v15, 0
	v_mov_b32_e32 v16, 0
	v_mov_b32_e32 v81, 0
	v_mov_b32_e32 v93, 0
	v_mov_b32_e32 v105, 0
	v_mov_b32_e32 v117, 0
	s_movk_i32 s12, 64
	s_nop 0
	global_load_dwordx4 v[70:73], v5, s[94:95]
	global_load_dwordx4 v[74:77], v5, s[94:95] offset:512
	global_load_ushort v78, v6, s[94:95]
	global_load_dword v79, v8, s[94:95]
	v_add_u32_e32 v5, 0x6800, v5
	v_add_u32_e32 v6, 0x6800, v6
	v_add_u32_e32 v8, 0x3180, v8
	s_waitcnt vmcnt(0)
	s_waitcnt vmcnt(2)
	v_lshlrev_b32_e32 v118, 16, v74
	v_and_b32_e32 v119, 0xffff0000, v74
	v_lshlrev_b32_e32 v120, 16, v75
	v_and_b32_e32 v121, 0xffff0000, v75
	ds_write_b128 v2, v[118:121] offset:0
	v_lshlrev_b32_e32 v124, 16, v76
	v_and_b32_e32 v125, 0xffff0000, v76
	v_lshlrev_b32_e32 v126, 16, v77
	v_and_b32_e32 v127, 0xffff0000, v77
	ds_write_b128 v2, v[124:127] offset:16
	v_lshlrev_b32_e32 v118, 16, v70
	v_and_b32_e32 v119, 0xffff0000, v70
	v_lshlrev_b32_e32 v120, 16, v71
	v_and_b32_e32 v121, 0xffff0000, v71
	ds_write_b128 v2, v[118:121] offset:2048
	v_lshlrev_b32_e32 v124, 16, v72
	v_and_b32_e32 v125, 0xffff0000, v72
	v_lshlrev_b32_e32 v126, 16, v73
	v_and_b32_e32 v127, 0xffff0000, v73
	ds_write_b128 v2, v[124:127] offset:2064
	s_waitcnt vmcnt(0)
	v_mov_b32_dpp v80, v79 quad_perm:[1,1,1,1] row_mask:0xf bank_mask:0xf
	v_mov_b32_dpp v79, v79 quad_perm:[0,0,0,0] row_mask:0xf bank_mask:0xf
	v_lshlrev_b32_e32 v78, 16, v78
	v_mul_f32_e32 v78, v79, v78
	v_mul_f32_e32 v79, v79, v80
	s_nop 0
	ds_write_b128 v4, v[78:81] offset:4096
	global_load_dwordx4 v[82:85], v5, s[94:95]
	global_load_dwordx4 v[86:89], v5, s[94:95] offset:512
	global_load_ushort v90, v6, s[94:95]
	global_load_dword v91, v8, s[94:95]
	v_add_u32_e32 v5, 0x6800, v5
	v_add_u32_e32 v6, 0x6800, v6
	v_add_u32_e32 v8, 0x3180, v8
	global_load_dwordx4 v[94:97], v5, s[94:95]
	global_load_dwordx4 v[98:101], v5, s[94:95] offset:512
	global_load_ushort v102, v6, s[94:95]
	global_load_dword v103, v8, s[94:95]
	v_add_u32_e32 v5, 0x6800, v5
	v_add_u32_e32 v6, 0x6800, v6
	v_add_u32_e32 v8, 0x3180, v8
	global_load_dwordx4 v[106:109], v5, s[94:95]
	global_load_dwordx4 v[110:113], v5, s[94:95] offset:512
	global_load_ushort v114, v6, s[94:95]
	global_load_dword v115, v8, s[94:95]
	v_add_u32_e32 v5, 0x6800, v5
	v_add_u32_e32 v6, 0x6800, v6
	v_add_u32_e32 v8, 0x3180, v8
	global_load_dwordx4 v[70:73], v5, s[94:95]
	global_load_dwordx4 v[74:77], v5, s[94:95] offset:512
	global_load_ushort v78, v6, s[94:95]
	global_load_dword v79, v8, s[94:95]
	v_add_u32_e32 v5, 0x6800, v5
	v_add_u32_e32 v6, 0x6800, v6
	v_add_u32_e32 v8, 0x3180, v8
	ds_read_b128 v[20:23], v0 offset:0
	ds_read_b128 v[38:41], v0 offset:2048
	ds_read_b128 v[54:57], v1 offset:4096
	ds_read_b128 v[24:27], v0 offset:256
	ds_read_b128 v[42:45], v0 offset:2304
	ds_read_b128 v[58:61], v1 offset:4160
	ds_read_b128 v[28:31], v0 offset:512
	ds_read_b128 v[46:49], v0 offset:2560
	ds_read_b128 v[62:65], v1 offset:4224

.Lls3_16_noflush:
	s_waitcnt lgkmcnt(9)
	v_mul_f32_e32 v36, v32, v10
	v_fmac_f32_e32 v36, v33, v11
	v_fmac_f32_e32 v36, v34, v12
	v_fmac_f32_e32 v36, v35, v13
	v_mul_f32_e32 v10, v68, v10
	v_mul_f32_e32 v11, v68, v11
	v_add_f32_dpp v36, v36, v36 quad_perm:[1,0,3,2] row_mask:0xf bank_mask:0xf bound_ctrl:1
	v_mul_f32_e32 v12, v68, v12
	v_mul_f32_e32 v13, v68, v13
	v_add_f32_dpp v36, v36, v36 quad_perm:[2,3,0,1] row_mask:0xf bank_mask:0xf bound_ctrl:1
	ds_read_b128 v[28:31], v0 offset:5120
	ds_read_b128 v[46:49], v0 offset:7168
	v_add_f32_dpp v36, v36, v36 row_half_mirror row_mask:0xf bank_mask:0xf bound_ctrl:1
	ds_read_b128 v[62:65], v1 offset:8832
	s_nop 0
	v_add_f32_dpp v36, v36, v36 row_mirror row_mask:0xf bank_mask:0xf bound_ctrl:1
	s_nop 0
	v_fma_f32 v19, -v67, v36, v66
	v_fmac_f32_e32 v10, v32, v19
	v_fmac_f32_e32 v11, v33, v19
	v_fmac_f32_e32 v12, v34, v19
	v_fmac_f32_e32 v13, v35, v19
	v_mul_f32_e32 v122, v50, v10
	v_fmac_f32_e32 v122, v51, v11
	v_fmac_f32_e32 v122, v52, v12
	v_fmac_f32_e32 v122, v53, v13
	ds_write_b32 v133, v122 offset:11008
	s_waitcnt lgkmcnt(10)
	v_mul_f32_e32 v36, v20, v10
	v_fmac_f32_e32 v36, v21, v11
	v_fmac_f32_e32 v36, v22, v12
	v_fmac_f32_e32 v36, v23, v13
	v_mul_f32_e32 v10, v56, v10
	v_mul_f32_e32 v11, v56, v11
	v_add_f32_dpp v36, v36, v36 quad_perm:[1,0,3,2] row_mask:0xf bank_mask:0xf bound_ctrl:1
	v_mul_f32_e32 v12, v56, v12
	v_mul_f32_e32 v13, v56, v13
	v_add_f32_dpp v36, v36, v36 quad_perm:[2,3,0,1] row_mask:0xf bank_mask:0xf bound_ctrl:1
	s_waitcnt vmcnt(14)
	v_lshlrev_b32_e32 v118, 16, v98
	v_add_f32_dpp v36, v36, v36 row_half_mirror row_mask:0xf bank_mask:0xf bound_ctrl:1
	v_and_b32_e32 v119, 0xffff0000, v98
	v_lshlrev_b32_e32 v120, 16, v99
	v_add_f32_dpp v36, v36, v36 row_mirror row_mask:0xf bank_mask:0xf bound_ctrl:1
	v_and_b32_e32 v121, 0xffff0000, v99
	v_fma_f32 v19, -v55, v36, v54
	v_fmac_f32_e32 v10, v20, v19
	v_fmac_f32_e32 v11, v21, v19
	v_fmac_f32_e32 v12, v22, v19
	v_fmac_f32_e32 v13, v23, v19
	v_mul_f32_e32 v122, v38, v10
	v_fmac_f32_e32 v122, v39, v11
	v_fmac_f32_e32 v122, v40, v12
	v_fmac_f32_e32 v122, v41, v13
	ds_write_b32 v133, v122 offset:11264
	ds_read_b128 v[32:35], v0 offset:5376
	ds_read_b128 v[50:53], v0 offset:7424
	ds_read_b128 v[66:69], v1 offset:8896
	ds_write_b128 v2, v[118:121] offset:0
	v_lshlrev_b32_e32 v124, 16, v100
	v_and_b32_e32 v125, 0xffff0000, v100
	s_waitcnt lgkmcnt(10)
	v_mul_f32_e32 v36, v24, v10
	v_fmac_f32_e32 v36, v25, v11
	v_fmac_f32_e32 v36, v26, v12
	v_fmac_f32_e32 v36, v27, v13
	v_mul_f32_e32 v10, v60, v10
	v_mul_f32_e32 v11, v60, v11
	v_add_f32_dpp v36, v36, v36 quad_perm:[1,0,3,2] row_mask:0xf bank_mask:0xf bound_ctrl:1
	v_mul_f32_e32 v12, v60, v12
	v_mul_f32_e32 v13, v60, v13
	v_add_f32_dpp v36, v36, v36 quad_perm:[2,3,0,1] row_mask:0xf bank_mask:0xf bound_ctrl:1
	v_lshlrev_b32_e32 v126, 16, v101
	v_and_b32_e32 v127, 0xffff0000, v101
	v_add_f32_dpp v36, v36, v36 row_half_mirror row_mask:0xf bank_mask:0xf bound_ctrl:1
	ds_write_b128 v2, v[124:127] offset:16
	v_lshlrev_b32_e32 v118, 16, v94
	v_add_f32_dpp v36, v36, v36 row_mirror row_mask:0xf bank_mask:0xf bound_ctrl:1
	v_and_b32_e32 v119, 0xffff0000, v94
	v_fma_f32 v19, -v59, v36, v58
	v_fmac_f32_e32 v10, v24, v19
	v_fmac_f32_e32 v11, v25, v19
	v_fmac_f32_e32 v12, v26, v19
	v_fmac_f32_e32 v13, v27, v19
	v_mul_f32_e32 v122, v42, v10
	v_fmac_f32_e32 v122, v43, v11
	v_fmac_f32_e32 v122, v44, v12
	v_fmac_f32_e32 v122, v45, v13
	ds_write_b32 v133, v122 offset:11520
	ds_read_b128 v[20:23], v0 offset:5632
	ds_read_b128 v[38:41], v0 offset:7680
	ds_read_b128 v[54:57], v1 offset:8960
	v_lshlrev_b32_e32 v120, 16, v95
	v_and_b32_e32 v121, 0xffff0000, v95
	ds_write_b128 v2, v[118:121] offset:2048
	s_waitcnt lgkmcnt(12)
	v_mul_f32_e32 v36, v28, v10
	v_fmac_f32_e32 v36, v29, v11
	v_fmac_f32_e32 v36, v30, v12
	v_fmac_f32_e32 v36, v31, v13
	v_mul_f32_e32 v10, v64, v10
	v_mul_f32_e32 v11, v64, v11
	v_add_f32_dpp v36, v36, v36 quad_perm:[1,0,3,2] row_mask:0xf bank_mask:0xf bound_ctrl:1
	v_mul_f32_e32 v12, v64, v12
	v_mul_f32_e32 v13, v64, v13
	v_add_f32_dpp v36, v36, v36 quad_perm:[2,3,0,1] row_mask:0xf bank_mask:0xf bound_ctrl:1
	v_lshlrev_b32_e32 v124, 16, v96
	v_and_b32_e32 v125, 0xffff0000, v96
	v_add_f32_dpp v36, v36, v36 row_half_mirror row_mask:0xf bank_mask:0xf bound_ctrl:1
	v_lshlrev_b32_e32 v126, 16, v97
	v_and_b32_e32 v127, 0xffff0000, v97
	v_add_f32_dpp v36, v36, v36 row_mirror row_mask:0xf bank_mask:0xf bound_ctrl:1
	ds_write_b128 v2, v[124:127] offset:2064
	v_fma_f32 v19, -v63, v36, v62
	v_fmac_f32_e32 v10, v28, v19
	v_fmac_f32_e32 v11, v29, v19
	v_fmac_f32_e32 v12, v30, v19
	v_fmac_f32_e32 v13, v31, v19
	v_mul_f32_e32 v122, v46, v10
	v_fmac_f32_e32 v122, v47, v11
	v_fmac_f32_e32 v122, v48, v12
	v_fmac_f32_e32 v122, v49, v13
	ds_write_b32 v133, v122 offset:11776
	ds_read_b128 v[24:27], v0 offset:5888
	ds_read_b128 v[42:45], v0 offset:7936
	ds_read_b128 v[58:61], v1 offset:9024
	s_waitcnt vmcnt(12)
	v_mov_b32_dpp v104, v103 quad_perm:[1,1,1,1] row_mask:0xf bank_mask:0xf
	v_mov_b32_dpp v103, v103 quad_perm:[0,0,0,0] row_mask:0xf bank_mask:0xf
	s_waitcnt lgkmcnt(12)
	v_mul_f32_e32 v36, v32, v10
	v_fmac_f32_e32 v36, v33, v11
	v_fmac_f32_e32 v36, v34, v12
	v_fmac_f32_e32 v36, v35, v13
	v_mul_f32_e32 v10, v68, v10
	v_mul_f32_e32 v11, v68, v11
	v_add_f32_dpp v36, v36, v36 quad_perm:[1,0,3,2] row_mask:0xf bank_mask:0xf bound_ctrl:1
	v_mul_f32_e32 v12, v68, v12
	v_mul_f32_e32 v13, v68, v13
	v_add_f32_dpp v36, v36, v36 quad_perm:[2,3,0,1] row_mask:0xf bank_mask:0xf bound_ctrl:1
	v_lshlrev_b32_e32 v102, 16, v102
	v_mul_f32_e32 v102, v103, v102
	v_add_f32_dpp v36, v36, v36 row_half_mirror row_mask:0xf bank_mask:0xf bound_ctrl:1
	v_mul_f32_e32 v103, v103, v104
	s_nop 0
	v_add_f32_dpp v36, v36, v36 row_mirror row_mask:0xf bank_mask:0xf bound_ctrl:1
	ds_write_b128 v4, v[102:105] offset:4096
	v_fma_f32 v19, -v67, v36, v66
	v_fmac_f32_e32 v10, v32, v19
	v_fmac_f32_e32 v11, v33, v19
	v_fmac_f32_e32 v12, v34, v19
	v_fmac_f32_e32 v13, v35, v19
	v_mul_f32_e32 v122, v50, v10
	v_fmac_f32_e32 v122, v51, v11
	v_fmac_f32_e32 v122, v52, v12
	v_fmac_f32_e32 v122, v53, v13
	ds_write_b32 v133, v122 offset:12032
	ds_read_b128 v[28:31], v0 offset:6144
	ds_read_b128 v[46:49], v0 offset:8192
	ds_read_b128 v[62:65], v1 offset:9088
	s_waitcnt lgkmcnt(11)
	v_mul_f32_e32 v36, v20, v10
	v_fmac_f32_e32 v36, v21, v11
	v_fmac_f32_e32 v36, v22, v12
	v_fmac_f32_e32 v36, v23, v13
	v_mul_f32_e32 v10, v56, v10
	v_mul_f32_e32 v11, v56, v11
	v_add_f32_dpp v36, v36, v36 quad_perm:[1,0,3,2] row_mask:0xf bank_mask:0xf bound_ctrl:1
	v_mul_f32_e32 v12, v56, v12
	v_mul_f32_e32 v13, v56, v13
	v_add_f32_dpp v36, v36, v36 quad_perm:[2,3,0,1] row_mask:0xf bank_mask:0xf bound_ctrl:1
	global_load_dwordx4 v[94:97], v5, s[94:95]
	global_load_dwordx4 v[98:101], v5, s[94:95] offset:512
	global_load_ushort v102, v6, s[94:95]
	global_load_dword v103, v8, s[94:95]
	v_add_u32_e32 v5, 0x6800, v5
	v_add_u32_e32 v6, 0x6800, v6
	v_add_u32_e32 v8, 0x3180, v8
	ds_read_b128 v[32:35], v0 offset:6400
	v_add_f32_dpp v36, v36, v36 row_half_mirror row_mask:0xf bank_mask:0xf bound_ctrl:1
	ds_read_b128 v[50:53], v0 offset:8448
	ds_read_b128 v[66:69], v1 offset:9152
	v_add_f32_dpp v36, v36, v36 row_mirror row_mask:0xf bank_mask:0xf bound_ctrl:1
	s_nop 0
	v_fma_f32 v19, -v55, v36, v54
	v_fmac_f32_e32 v10, v20, v19
	v_fmac_f32_e32 v11, v21, v19
	v_fmac_f32_e32 v12, v22, v19
	v_fmac_f32_e32 v13, v23, v19
	v_mul_f32_e32 v122, v38, v10
	v_fmac_f32_e32 v122, v39, v11
	v_fmac_f32_e32 v122, v40, v12
	v_fmac_f32_e32 v122, v41, v13
	ds_write_b32 v133, v122 offset:12288
	s_waitcnt lgkmcnt(9)
	v_mul_f32_e32 v36, v24, v10
	v_fmac_f32_e32 v36, v25, v11
	v_fmac_f32_e32 v36, v26, v12
	v_fmac_f32_e32 v36, v27, v13
	v_mul_f32_e32 v10, v60, v10
	v_mul_f32_e32 v11, v60, v11
	v_add_f32_dpp v36, v36, v36 quad_perm:[1,0,3,2] row_mask:0xf bank_mask:0xf bound_ctrl:1
	v_mul_f32_e32 v12, v60, v12
	v_mul_f32_e32 v13, v60, v13
	v_add_f32_dpp v36, v36, v36 quad_perm:[2,3,0,1] row_mask:0xf bank_mask:0xf bound_ctrl:1
	ds_read_b128 v[20:23], v0 offset:0
	ds_read_b128 v[38:41], v0 offset:2048
	v_add_f32_dpp v36, v36, v36 row_half_mirror row_mask:0xf bank_mask:0xf bound_ctrl:1
	ds_read_b128 v[54:57], v1 offset:4096
	s_nop 0
	v_add_f32_dpp v36, v36, v36 row_mirror row_mask:0xf bank_mask:0xf bound_ctrl:1
	s_nop 0
	v_fma_f32 v19, -v59, v36, v58
	v_fmac_f32_e32 v10, v24, v19
	v_fmac_f32_e32 v11, v25, v19
	v_fmac_f32_e32 v12, v26, v19
	v_fmac_f32_e32 v13, v27, v19
	v_mul_f32_e32 v122, v42, v10
	v_fmac_f32_e32 v122, v43, v11
	v_fmac_f32_e32 v122, v44, v12
	v_fmac_f32_e32 v122, v45, v13
	ds_write_b32 v133, v122 offset:12544
	s_waitcnt lgkmcnt(8)
	v_mul_f32_e32 v36, v28, v10
	v_fmac_f32_e32 v36, v29, v11
	v_fmac_f32_e32 v36, v30, v12
	v_fmac_f32_e32 v36, v31, v13
	v_mul_f32_e32 v10, v64, v10
	v_mul_f32_e32 v11, v64, v11
	v_add_f32_dpp v36, v36, v36 quad_perm:[1,0,3,2] row_mask:0xf bank_mask:0xf bound_ctrl:1
	v_mul_f32_e32 v12, v64, v12
	v_mul_f32_e32 v13, v64, v13
	v_add_f32_dpp v36, v36, v36 quad_perm:[2,3,0,1] row_mask:0xf bank_mask:0xf bound_ctrl:1
	ds_read_b128 v[24:27], v0 offset:256
	ds_read_b128 v[42:45], v0 offset:2304
	v_add_f32_dpp v36, v36, v36 row_half_mirror row_mask:0xf bank_mask:0xf bound_ctrl:1
	ds_read_b128 v[58:61], v1 offset:4160
	s_nop 0
	v_add_f32_dpp v36, v36, v36 row_mirror row_mask:0xf bank_mask:0xf bound_ctrl:1
	s_nop 0
	v_fma_f32 v19, -v63, v36, v62
	v_fmac_f32_e32 v10, v28, v19
	v_fmac_f32_e32 v11, v29, v19
	v_fmac_f32_e32 v12, v30, v19
	v_fmac_f32_e32 v13, v31, v19
	v_mul_f32_e32 v122, v46, v10
	v_fmac_f32_e32 v122, v47, v11
	v_fmac_f32_e32 v122, v48, v12
	v_fmac_f32_e32 v122, v49, v13
	ds_write_b32 v133, v122 offset:12800
	s_waitcnt lgkmcnt(9)
	v_mul_f32_e32 v36, v32, v10
	v_fmac_f32_e32 v36, v33, v11
	v_fmac_f32_e32 v36, v34, v12
	v_fmac_f32_e32 v36, v35, v13
	v_mul_f32_e32 v10, v68, v10
	v_mul_f32_e32 v11, v68, v11
	v_add_f32_dpp v36, v36, v36 quad_perm:[1,0,3,2] row_mask:0xf bank_mask:0xf bound_ctrl:1
	v_mul_f32_e32 v12, v68, v12
	v_mul_f32_e32 v13, v68, v13
	v_add_f32_dpp v36, v36, v36 quad_perm:[2,3,0,1] row_mask:0xf bank_mask:0xf bound_ctrl:1
	ds_read_b128 v[28:31], v0 offset:512
	ds_read_b128 v[46:49], v0 offset:2560
	v_add_f32_dpp v36, v36, v36 row_half_mirror row_mask:0xf bank_mask:0xf bound_ctrl:1
	ds_read_b128 v[62:65], v1 offset:4224
	s_nop 0
	v_add_f32_dpp v36, v36, v36 row_mirror row_mask:0xf bank_mask:0xf bound_ctrl:1
	s_nop 0
	v_fma_f32 v19, -v67, v36, v66
	v_fmac_f32_e32 v10, v32, v19
	v_fmac_f32_e32 v11, v33, v19
	v_fmac_f32_e32 v12, v34, v19
	v_fmac_f32_e32 v13, v35, v19
	v_mul_f32_e32 v122, v50, v10
	v_fmac_f32_e32 v122, v51, v11
	v_fmac_f32_e32 v122, v52, v12
	v_fmac_f32_e32 v122, v53, v13
	ds_write_b32 v133, v122 offset:13056
	s_waitcnt lgkmcnt(9)
	v_mul_f32_e32 v36, v20, v10
	v_fmac_f32_e32 v36, v21, v11
	v_fmac_f32_e32 v36, v22, v12
	v_fmac_f32_e32 v36, v23, v13
	v_mul_f32_e32 v10, v56, v10
	v_mul_f32_e32 v11, v56, v11
	v_add_f32_dpp v36, v36, v36 quad_perm:[1,0,3,2] row_mask:0xf bank_mask:0xf bound_ctrl:1
	v_mul_f32_e32 v12, v56, v12
	v_mul_f32_e32 v13, v56, v13
	v_add_f32_dpp v36, v36, v36 quad_perm:[2,3,0,1] row_mask:0xf bank_mask:0xf bound_ctrl:1
	s_waitcnt vmcnt(14)
	v_lshlrev_b32_e32 v118, 16, v110
	v_add_f32_dpp v36, v36, v36 row_half_mirror row_mask:0xf bank_mask:0xf bound_ctrl:1
	v_and_b32_e32 v119, 0xffff0000, v110
	v_lshlrev_b32_e32 v120, 16, v111
	v_add_f32_dpp v36, v36, v36 row_mirror row_mask:0xf bank_mask:0xf bound_ctrl:1
	v_and_b32_e32 v121, 0xffff0000, v111
	v_fma_f32 v19, -v55, v36, v54
	v_fmac_f32_e32 v10, v20, v19
	v_fmac_f32_e32 v11, v21, v19
	v_fmac_f32_e32 v12, v22, v19
	v_fmac_f32_e32 v13, v23, v19
	v_mul_f32_e32 v122, v38, v10
	v_fmac_f32_e32 v122, v39, v11
	v_fmac_f32_e32 v122, v40, v12
	v_fmac_f32_e32 v122, v41, v13
	ds_write_b32 v133, v122 offset:13312
	ds_read_b128 v[32:35], v0 offset:768
	ds_read_b128 v[50:53], v0 offset:2816
	ds_read_b128 v[66:69], v1 offset:4288
	ds_write_b128 v2, v[118:121] offset:4608
	v_lshlrev_b32_e32 v124, 16, v112
	v_and_b32_e32 v125, 0xffff0000, v112
	s_waitcnt lgkmcnt(10)
	v_mul_f32_e32 v36, v24, v10
	v_fmac_f32_e32 v36, v25, v11
	v_fmac_f32_e32 v36, v26, v12
	v_fmac_f32_e32 v36, v27, v13
	v_mul_f32_e32 v10, v60, v10
	v_mul_f32_e32 v11, v60, v11
	v_add_f32_dpp v36, v36, v36 quad_perm:[1,0,3,2] row_mask:0xf bank_mask:0xf bound_ctrl:1
	v_mul_f32_e32 v12, v60, v12
	v_mul_f32_e32 v13, v60, v13
	v_add_f32_dpp v36, v36, v36 quad_perm:[2,3,0,1] row_mask:0xf bank_mask:0xf bound_ctrl:1
	v_lshlrev_b32_e32 v126, 16, v113
	v_and_b32_e32 v127, 0xffff0000, v113
	v_add_f32_dpp v36, v36, v36 row_half_mirror row_mask:0xf bank_mask:0xf bound_ctrl:1
	ds_write_b128 v2, v[124:127] offset:4624
	v_lshlrev_b32_e32 v118, 16, v106
	v_add_f32_dpp v36, v36, v36 row_mirror row_mask:0xf bank_mask:0xf bound_ctrl:1
	v_and_b32_e32 v119, 0xffff0000, v106
	v_fma_f32 v19, -v59, v36, v58
	v_fmac_f32_e32 v10, v24, v19
	v_fmac_f32_e32 v11, v25, v19
	v_fmac_f32_e32 v12, v26, v19
	v_fmac_f32_e32 v13, v27, v19
	v_mul_f32_e32 v122, v42, v10
	v_fmac_f32_e32 v122, v43, v11
	v_fmac_f32_e32 v122, v44, v12
	v_fmac_f32_e32 v122, v45, v13
	ds_write_b32 v133, v122 offset:13568
	ds_read_b128 v[20:23], v0 offset:1024
	ds_read_b128 v[38:41], v0 offset:3072
	ds_read_b128 v[54:57], v1 offset:4352
	v_lshlrev_b32_e32 v120, 16, v107
	v_and_b32_e32 v121, 0xffff0000, v107
	ds_write_b128 v2, v[118:121] offset:6656
	s_waitcnt lgkmcnt(12)
	v_mul_f32_e32 v36, v28, v10
	v_fmac_f32_e32 v36, v29, v11
	v_fmac_f32_e32 v36, v30, v12
	v_fmac_f32_e32 v36, v31, v13
	v_mul_f32_e32 v10, v64, v10
	v_mul_f32_e32 v11, v64, v11
	v_add_f32_dpp v36, v36, v36 quad_perm:[1,0,3,2] row_mask:0xf bank_mask:0xf bound_ctrl:1
	v_mul_f32_e32 v12, v64, v12
	v_mul_f32_e32 v13, v64, v13
	v_add_f32_dpp v36, v36, v36 quad_perm:[2,3,0,1] row_mask:0xf bank_mask:0xf bound_ctrl:1
	v_lshlrev_b32_e32 v124, 16, v108
	v_and_b32_e32 v125, 0xffff0000, v108
	v_add_f32_dpp v36, v36, v36 row_half_mirror row_mask:0xf bank_mask:0xf bound_ctrl:1
	v_lshlrev_b32_e32 v126, 16, v109
	v_and_b32_e32 v127, 0xffff0000, v109
	v_add_f32_dpp v36, v36, v36 row_mirror row_mask:0xf bank_mask:0xf bound_ctrl:1
	ds_write_b128 v2, v[124:127] offset:6672
	v_fma_f32 v19, -v63, v36, v62
	v_fmac_f32_e32 v10, v28, v19
	v_fmac_f32_e32 v11, v29, v19
	v_fmac_f32_e32 v12, v30, v19
	v_fmac_f32_e32 v13, v31, v19
	v_mul_f32_e32 v122, v46, v10
	v_fmac_f32_e32 v122, v47, v11
	v_fmac_f32_e32 v122, v48, v12
	v_fmac_f32_e32 v122, v49, v13
	ds_write_b32 v133, v122 offset:13824
	ds_read_b128 v[24:27], v0 offset:1280
	ds_read_b128 v[42:45], v0 offset:3328
	ds_read_b128 v[58:61], v1 offset:4416
	s_waitcnt vmcnt(12)
	v_mov_b32_dpp v116, v115 quad_perm:[1,1,1,1] row_mask:0xf bank_mask:0xf
	v_mov_b32_dpp v115, v115 quad_perm:[0,0,0,0] row_mask:0xf bank_mask:0xf
	s_waitcnt lgkmcnt(12)
	v_mul_f32_e32 v36, v32, v10
	v_fmac_f32_e32 v36, v33, v11
	v_fmac_f32_e32 v36, v34, v12
	v_fmac_f32_e32 v36, v35, v13
	v_mul_f32_e32 v10, v68, v10
	v_mul_f32_e32 v11, v68, v11
	v_add_f32_dpp v36, v36, v36 quad_perm:[1,0,3,2] row_mask:0xf bank_mask:0xf bound_ctrl:1
	v_mul_f32_e32 v12, v68, v12
	v_mul_f32_e32 v13, v68, v13
	v_add_f32_dpp v36, v36, v36 quad_perm:[2,3,0,1] row_mask:0xf bank_mask:0xf bound_ctrl:1
	v_lshlrev_b32_e32 v114, 16, v114
	v_mul_f32_e32 v114, v115, v114
	v_add_f32_dpp v36, v36, v36 row_half_mirror row_mask:0xf bank_mask:0xf bound_ctrl:1
	v_mul_f32_e32 v115, v115, v116
	s_nop 0
	v_add_f32_dpp v36, v36, v36 row_mirror row_mask:0xf bank_mask:0xf bound_ctrl:1
	ds_write_b128 v4, v[114:117] offset:8704
	v_fma_f32 v19, -v67, v36, v66
	v_fmac_f32_e32 v10, v32, v19
	v_fmac_f32_e32 v11, v33, v19
	v_fmac_f32_e32 v12, v34, v19
	v_fmac_f32_e32 v13, v35, v19
	v_mul_f32_e32 v122, v50, v10
	v_fmac_f32_e32 v122, v51, v11
	v_fmac_f32_e32 v122, v52, v12
	v_fmac_f32_e32 v122, v53, v13
	ds_write_b32 v133, v122 offset:14080
	ds_read_b128 v[28:31], v0 offset:1536
	ds_read_b128 v[46:49], v0 offset:3584
	ds_read_b128 v[62:65], v1 offset:4480
	s_waitcnt lgkmcnt(11)
	v_mul_f32_e32 v36, v20, v10
	v_fmac_f32_e32 v36, v21, v11
	v_fmac_f32_e32 v36, v22, v12
	v_fmac_f32_e32 v36, v23, v13
	v_mul_f32_e32 v10, v56, v10
	v_mul_f32_e32 v11, v56, v11
	v_add_f32_dpp v36, v36, v36 quad_perm:[1,0,3,2] row_mask:0xf bank_mask:0xf bound_ctrl:1
	v_mul_f32_e32 v12, v56, v12
	v_mul_f32_e32 v13, v56, v13
	v_add_f32_dpp v36, v36, v36 quad_perm:[2,3,0,1] row_mask:0xf bank_mask:0xf bound_ctrl:1
	global_load_dwordx4 v[106:109], v5, s[94:95]
	global_load_dwordx4 v[110:113], v5, s[94:95] offset:512
	global_load_ushort v114, v6, s[94:95]
	global_load_dword v115, v8, s[94:95]
	v_add_u32_e32 v5, 0x6800, v5
	v_add_u32_e32 v6, 0x6800, v6
	v_add_u32_e32 v8, 0x3180, v8
	ds_read_b128 v[140:143], v136 offset:9216
	v_add_f32_dpp v36, v36, v36 row_half_mirror row_mask:0xf bank_mask:0xf bound_ctrl:1
	ds_read_b128 v[154:157], v137 offset:9216
	ds_read_b128 v[158:161], v138 offset:9216
	v_add_f32_dpp v36, v36, v36 row_mirror row_mask:0xf bank_mask:0xf bound_ctrl:1
	ds_read_b128 v[162:165], v139 offset:9216
	v_fma_f32 v19, -v55, v36, v54
	v_fmac_f32_e32 v10, v20, v19
	v_fmac_f32_e32 v11, v21, v19
	v_fmac_f32_e32 v12, v22, v19
	v_fmac_f32_e32 v13, v23, v19
	v_mul_f32_e32 v122, v38, v10
	v_fmac_f32_e32 v122, v39, v11
	v_fmac_f32_e32 v122, v40, v12
	v_fmac_f32_e32 v122, v41, v13
	ds_write_b32 v133, v122 offset:14336
	ds_read_b128 v[32:35], v0 offset:1792
	ds_read_b128 v[50:53], v0 offset:3840
	ds_read_b128 v[66:69], v1 offset:4544
	s_waitcnt lgkmcnt(13)
	v_mul_f32_e32 v36, v24, v10
	v_fmac_f32_e32 v36, v25, v11
	v_fmac_f32_e32 v36, v26, v12
	v_fmac_f32_e32 v36, v27, v13
	v_mul_f32_e32 v10, v60, v10
	v_mul_f32_e32 v11, v60, v11
	v_add_f32_dpp v36, v36, v36 quad_perm:[1,0,3,2] row_mask:0xf bank_mask:0xf bound_ctrl:1
	v_mul_f32_e32 v12, v60, v12
	v_mul_f32_e32 v13, v60, v13
	v_add_f32_dpp v36, v36, v36 quad_perm:[2,3,0,1] row_mask:0xf bank_mask:0xf bound_ctrl:1
	ds_read_b128 v[20:23], v0 offset:4608
	ds_read_b128 v[38:41], v0 offset:6656
	v_add_f32_dpp v36, v36, v36 row_half_mirror row_mask:0xf bank_mask:0xf bound_ctrl:1
	ds_read_b128 v[54:57], v1 offset:8704
	s_nop 0
	v_add_f32_dpp v36, v36, v36 row_mirror row_mask:0xf bank_mask:0xf bound_ctrl:1
	s_nop 0
	v_fma_f32 v19, -v59, v36, v58
	v_fmac_f32_e32 v10, v24, v19
	v_fmac_f32_e32 v11, v25, v19
	v_fmac_f32_e32 v12, v26, v19
	v_fmac_f32_e32 v13, v27, v19
	v_mul_f32_e32 v122, v42, v10
	v_fmac_f32_e32 v122, v43, v11
	v_fmac_f32_e32 v122, v44, v12
	v_fmac_f32_e32 v122, v45, v13
	ds_write_b32 v133, v122 offset:14592
	s_waitcnt lgkmcnt(12)
	v_mul_f32_e32 v36, v28, v10
	v_fmac_f32_e32 v36, v29, v11
	v_fmac_f32_e32 v36, v30, v12
	v_fmac_f32_e32 v36, v31, v13
	v_mul_f32_e32 v10, v64, v10
	v_mul_f32_e32 v11, v64, v11
	v_add_f32_dpp v36, v36, v36 quad_perm:[1,0,3,2] row_mask:0xf bank_mask:0xf bound_ctrl:1
	v_mul_f32_e32 v12, v64, v12
	v_mul_f32_e32 v13, v64, v13
	v_add_f32_dpp v36, v36, v36 quad_perm:[2,3,0,1] row_mask:0xf bank_mask:0xf bound_ctrl:1
	s_waitcnt lgkmcnt(8)
	v_add_f32_e32 v140, v140, v158
	v_add_f32_dpp v36, v36, v36 row_half_mirror row_mask:0xf bank_mask:0xf bound_ctrl:1
	v_add_f32_e32 v141, v141, v159
	v_add_f32_e32 v142, v142, v160
	v_add_f32_dpp v36, v36, v36 row_mirror row_mask:0xf bank_mask:0xf bound_ctrl:1
	v_add_f32_e32 v143, v143, v161
	v_fma_f32 v19, -v63, v36, v62
	v_fmac_f32_e32 v10, v28, v19
	v_fmac_f32_e32 v11, v29, v19
	v_fmac_f32_e32 v12, v30, v19
	v_fmac_f32_e32 v13, v31, v19
	v_mul_f32_e32 v122, v46, v10
	v_fmac_f32_e32 v122, v47, v11
	v_fmac_f32_e32 v122, v48, v12
	v_fmac_f32_e32 v122, v49, v13
	ds_write_b32 v133, v122 offset:14848
	ds_read_b128 v[24:27], v0 offset:4864
	ds_read_b128 v[42:45], v0 offset:6912
	ds_read_b128 v[58:61], v1 offset:8768
	v_add_f32_e32 v154, v154, v162
	v_add_f32_e32 v155, v155, v163
	v_add_f32_e32 v156, v156, v164
	v_add_f32_e32 v157, v157, v165
	v_add_f32_e32 v140, v140, v154
	v_add_f32_e32 v141, v141, v155
	v_add_f32_e32 v142, v142, v156
	v_add_f32_e32 v143, v143, v157
	v_add_f32_e32 v140, v140, v141
	v_add_f32_e32 v142, v142, v143
	v_add_f32_e32 v140, v140, v142
	v_cvt_pk_bf16_f32 v18, v140, v140
	ds_write_b16 v131, v18 offset:17664
	s_waitcnt lgkmcnt(9)
	v_mul_f32_e32 v36, v32, v10
	v_fmac_f32_e32 v36, v33, v11
	v_fmac_f32_e32 v36, v34, v12
	v_fmac_f32_e32 v36, v35, v13
	v_mul_f32_e32 v10, v68, v10
	v_mul_f32_e32 v11, v68, v11
	v_add_f32_dpp v36, v36, v36 quad_perm:[1,0,3,2] row_mask:0xf bank_mask:0xf bound_ctrl:1
	v_mul_f32_e32 v12, v68, v12
	v_mul_f32_e32 v13, v68, v13
	v_add_f32_dpp v36, v36, v36 quad_perm:[2,3,0,1] row_mask:0xf bank_mask:0xf bound_ctrl:1
	ds_read_b128 v[28:31], v0 offset:5120
	ds_read_b128 v[46:49], v0 offset:7168
	v_add_f32_dpp v36, v36, v36 row_half_mirror row_mask:0xf bank_mask:0xf bound_ctrl:1
	ds_read_b128 v[62:65], v1 offset:8832
	s_nop 0
	v_add_f32_dpp v36, v36, v36 row_mirror row_mask:0xf bank_mask:0xf bound_ctrl:1
	s_nop 0
	v_fma_f32 v19, -v67, v36, v66
	v_fmac_f32_e32 v10, v32, v19
	v_fmac_f32_e32 v11, v33, v19
	v_fmac_f32_e32 v12, v34, v19
	v_fmac_f32_e32 v13, v35, v19
	v_mul_f32_e32 v122, v50, v10
	v_fmac_f32_e32 v122, v51, v11
	v_fmac_f32_e32 v122, v52, v12
	v_fmac_f32_e32 v122, v53, v13
	ds_write_b32 v133, v122 offset:15104
	s_waitcnt lgkmcnt(10)
	v_mul_f32_e32 v36, v20, v10
	v_fmac_f32_e32 v36, v21, v11
	v_fmac_f32_e32 v36, v22, v12
	v_fmac_f32_e32 v36, v23, v13
	v_mul_f32_e32 v10, v56, v10
	v_mul_f32_e32 v11, v56, v11
	v_add_f32_dpp v36, v36, v36 quad_perm:[1,0,3,2] row_mask:0xf bank_mask:0xf bound_ctrl:1
	v_mul_f32_e32 v12, v56, v12
	v_mul_f32_e32 v13, v56, v13
	v_add_f32_dpp v36, v36, v36 quad_perm:[2,3,0,1] row_mask:0xf bank_mask:0xf bound_ctrl:1
	s_waitcnt vmcnt(14)
	v_lshlrev_b32_e32 v118, 16, v74
	v_add_f32_dpp v36, v36, v36 row_half_mirror row_mask:0xf bank_mask:0xf bound_ctrl:1
	v_and_b32_e32 v119, 0xffff0000, v74
	v_lshlrev_b32_e32 v120, 16, v75
	v_add_f32_dpp v36, v36, v36 row_mirror row_mask:0xf bank_mask:0xf bound_ctrl:1
	v_and_b32_e32 v121, 0xffff0000, v75
	v_fma_f32 v19, -v55, v36, v54
	v_fmac_f32_e32 v10, v20, v19
	v_fmac_f32_e32 v11, v21, v19
	v_fmac_f32_e32 v12, v22, v19
	v_fmac_f32_e32 v13, v23, v19
	v_mul_f32_e32 v122, v38, v10
	v_fmac_f32_e32 v122, v39, v11
	v_fmac_f32_e32 v122, v40, v12
	v_fmac_f32_e32 v122, v41, v13
	ds_write_b32 v133, v122 offset:15360
	ds_read_b128 v[32:35], v0 offset:5376
	ds_read_b128 v[50:53], v0 offset:7424
	ds_read_b128 v[66:69], v1 offset:8896
	ds_write_b128 v2, v[118:121] offset:0
	v_lshlrev_b32_e32 v124, 16, v76
	v_and_b32_e32 v125, 0xffff0000, v76
	s_waitcnt lgkmcnt(10)
	v_mul_f32_e32 v36, v24, v10
	v_fmac_f32_e32 v36, v25, v11
	v_fmac_f32_e32 v36, v26, v12
	v_fmac_f32_e32 v36, v27, v13
	v_mul_f32_e32 v10, v60, v10
	v_mul_f32_e32 v11, v60, v11
	v_add_f32_dpp v36, v36, v36 quad_perm:[1,0,3,2] row_mask:0xf bank_mask:0xf bound_ctrl:1
	v_mul_f32_e32 v12, v60, v12
	v_mul_f32_e32 v13, v60, v13
	v_add_f32_dpp v36, v36, v36 quad_perm:[2,3,0,1] row_mask:0xf bank_mask:0xf bound_ctrl:1
	v_lshlrev_b32_e32 v126, 16, v77
	v_and_b32_e32 v127, 0xffff0000, v77
	v_add_f32_dpp v36, v36, v36 row_half_mirror row_mask:0xf bank_mask:0xf bound_ctrl:1
	ds_write_b128 v2, v[124:127] offset:16
	v_lshlrev_b32_e32 v118, 16, v70
	v_add_f32_dpp v36, v36, v36 row_mirror row_mask:0xf bank_mask:0xf bound_ctrl:1
	v_and_b32_e32 v119, 0xffff0000, v70
	v_fma_f32 v19, -v59, v36, v58
	v_fmac_f32_e32 v10, v24, v19
	v_fmac_f32_e32 v11, v25, v19
	v_fmac_f32_e32 v12, v26, v19
	v_fmac_f32_e32 v13, v27, v19
	v_mul_f32_e32 v122, v42, v10
	v_fmac_f32_e32 v122, v43, v11
	v_fmac_f32_e32 v122, v44, v12
	v_fmac_f32_e32 v122, v45, v13
	ds_write_b32 v133, v122 offset:15616
	ds_read_b128 v[20:23], v0 offset:5632
	ds_read_b128 v[38:41], v0 offset:7680
	ds_read_b128 v[54:57], v1 offset:8960
	v_lshlrev_b32_e32 v120, 16, v71
	v_and_b32_e32 v121, 0xffff0000, v71
	ds_write_b128 v2, v[118:121] offset:2048
	s_waitcnt lgkmcnt(12)
	v_mul_f32_e32 v36, v28, v10
	v_fmac_f32_e32 v36, v29, v11
	v_fmac_f32_e32 v36, v30, v12
	v_fmac_f32_e32 v36, v31, v13
	v_mul_f32_e32 v10, v64, v10
	v_mul_f32_e32 v11, v64, v11
	v_add_f32_dpp v36, v36, v36 quad_perm:[1,0,3,2] row_mask:0xf bank_mask:0xf bound_ctrl:1
	v_mul_f32_e32 v12, v64, v12
	v_mul_f32_e32 v13, v64, v13
	v_add_f32_dpp v36, v36, v36 quad_perm:[2,3,0,1] row_mask:0xf bank_mask:0xf bound_ctrl:1
	v_lshlrev_b32_e32 v124, 16, v72
	v_and_b32_e32 v125, 0xffff0000, v72
	v_add_f32_dpp v36, v36, v36 row_half_mirror row_mask:0xf bank_mask:0xf bound_ctrl:1
	v_lshlrev_b32_e32 v126, 16, v73
	v_and_b32_e32 v127, 0xffff0000, v73
	v_add_f32_dpp v36, v36, v36 row_mirror row_mask:0xf bank_mask:0xf bound_ctrl:1
	ds_write_b128 v2, v[124:127] offset:2064
	v_fma_f32 v19, -v63, v36, v62
	v_fmac_f32_e32 v10, v28, v19
	v_fmac_f32_e32 v11, v29, v19
	v_fmac_f32_e32 v12, v30, v19
	v_fmac_f32_e32 v13, v31, v19
	v_mul_f32_e32 v122, v46, v10
	v_fmac_f32_e32 v122, v47, v11
	v_fmac_f32_e32 v122, v48, v12
	v_fmac_f32_e32 v122, v49, v13
	ds_write_b32 v133, v122 offset:15872
	ds_read_b128 v[24:27], v0 offset:5888
	ds_read_b128 v[42:45], v0 offset:7936
	ds_read_b128 v[58:61], v1 offset:9024
	s_waitcnt vmcnt(12)
	v_mov_b32_dpp v80, v79 quad_perm:[1,1,1,1] row_mask:0xf bank_mask:0xf
	v_mov_b32_dpp v79, v79 quad_perm:[0,0,0,0] row_mask:0xf bank_mask:0xf
	s_waitcnt lgkmcnt(12)
	v_mul_f32_e32 v36, v32, v10
	v_fmac_f32_e32 v36, v33, v11
	v_fmac_f32_e32 v36, v34, v12
	v_fmac_f32_e32 v36, v35, v13
	v_mul_f32_e32 v10, v68, v10
	v_mul_f32_e32 v11, v68, v11
	v_add_f32_dpp v36, v36, v36 quad_perm:[1,0,3,2] row_mask:0xf bank_mask:0xf bound_ctrl:1
	v_mul_f32_e32 v12, v68, v12
	v_mul_f32_e32 v13, v68, v13
	v_add_f32_dpp v36, v36, v36 quad_perm:[2,3,0,1] row_mask:0xf bank_mask:0xf bound_ctrl:1
	v_lshlrev_b32_e32 v78, 16, v78
	v_mul_f32_e32 v78, v79, v78
	v_add_f32_dpp v36, v36, v36 row_half_mirror row_mask:0xf bank_mask:0xf bound_ctrl:1
	v_mul_f32_e32 v79, v79, v80
	s_nop 0
	v_add_f32_dpp v36, v36, v36 row_mirror row_mask:0xf bank_mask:0xf bound_ctrl:1
	ds_write_b128 v4, v[78:81] offset:4096
	v_fma_f32 v19, -v67, v36, v66
	v_fmac_f32_e32 v10, v32, v19
	v_fmac_f32_e32 v11, v33, v19
	v_fmac_f32_e32 v12, v34, v19
	v_fmac_f32_e32 v13, v35, v19
	v_mul_f32_e32 v122, v50, v10
	v_fmac_f32_e32 v122, v51, v11
	v_fmac_f32_e32 v122, v52, v12
	v_fmac_f32_e32 v122, v53, v13
	ds_write_b32 v133, v122 offset:16128
	ds_read_b128 v[28:31], v0 offset:6144
	ds_read_b128 v[46:49], v0 offset:8192
	ds_read_b128 v[62:65], v1 offset:9088
	s_waitcnt lgkmcnt(11)
	v_mul_f32_e32 v36, v20, v10
	v_fmac_f32_e32 v36, v21, v11
	v_fmac_f32_e32 v36, v22, v12
	v_fmac_f32_e32 v36, v23, v13
	v_mul_f32_e32 v10, v56, v10
	v_mul_f32_e32 v11, v56, v11
	v_add_f32_dpp v36, v36, v36 quad_perm:[1,0,3,2] row_mask:0xf bank_mask:0xf bound_ctrl:1
	v_mul_f32_e32 v12, v56, v12
	v_mul_f32_e32 v13, v56, v13
	v_add_f32_dpp v36, v36, v36 quad_perm:[2,3,0,1] row_mask:0xf bank_mask:0xf bound_ctrl:1
	global_load_dwordx4 v[70:73], v5, s[94:95]
	global_load_dwordx4 v[74:77], v5, s[94:95] offset:512
	global_load_ushort v78, v6, s[94:95]
	global_load_dword v79, v8, s[94:95]
	v_add_u32_e32 v5, 0x6800, v5
	v_add_u32_e32 v6, 0x6800, v6
	v_add_u32_e32 v8, 0x3180, v8
	ds_read_b128 v[32:35], v0 offset:6400
	v_add_f32_dpp v36, v36, v36 row_half_mirror row_mask:0xf bank_mask:0xf bound_ctrl:1
	ds_read_b128 v[50:53], v0 offset:8448
	ds_read_b128 v[66:69], v1 offset:9152
	v_add_f32_dpp v36, v36, v36 row_mirror row_mask:0xf bank_mask:0xf bound_ctrl:1
	s_nop 0
	v_fma_f32 v19, -v55, v36, v54
	v_fmac_f32_e32 v10, v20, v19
	v_fmac_f32_e32 v11, v21, v19
	v_fmac_f32_e32 v12, v22, v19
	v_fmac_f32_e32 v13, v23, v19
	v_mul_f32_e32 v122, v38, v10
	v_fmac_f32_e32 v122, v39, v11
	v_fmac_f32_e32 v122, v40, v12
	v_fmac_f32_e32 v122, v41, v13
	ds_write_b32 v133, v122 offset:16384
	s_waitcnt lgkmcnt(9)
	v_mul_f32_e32 v36, v24, v10
	v_fmac_f32_e32 v36, v25, v11
	v_fmac_f32_e32 v36, v26, v12
	v_fmac_f32_e32 v36, v27, v13
	v_mul_f32_e32 v10, v60, v10
	v_mul_f32_e32 v11, v60, v11
	v_add_f32_dpp v36, v36, v36 quad_perm:[1,0,3,2] row_mask:0xf bank_mask:0xf bound_ctrl:1
	v_mul_f32_e32 v12, v60, v12
	v_mul_f32_e32 v13, v60, v13
	v_add_f32_dpp v36, v36, v36 quad_perm:[2,3,0,1] row_mask:0xf bank_mask:0xf bound_ctrl:1
	ds_read_b128 v[20:23], v0 offset:0
	ds_read_b128 v[38:41], v0 offset:2048
	v_add_f32_dpp v36, v36, v36 row_half_mirror row_mask:0xf bank_mask:0xf bound_ctrl:1
	ds_read_b128 v[54:57], v1 offset:4096
	s_nop 0
	v_add_f32_dpp v36, v36, v36 row_mirror row_mask:0xf bank_mask:0xf bound_ctrl:1
	s_nop 0
	v_fma_f32 v19, -v59, v36, v58
	v_fmac_f32_e32 v10, v24, v19
	v_fmac_f32_e32 v11, v25, v19
	v_fmac_f32_e32 v12, v26, v19
	v_fmac_f32_e32 v13, v27, v19
	v_mul_f32_e32 v122, v42, v10
	v_fmac_f32_e32 v122, v43, v11
	v_fmac_f32_e32 v122, v44, v12
	v_fmac_f32_e32 v122, v45, v13
	ds_write_b32 v133, v122 offset:16640
	s_waitcnt lgkmcnt(8)
	v_mul_f32_e32 v36, v28, v10
	v_fmac_f32_e32 v36, v29, v11
	v_fmac_f32_e32 v36, v30, v12
	v_fmac_f32_e32 v36, v31, v13
	v_mul_f32_e32 v10, v64, v10
	v_mul_f32_e32 v11, v64, v11
	v_add_f32_dpp v36, v36, v36 quad_perm:[1,0,3,2] row_mask:0xf bank_mask:0xf bound_ctrl:1
	v_mul_f32_e32 v12, v64, v12
	v_mul_f32_e32 v13, v64, v13
	v_add_f32_dpp v36, v36, v36 quad_perm:[2,3,0,1] row_mask:0xf bank_mask:0xf bound_ctrl:1
	ds_read_b128 v[24:27], v0 offset:256
	ds_read_b128 v[42:45], v0 offset:2304
	v_add_f32_dpp v36, v36, v36 row_half_mirror row_mask:0xf bank_mask:0xf bound_ctrl:1
	ds_read_b128 v[58:61], v1 offset:4160
	s_nop 0
	v_add_f32_dpp v36, v36, v36 row_mirror row_mask:0xf bank_mask:0xf bound_ctrl:1
	s_nop 0
	v_fma_f32 v19, -v63, v36, v62
	v_fmac_f32_e32 v10, v28, v19
	v_fmac_f32_e32 v11, v29, v19
	v_fmac_f32_e32 v12, v30, v19
	v_fmac_f32_e32 v13, v31, v19
	v_mul_f32_e32 v122, v46, v10
	v_fmac_f32_e32 v122, v47, v11
	v_fmac_f32_e32 v122, v48, v12
	v_fmac_f32_e32 v122, v49, v13
	ds_write_b32 v133, v122 offset:16896
	s_waitcnt lgkmcnt(9)
	v_mul_f32_e32 v36, v32, v10
	v_fmac_f32_e32 v36, v33, v11
	v_fmac_f32_e32 v36, v34, v12
	v_fmac_f32_e32 v36, v35, v13
	v_mul_f32_e32 v10, v68, v10
	v_mul_f32_e32 v11, v68, v11
	v_add_f32_dpp v36, v36, v36 quad_perm:[1,0,3,2] row_mask:0xf bank_mask:0xf bound_ctrl:1
	v_mul_f32_e32 v12, v68, v12
	v_mul_f32_e32 v13, v68, v13
	v_add_f32_dpp v36, v36, v36 quad_perm:[2,3,0,1] row_mask:0xf bank_mask:0xf bound_ctrl:1
	ds_read_b128 v[28:31], v0 offset:512
	ds_read_b128 v[46:49], v0 offset:2560
	v_add_f32_dpp v36, v36, v36 row_half_mirror row_mask:0xf bank_mask:0xf bound_ctrl:1
	ds_read_b128 v[62:65], v1 offset:4224
	s_nop 0
	v_add_f32_dpp v36, v36, v36 row_mirror row_mask:0xf bank_mask:0xf bound_ctrl:1
	s_nop 0
	v_fma_f32 v19, -v67, v36, v66
	v_fmac_f32_e32 v10, v32, v19
	v_fmac_f32_e32 v11, v33, v19
	v_fmac_f32_e32 v12, v34, v19
	v_fmac_f32_e32 v13, v35, v19
	v_mul_f32_e32 v122, v50, v10
	v_fmac_f32_e32 v122, v51, v11
	v_fmac_f32_e32 v122, v52, v12
	v_fmac_f32_e32 v122, v53, v13
	ds_write_b32 v133, v122 offset:17152
	s_sub_u32 s12, s12, 1
	s_cmp_lg_u32 s12, 0
	s_cbranch_scc1 .Lls3_16_loop
	ds_read_b128 v[140:143], v136 offset:13312
	ds_read_b128 v[154:157], v137 offset:13312
	ds_read_b128 v[158:161], v138 offset:13312
	ds_read_b128 v[162:165], v139 offset:13312
	s_waitcnt lgkmcnt(0)
	v_add_f32_e32 v140, v140, v158
	v_add_f32_e32 v141, v141, v159
	v_add_f32_e32 v142, v142, v160
	v_add_f32_e32 v143, v143, v161
	v_add_f32_e32 v154, v154, v162
	v_add_f32_e32 v155, v155, v163
	v_add_f32_e32 v156, v156, v164
	v_add_f32_e32 v157, v157, v165
	v_add_f32_e32 v140, v140, v154
	v_add_f32_e32 v141, v141, v155
	v_add_f32_e32 v142, v142, v156
	v_add_f32_e32 v143, v143, v157
	v_add_f32_e32 v140, v140, v141
	v_add_f32_e32 v142, v142, v143
	v_add_f32_e32 v140, v140, v142
	v_cvt_pk_bf16_f32 v18, v140, v140
	ds_write_b16 v131, v18 offset:17792
	s_waitcnt lgkmcnt(0)
	ds_read_b64 v[134:135], v132 offset:17664
	s_waitcnt lgkmcnt(0)
	global_store_dwordx2 v7, v[134:135], s[94:95]
	v_add_u32_e32 v7, 0x20000, v7
	s_nop 0
	ds_read_b64 v[134:135], v132 offset:18176
	s_waitcnt lgkmcnt(0)
	global_store_dwordx2 v7, v[134:135], s[94:95]
	v_add_u32_e32 v7, 0x20000, v7
	s_nop 0
	ds_read_b64 v[134:135], v132 offset:18688
	s_waitcnt lgkmcnt(0)
	global_store_dwordx2 v7, v[134:135], s[94:95]
	v_add_u32_e32 v7, 0x20000, v7
	s_nop 0
	ds_read_b64 v[134:135], v132 offset:19200
	s_waitcnt lgkmcnt(0)
	global_store_dwordx2 v7, v[134:135], s[94:95]
	v_add_u32_e32 v7, 0x20000, v7
	s_nop 0
	ds_read_b64 v[134:135], v132 offset:19712
	s_waitcnt lgkmcnt(0)
	global_store_dwordx2 v7, v[134:135], s[94:95]
	v_add_u32_e32 v7, 0x20000, v7
	s_nop 0
	ds_read_b64 v[134:135], v132 offset:20224
	s_waitcnt lgkmcnt(0)
	global_store_dwordx2 v7, v[134:135], s[94:95]
	v_add_u32_e32 v7, 0x20000, v7
	s_nop 0
	ds_read_b64 v[134:135], v132 offset:20736
	s_waitcnt lgkmcnt(0)
	global_store_dwordx2 v7, v[134:135], s[94:95]
	v_add_u32_e32 v7, 0x20000, v7
	s_nop 0
	ds_read_b64 v[134:135], v132 offset:21248
	s_waitcnt lgkmcnt(0)
	global_store_dwordx2 v7, v[134:135], s[94:95]
	v_add_u32_e32 v7, 0x20000, v7
	s_nop 0
	global_store_dword v130, v10, s[26:27] offset:0
	global_store_dword v130, v11, s[26:27] offset:256
	global_store_dword v130, v12, s[26:27] offset:512
	global_store_dword v130, v13, s[26:27] offset:768
	s_waitcnt vmcnt(0) lgkmcnt(0)
	s_branch .Lls_done
.Lls0_8_entry:
	v_and_b32_e32 v98, 63, v196
	v_and_b32_e32 v99, 7, v98
	v_lshrrev_b32_e32 v100, 3, v98
	s_min_u32 s29, s0, 4
	s_mul_i32 s29, s29, 0x5600
	v_and_b32_e32 v101, 3, v99
	v_cmp_eq_u32_e64 s[6:7], 1, v101
	v_cmp_eq_u32_e64 s[8:9], 2, v101
	v_cmp_eq_u32_e64 s[10:11], 3, v101
	v_lshl_add_u32 v0, v99, 5, s29
	v_lshl_add_u32 v1, v100, 2, s29
	s_lshl_b32 s37, s16, 11
	v_lshrrev_b32_e32 v99, 3, v98
	v_and_b32_e32 v100, 7, v98
	v_add_u32_e32 v101, s37, v99
	s_lshl_b32 s21, s17, 7
	s_add_u32 s21, s21, 0x10800000
	v_mul_u32_u24_e32 v5, 0xd00, v101
	v_lshl_add_u32 v5, v100, 4, v5
	v_add_u32_e32 v5, s21, v5
	v_lshlrev_b32_e32 v2, 8, v99
	v_lshl_add_u32 v2, v100, 5, v2
	v_add_u32_e32 v2, s29, v2
	v_lshrrev_b32_e32 v100, 3, v98
	v_and_b32_e32 v99, 7, v98
	v_add_u32_e32 v101, s37, v100
	s_lshl_b32 s22, s14, 3
	s_lshl_b32 s21, s17, 6
	s_add_u32 s21, s21, s22
	s_lshl_b32 s44, s21, 1
	s_add_u32 s44, s44, 0x8400400
	v_lshlrev_b32_e32 v6, 13, v101
	v_lshlrev_b32_e32 v4, 5, v100
	v_lshl_add_u32 v4, v99, 2, v4
	v_lshl_add_u32 v6, v99, 1, v6
	v_add_u32_e32 v6, s44, v6
	v_add_u32_e32 v4, s29, v4
	v_and_b32_e32 v99, 7, v98
	v_lshrrev_b32_e32 v100, 3, v98
	v_add_u32_e32 v101, s37, v98
	v_lshlrev_b32_e32 v7, 11, v101
	s_lshl_b32 s44, s21, 1
	s_add_u32 s44, s44, 0x6300000
	v_add_u32_e32 v7, s44, v7
	s_lshl_b32 s44, s28, 3
	s_add_u32 s44, s44, s16
	s_lshl_b32 s44, s44, 2
	s_add_u32 s44, s44, s17
	s_mul_i32 s44, s44, 0x4000
	s_add_u32 s44, s44, 0x4200000
	s_lshl_b32 s24, s22, 2
	s_add_u32 s44, s44, s24
	v_lshlrev_b32_e32 v111, 11, v99
	v_lshl_add_u32 v111, v100, 2, v111
	v_add_u32_e32 v111, s44, v111
	v_readlane_b32 s26, v253, 29
	v_readlane_b32 s27, v253, 30
	v_lshlrev_b32_e32 v112, 4, v99
	v_lshl_add_u32 v112, v100, 1, v112
	v_add_u32_e32 v112, s29, v112
	v_lshl_add_u32 v113, v98, 4, s29
	v_lshl_add_u32 v118, v98, 2, s29
	v_lshl_add_u32 v112, v98, 1, s29
	v_subrev_u32_e32 v112, 0x200, v112
	v_lshrrev_b32_e32 v99, 3, v98
	v_and_b32_e32 v100, 7, v98
	v_lshlrev_b32_e32 v101, 8, v99
	v_lshl_add_u32 v101, v100, 5, v101
	v_add_u32_e32 v101, s29, v101
	v_bfe_u32 v99, v99, 1, 1
	v_xor_b32_e32 v100, 0, v99
	v_lshl_add_u32 v119, v100, 4, v101
	v_xor_b32_e32 v100, 1, v99
	v_lshl_add_u32 v120, v100, 4, v101
	s_lshr_b32 s44, 0x80000, s17
	s_sub_u32 s44, 0x3f800000, s44
	s_mov_b32 s45, s44
	v_mov_b32_e32 v98, s45
	v_log_f32_e32 v98, v98
	v_lshrrev_b32_e32 v99, 3, v196
	v_and_b32_e32 v99, 7, v99
	v_add_u32_e32 v100, 1, v99
	v_cvt_f32_u32_e32 v100, v100
	v_mul_f32_e32 v100, v98, v100
	v_exp_f32_e32 v107, v100
	v_sub_f32_e32 v101, 0, v100
	v_exp_f32_e32 v103, v101
	v_add_u32_e32 v100, 9, v99
	v_cvt_f32_u32_e32 v100, v100
	v_mul_f32_e32 v100, v98, v100
	v_exp_f32_e32 v108, v100
	v_sub_f32_e32 v101, 0, v100
	v_exp_f32_e32 v104, v101
	v_add_u32_e32 v100, 17, v99
	v_cvt_f32_u32_e32 v100, v100
	v_mul_f32_e32 v100, v98, v100
	v_exp_f32_e32 v109, v100
	v_sub_f32_e32 v101, 0, v100
	v_exp_f32_e32 v105, v101
	v_add_u32_e32 v100, 25, v99
	v_cvt_f32_u32_e32 v100, v100
	v_mul_f32_e32 v100, v98, v100
	v_exp_f32_e32 v110, v100
	v_sub_f32_e32 v101, 0, v100
	v_exp_f32_e32 v106, v101
	v_mul_f32_e32 v100, 0x42000000, v98
	v_exp_f32_e32 v100, v100
	s_nop 1
	v_readfirstlane_b32 s44, v100
	v_mov_b32_e32 v8, 0
	v_mov_b32_e32 v9, 0
	v_mov_b32_e32 v10, 0
	v_mov_b32_e32 v11, 0
	v_mov_b32_e32 v12, 0
	v_mov_b32_e32 v13, 0
	v_mov_b32_e32 v14, 0
	v_mov_b32_e32 v15, 0
	v_mov_b32_e32 v16, 0
	v_mov_b32_e32 v17, 0
	v_mov_b32_e32 v18, 0
	v_mov_b32_e32 v19, 0
	v_mov_b32_e32 v36, 0
	v_mov_b32_e32 v102, 0
	s_movk_i32 s12, 64
	s_nop 0
	global_load_dwordx4 v[62:65], v5, s[94:95]
	global_load_dwordx4 v[66:69], v5, s[94:95] offset:512
	global_load_ushort v31, v6, s[94:95]
	v_add_u32_e32 v5, 0x6800, v5
	v_add_u32_e32 v6, 0x10000, v6
	s_waitcnt vmcnt(0)
	s_waitcnt vmcnt(1)
	v_lshlrev_b32_e32 v94, 16, v66
	v_and_b32_e32 v95, 0xffff0000, v66
	v_lshlrev_b32_e32 v96, 16, v67
	v_and_b32_e32 v97, 0xffff0000, v67
	ds_write_b128 v2, v[94:97] offset:0
	v_lshlrev_b32_e32 v98, 16, v68
	v_and_b32_e32 v99, 0xffff0000, v68
	v_lshlrev_b32_e32 v100, 16, v69
	v_and_b32_e32 v101, 0xffff0000, v69
	ds_write_b128 v2, v[98:101] offset:16
	v_lshlrev_b32_e32 v94, 16, v62
	v_and_b32_e32 v95, 0xffff0000, v62
	v_lshlrev_b32_e32 v96, 16, v63
	v_and_b32_e32 v97, 0xffff0000, v63
	ds_write_b128 v2, v[94:97] offset:2048
	v_lshlrev_b32_e32 v98, 16, v64
	v_and_b32_e32 v99, 0xffff0000, v64
	v_lshlrev_b32_e32 v100, 16, v65
	v_and_b32_e32 v101, 0xffff0000, v65
	ds_write_b128 v2, v[98:101] offset:2064
	s_waitcnt vmcnt(0)
	v_lshlrev_b32_e32 v31, 16, v31
	v_mul_f32_e32 v31, v103, v31
	s_nop 0
	ds_write_b32 v4, v31 offset:4096
	global_load_dwordx4 v[70:73], v5, s[94:95]
	global_load_dwordx4 v[74:77], v5, s[94:95] offset:512
	global_load_ushort v33, v6, s[94:95]
	v_add_u32_e32 v5, 0x6800, v5
	v_add_u32_e32 v6, 0x10000, v6
	global_load_dwordx4 v[78:81], v5, s[94:95]
	global_load_dwordx4 v[82:85], v5, s[94:95] offset:512
	global_load_ushort v34, v6, s[94:95]
	v_add_u32_e32 v5, 0x6800, v5
	v_add_u32_e32 v6, 0x10000, v6
	global_load_dwordx4 v[86:89], v5, s[94:95]
	global_load_dwordx4 v[90:93], v5, s[94:95] offset:512
	global_load_ushort v35, v6, s[94:95]
	v_add_u32_e32 v5, 0x6800, v5
	v_add_u32_e32 v6, 0x10000, v6
	global_load_dwordx4 v[62:65], v5, s[94:95]
	global_load_dwordx4 v[66:69], v5, s[94:95] offset:512
	global_load_ushort v31, v6, s[94:95]
	v_add_u32_e32 v5, 0x6800, v5
	v_add_u32_e32 v6, 0x10000, v6
	ds_read_b128 v[22:25], v0 offset:0
	ds_read_b128 v[26:29], v0 offset:16
	ds_read_b128 v[46:49], v0 offset:2048
	ds_read_b128 v[50:53], v0 offset:2064
	ds_read_b32 v30, v1 offset:4096

.Lls0_8_noflush:
	s_waitcnt lgkmcnt(2)
	ds_read_b128 v[22:25], v0 offset:4352
	ds_read_b128 v[26:29], v0 offset:4368
	ds_read_b128 v[46:49], v0 offset:6400
	ds_read_b128 v[50:53], v0 offset:6416
	ds_read_b32 v30, v1 offset:8448
	v_fmac_f32_e32 v8, v38, v32
	v_fmac_f32_e32 v9, v39, v32
	v_mul_f32_e32 v102, v54, v8
	v_fmac_f32_e32 v10, v40, v32
	v_fmac_f32_e32 v102, v55, v9
	v_fmac_f32_e32 v11, v41, v32
	v_fmac_f32_e32 v102, v56, v10
	v_fmac_f32_e32 v12, v42, v32
	v_fmac_f32_e32 v102, v57, v11
	v_fmac_f32_e32 v13, v43, v32
	v_fmac_f32_e32 v102, v58, v12
	v_fmac_f32_e32 v14, v44, v32
	v_fmac_f32_e32 v102, v59, v13
	v_fmac_f32_e32 v15, v45, v32
	v_fmac_f32_e32 v102, v60, v14
	v_fmac_f32_e32 v102, v61, v15
	ds_write_b32 v118, v102 offset:10496
	s_waitcnt lgkmcnt(1)
	ds_read_b128 v[38:41], v0 offset:4608
	ds_read_b128 v[42:45], v0 offset:4624
	ds_read_b128 v[54:57], v0 offset:6656
	ds_read_b128 v[58:61], v0 offset:6672
	ds_read_b32 v32, v1 offset:8480
	v_fmac_f32_e32 v8, v22, v30
	v_fmac_f32_e32 v9, v23, v30
	v_mul_f32_e32 v36, v46, v8
	s_waitcnt vmcnt(10)
	v_fmac_f32_e32 v10, v24, v30
	v_fmac_f32_e32 v36, v47, v9
	v_fmac_f32_e32 v11, v25, v30
	v_lshlrev_b32_e32 v94, 16, v82
	v_fmac_f32_e32 v36, v48, v10
	v_fmac_f32_e32 v12, v26, v30
	v_fmac_f32_e32 v36, v49, v11
	v_and_b32_e32 v95, 0xffff0000, v82
	v_fmac_f32_e32 v13, v27, v30
	v_fmac_f32_e32 v36, v50, v12
	v_fmac_f32_e32 v14, v28, v30
	v_lshlrev_b32_e32 v96, 16, v83
	v_fmac_f32_e32 v36, v51, v13
	v_fmac_f32_e32 v15, v29, v30
	v_fmac_f32_e32 v36, v52, v14
	v_and_b32_e32 v97, 0xffff0000, v83
	v_fmac_f32_e32 v36, v53, v15
	ds_write_b32 v118, v36 offset:10752
	ds_write_b128 v2, v[94:97] offset:0
	v_lshlrev_b32_e32 v98, 16, v84
	s_waitcnt lgkmcnt(2)
	ds_read_b128 v[22:25], v0 offset:4864
	ds_read_b128 v[26:29], v0 offset:4880
	ds_read_b128 v[46:49], v0 offset:6912
	ds_read_b128 v[50:53], v0 offset:6928
	ds_read_b32 v30, v1 offset:8512
	v_fmac_f32_e32 v8, v38, v32
	v_fmac_f32_e32 v9, v39, v32
	v_mul_f32_e32 v102, v54, v8
	v_and_b32_e32 v99, 0xffff0000, v84
	v_fmac_f32_e32 v10, v40, v32
	v_fmac_f32_e32 v102, v55, v9
	v_fmac_f32_e32 v11, v41, v32
	v_lshlrev_b32_e32 v100, 16, v85
	v_fmac_f32_e32 v102, v56, v10
	v_fmac_f32_e32 v12, v42, v32
	v_fmac_f32_e32 v102, v57, v11
	v_and_b32_e32 v101, 0xffff0000, v85
	v_fmac_f32_e32 v13, v43, v32
	v_fmac_f32_e32 v102, v58, v12
	v_fmac_f32_e32 v14, v44, v32
	ds_write_b128 v2, v[98:101] offset:16
	v_fmac_f32_e32 v102, v59, v13
	v_fmac_f32_e32 v15, v45, v32
	v_fmac_f32_e32 v102, v60, v14
	v_lshlrev_b32_e32 v94, 16, v78
	v_fmac_f32_e32 v102, v61, v15
	ds_write_b32 v118, v102 offset:11008
	v_and_b32_e32 v95, 0xffff0000, v78
	v_lshlrev_b32_e32 v96, 16, v79
	s_waitcnt lgkmcnt(2)
	ds_read_b128 v[38:41], v0 offset:5120
	ds_read_b128 v[42:45], v0 offset:5136
	ds_read_b128 v[54:57], v0 offset:7168
	ds_read_b128 v[58:61], v0 offset:7184
	ds_read_b32 v32, v1 offset:8544
	v_fmac_f32_e32 v8, v22, v30
	v_fmac_f32_e32 v9, v23, v30
	v_mul_f32_e32 v36, v46, v8
	v_and_b32_e32 v97, 0xffff0000, v79
	v_fmac_f32_e32 v10, v24, v30
	v_fmac_f32_e32 v36, v47, v9
	v_fmac_f32_e32 v11, v25, v30
	ds_write_b128 v2, v[94:97] offset:2048
	v_fmac_f32_e32 v36, v48, v10
	v_fmac_f32_e32 v12, v26, v30
	v_fmac_f32_e32 v36, v49, v11
	v_lshlrev_b32_e32 v98, 16, v80
	v_fmac_f32_e32 v13, v27, v30
	v_fmac_f32_e32 v36, v50, v12
	v_fmac_f32_e32 v14, v28, v30
	v_and_b32_e32 v99, 0xffff0000, v80
	v_fmac_f32_e32 v36, v51, v13
	v_fmac_f32_e32 v15, v29, v30
	v_fmac_f32_e32 v36, v52, v14
	v_lshlrev_b32_e32 v100, 16, v81
	v_fmac_f32_e32 v36, v53, v15
	ds_write_b32 v118, v36 offset:11264
	v_and_b32_e32 v101, 0xffff0000, v81
	ds_write_b128 v2, v[98:101] offset:2064
	s_waitcnt lgkmcnt(3)
	ds_read_b128 v[22:25], v0 offset:5376
	ds_read_b128 v[26:29], v0 offset:5392
	ds_read_b128 v[46:49], v0 offset:7424
	ds_read_b128 v[50:53], v0 offset:7440
	ds_read_b32 v30, v1 offset:8576
	v_fmac_f32_e32 v8, v38, v32
	v_fmac_f32_e32 v9, v39, v32
	v_mul_f32_e32 v102, v54, v8
	s_waitcnt vmcnt(9)
	v_fmac_f32_e32 v10, v40, v32
	v_fmac_f32_e32 v102, v55, v9
	v_fmac_f32_e32 v11, v41, v32
	v_lshlrev_b32_e32 v34, 16, v34
	v_fmac_f32_e32 v102, v56, v10
	v_fmac_f32_e32 v12, v42, v32
	v_fmac_f32_e32 v102, v57, v11
	v_mul_f32_e32 v34, v105, v34
	v_fmac_f32_e32 v13, v43, v32
	v_fmac_f32_e32 v102, v58, v12
	v_fmac_f32_e32 v14, v44, v32
	s_nop 0
	v_fmac_f32_e32 v102, v59, v13
	v_fmac_f32_e32 v15, v45, v32
	v_fmac_f32_e32 v102, v60, v14
	ds_write_b32 v4, v34 offset:4096
	v_fmac_f32_e32 v102, v61, v15
	ds_write_b32 v118, v102 offset:11520
	s_waitcnt lgkmcnt(2)
	ds_read_b128 v[38:41], v0 offset:5632
	ds_read_b128 v[42:45], v0 offset:5648
	ds_read_b128 v[54:57], v0 offset:7680
	ds_read_b128 v[58:61], v0 offset:7696
	ds_read_b32 v32, v1 offset:8608
	v_fmac_f32_e32 v8, v22, v30
	v_fmac_f32_e32 v9, v23, v30
	v_mul_f32_e32 v36, v46, v8
	global_load_dwordx4 v[78:81], v5, s[94:95]
	global_load_dwordx4 v[82:85], v5, s[94:95] offset:512
	global_load_ushort v34, v6, s[94:95]
	v_add_u32_e32 v5, 0x6800, v5
	v_add_u32_e32 v6, 0x10000, v6
	v_fmac_f32_e32 v10, v24, v30
	v_fmac_f32_e32 v36, v47, v9
	v_fmac_f32_e32 v11, v25, v30
	ds_read_b128 v[124:127], v119 offset:8704
	v_fmac_f32_e32 v36, v48, v10
	v_fmac_f32_e32 v12, v26, v30
	v_fmac_f32_e32 v36, v49, v11
	ds_read_b128 v[128:131], v120 offset:8704
	v_fmac_f32_e32 v13, v27, v30
	v_fmac_f32_e32 v36, v50, v12
	v_fmac_f32_e32 v14, v28, v30
	v_fmac_f32_e32 v36, v51, v13
	v_fmac_f32_e32 v15, v29, v30
	v_fmac_f32_e32 v36, v52, v14
	v_fmac_f32_e32 v36, v53, v15
	ds_write_b32 v118, v36 offset:11776
	s_waitcnt lgkmcnt(3)
	ds_read_b128 v[22:25], v0 offset:5888
	ds_read_b128 v[26:29], v0 offset:5904
	ds_read_b128 v[46:49], v0 offset:7936
	ds_read_b128 v[50:53], v0 offset:7952
	ds_read_b32 v30, v1 offset:8640
	v_fmac_f32_e32 v8, v38, v32
	v_fmac_f32_e32 v9, v39, v32
	v_mul_f32_e32 v102, v54, v8
	v_fmac_f32_e32 v10, v40, v32
	v_fmac_f32_e32 v102, v55, v9
	v_fmac_f32_e32 v11, v41, v32
	v_fmac_f32_e32 v102, v56, v10
	v_fmac_f32_e32 v12, v42, v32
	v_fmac_f32_e32 v102, v57, v11
	v_fmac_f32_e32 v13, v43, v32
	v_fmac_f32_e32 v102, v58, v12
	v_fmac_f32_e32 v14, v44, v32
	v_fmac_f32_e32 v102, v59, v13
	v_fmac_f32_e32 v15, v45, v32
	v_fmac_f32_e32 v102, v60, v14
	v_fmac_f32_e32 v102, v61, v15
	ds_write_b32 v118, v102 offset:12032
	s_waitcnt lgkmcnt(1)
	ds_read_b128 v[38:41], v0 offset:6144
	ds_read_b128 v[42:45], v0 offset:6160
	ds_read_b128 v[54:57], v0 offset:8192
	ds_read_b128 v[58:61], v0 offset:8208
	ds_read_b32 v32, v1 offset:8672
	v_fmac_f32_e32 v8, v22, v30
	v_fmac_f32_e32 v9, v23, v30
	v_mul_f32_e32 v36, v46, v8
	s_waitcnt lgkmcnt(12)
	v_fmac_f32_e32 v10, v24, v30
	v_fmac_f32_e32 v36, v47, v9
	v_fmac_f32_e32 v11, v25, v30
	v_add_f32_e32 v124, v124, v128
	v_fmac_f32_e32 v36, v48, v10
	v_fmac_f32_e32 v12, v26, v30
	v_fmac_f32_e32 v36, v49, v11
	v_add_f32_e32 v125, v125, v129
	v_fmac_f32_e32 v13, v27, v30
	v_fmac_f32_e32 v36, v50, v12
	v_fmac_f32_e32 v14, v28, v30
	v_add_f32_e32 v126, v126, v130
	v_fmac_f32_e32 v36, v51, v13
	v_fmac_f32_e32 v15, v29, v30
	v_fmac_f32_e32 v36, v52, v14
	v_add_f32_e32 v127, v127, v131
	v_fmac_f32_e32 v36, v53, v15
	ds_write_b32 v118, v36 offset:12288
	v_add_f32_e32 v124, v124, v125
	v_add_f32_e32 v126, v126, v127
	v_add_f32_e32 v124, v124, v126
	v_mul_f32_e32 v124, v107, v124
	v_cvt_pk_bf16_f32 v21, v124, v124
	ds_write_b16 v112, v21 offset:13312
	s_waitcnt lgkmcnt(2)
	ds_read_b128 v[22:25], v0 offset:0
	ds_read_b128 v[26:29], v0 offset:16
	ds_read_b128 v[46:49], v0 offset:2048
	ds_read_b128 v[50:53], v0 offset:2064
	ds_read_b32 v30, v1 offset:4096
	v_fmac_f32_e32 v8, v38, v32
	v_fmac_f32_e32 v9, v39, v32
	v_mul_f32_e32 v102, v54, v8
	v_fmac_f32_e32 v10, v40, v32
	v_fmac_f32_e32 v102, v55, v9
	v_fmac_f32_e32 v11, v41, v32
	v_fmac_f32_e32 v102, v56, v10
	v_fmac_f32_e32 v12, v42, v32
	v_fmac_f32_e32 v102, v57, v11
	v_fmac_f32_e32 v13, v43, v32
	v_fmac_f32_e32 v102, v58, v12
	v_fmac_f32_e32 v14, v44, v32
	v_fmac_f32_e32 v102, v59, v13
	v_fmac_f32_e32 v15, v45, v32
	v_fmac_f32_e32 v102, v60, v14
	v_fmac_f32_e32 v102, v61, v15
	ds_write_b32 v118, v102 offset:12544
	s_waitcnt lgkmcnt(1)
	ds_read_b128 v[38:41], v0 offset:256
	ds_read_b128 v[42:45], v0 offset:272
	ds_read_b128 v[54:57], v0 offset:2304
	ds_read_b128 v[58:61], v0 offset:2320
	ds_read_b32 v32, v1 offset:4128
	v_fmac_f32_e32 v8, v22, v30
	v_fmac_f32_e32 v9, v23, v30
	v_mul_f32_e32 v36, v46, v8
	s_waitcnt vmcnt(10)
	v_fmac_f32_e32 v10, v24, v30
	v_fmac_f32_e32 v36, v47, v9
	v_fmac_f32_e32 v11, v25, v30
	v_lshlrev_b32_e32 v94, 16, v90
	v_fmac_f32_e32 v36, v48, v10
	v_fmac_f32_e32 v12, v26, v30
	v_fmac_f32_e32 v36, v49, v11
	v_and_b32_e32 v95, 0xffff0000, v90
	v_fmac_f32_e32 v13, v27, v30
	v_fmac_f32_e32 v36, v50, v12
	v_fmac_f32_e32 v14, v28, v30
	v_lshlrev_b32_e32 v96, 16, v91
	v_fmac_f32_e32 v36, v51, v13
	v_fmac_f32_e32 v15, v29, v30
	v_fmac_f32_e32 v36, v52, v14
	v_and_b32_e32 v97, 0xffff0000, v91
	v_fmac_f32_e32 v36, v53, v15
	ds_write_b32 v118, v36 offset:8704
	ds_write_b128 v2, v[94:97] offset:4352
	v_lshlrev_b32_e32 v98, 16, v92
	s_waitcnt lgkmcnt(2)
	ds_read_b128 v[22:25], v0 offset:512
	ds_read_b128 v[26:29], v0 offset:528
	ds_read_b128 v[46:49], v0 offset:2560
	ds_read_b128 v[50:53], v0 offset:2576
	ds_read_b32 v30, v1 offset:4160
	v_fmac_f32_e32 v8, v38, v32
	v_fmac_f32_e32 v9, v39, v32
	v_mul_f32_e32 v102, v54, v8
	v_and_b32_e32 v99, 0xffff0000, v92
	v_fmac_f32_e32 v10, v40, v32
	v_fmac_f32_e32 v102, v55, v9
	v_fmac_f32_e32 v11, v41, v32
	v_lshlrev_b32_e32 v100, 16, v93
	v_fmac_f32_e32 v102, v56, v10
	v_fmac_f32_e32 v12, v42, v32
	v_fmac_f32_e32 v102, v57, v11
	v_and_b32_e32 v101, 0xffff0000, v93
	v_fmac_f32_e32 v13, v43, v32
	v_fmac_f32_e32 v102, v58, v12
	v_fmac_f32_e32 v14, v44, v32
	ds_write_b128 v2, v[98:101] offset:4368
	v_fmac_f32_e32 v102, v59, v13
	v_fmac_f32_e32 v15, v45, v32
	v_fmac_f32_e32 v102, v60, v14
	v_lshlrev_b32_e32 v94, 16, v86
	v_fmac_f32_e32 v102, v61, v15
	ds_write_b32 v118, v102 offset:8960
	v_and_b32_e32 v95, 0xffff0000, v86
	v_lshlrev_b32_e32 v96, 16, v87
	s_waitcnt lgkmcnt(2)
	ds_read_b128 v[38:41], v0 offset:768
	ds_read_b128 v[42:45], v0 offset:784
	ds_read_b128 v[54:57], v0 offset:2816
	ds_read_b128 v[58:61], v0 offset:2832
	ds_read_b32 v32, v1 offset:4192
	v_fmac_f32_e32 v8, v22, v30
	v_fmac_f32_e32 v9, v23, v30
	v_mul_f32_e32 v36, v46, v8
	v_and_b32_e32 v97, 0xffff0000, v87
	v_fmac_f32_e32 v10, v24, v30
	v_fmac_f32_e32 v36, v47, v9
	v_fmac_f32_e32 v11, v25, v30
	ds_write_b128 v2, v[94:97] offset:6400
	v_fmac_f32_e32 v36, v48, v10
	v_fmac_f32_e32 v12, v26, v30
	v_fmac_f32_e32 v36, v49, v11
	v_lshlrev_b32_e32 v98, 16, v88
	v_fmac_f32_e32 v13, v27, v30
	v_fmac_f32_e32 v36, v50, v12
	v_fmac_f32_e32 v14, v28, v30
	v_and_b32_e32 v99, 0xffff0000, v88
	v_fmac_f32_e32 v36, v51, v13
	v_fmac_f32_e32 v15, v29, v30
	v_fmac_f32_e32 v36, v52, v14
	v_lshlrev_b32_e32 v100, 16, v89
	v_fmac_f32_e32 v36, v53, v15
	ds_write_b32 v118, v36 offset:9216
	v_and_b32_e32 v101, 0xffff0000, v89
	ds_write_b128 v2, v[98:101] offset:6416
	s_waitcnt lgkmcnt(3)
	ds_read_b128 v[22:25], v0 offset:1024
	ds_read_b128 v[26:29], v0 offset:1040
	ds_read_b128 v[46:49], v0 offset:3072
	ds_read_b128 v[50:53], v0 offset:3088
	ds_read_b32 v30, v1 offset:4224
	v_fmac_f32_e32 v8, v38, v32
	v_fmac_f32_e32 v9, v39, v32
	v_mul_f32_e32 v102, v54, v8
	s_waitcnt vmcnt(9)
	v_fmac_f32_e32 v10, v40, v32
	v_fmac_f32_e32 v102, v55, v9
	v_fmac_f32_e32 v11, v41, v32
	v_lshlrev_b32_e32 v35, 16, v35
	v_fmac_f32_e32 v102, v56, v10
	v_fmac_f32_e32 v12, v42, v32
	v_fmac_f32_e32 v102, v57, v11
	v_mul_f32_e32 v35, v106, v35
	v_fmac_f32_e32 v13, v43, v32
	v_fmac_f32_e32 v102, v58, v12
	v_fmac_f32_e32 v14, v44, v32
	s_nop 0
	v_fmac_f32_e32 v102, v59, v13
	v_fmac_f32_e32 v15, v45, v32
	v_fmac_f32_e32 v102, v60, v14
	ds_write_b32 v4, v35 offset:8448
	v_fmac_f32_e32 v102, v61, v15
	ds_write_b32 v118, v102 offset:9472
	s_waitcnt lgkmcnt(2)
	ds_read_b128 v[38:41], v0 offset:1280
	ds_read_b128 v[42:45], v0 offset:1296
	ds_read_b128 v[54:57], v0 offset:3328
	ds_read_b128 v[58:61], v0 offset:3344
	ds_read_b32 v32, v1 offset:4256
	v_fmac_f32_e32 v8, v22, v30
	v_fmac_f32_e32 v9, v23, v30
	v_mul_f32_e32 v36, v46, v8
	global_load_dwordx4 v[86:89], v5, s[94:95]
	global_load_dwordx4 v[90:93], v5, s[94:95] offset:512
	global_load_ushort v35, v6, s[94:95]
	v_add_u32_e32 v5, 0x6800, v5
	v_add_u32_e32 v6, 0x10000, v6
	v_fmac_f32_e32 v10, v24, v30
	v_fmac_f32_e32 v36, v47, v9
	v_fmac_f32_e32 v11, v25, v30
	ds_read_b128 v[124:127], v119 offset:10752
	v_fmac_f32_e32 v36, v48, v10
	v_fmac_f32_e32 v12, v26, v30
	v_fmac_f32_e32 v36, v49, v11
	ds_read_b128 v[128:131], v120 offset:10752
	v_fmac_f32_e32 v13, v27, v30
	v_fmac_f32_e32 v36, v50, v12
	v_fmac_f32_e32 v14, v28, v30
	v_fmac_f32_e32 v36, v51, v13
	v_fmac_f32_e32 v15, v29, v30
	v_fmac_f32_e32 v36, v52, v14
	v_fmac_f32_e32 v36, v53, v15
	ds_write_b32 v118, v36 offset:9728
	s_waitcnt lgkmcnt(3)
	ds_read_b128 v[22:25], v0 offset:1536
	ds_read_b128 v[26:29], v0 offset:1552
	ds_read_b128 v[46:49], v0 offset:3584
	ds_read_b128 v[50:53], v0 offset:3600
	ds_read_b32 v30, v1 offset:4288
	v_fmac_f32_e32 v8, v38, v32
	v_fmac_f32_e32 v9, v39, v32
	v_mul_f32_e32 v102, v54, v8
	v_fmac_f32_e32 v10, v40, v32
	v_fmac_f32_e32 v102, v55, v9
	v_fmac_f32_e32 v11, v41, v32
	v_fmac_f32_e32 v102, v56, v10
	v_fmac_f32_e32 v12, v42, v32
	v_fmac_f32_e32 v102, v57, v11
	v_fmac_f32_e32 v13, v43, v32
	v_fmac_f32_e32 v102, v58, v12
	v_fmac_f32_e32 v14, v44, v32
	v_fmac_f32_e32 v102, v59, v13
	v_fmac_f32_e32 v15, v45, v32
	v_fmac_f32_e32 v102, v60, v14
	v_fmac_f32_e32 v102, v61, v15
	ds_write_b32 v118, v102 offset:9984
	s_waitcnt lgkmcnt(1)
	ds_read_b128 v[38:41], v0 offset:1792
	ds_read_b128 v[42:45], v0 offset:1808
	ds_read_b128 v[54:57], v0 offset:3840
	ds_read_b128 v[58:61], v0 offset:3856
	ds_read_b32 v32, v1 offset:4320
	v_fmac_f32_e32 v8, v22, v30
	v_fmac_f32_e32 v9, v23, v30
	v_mul_f32_e32 v36, v46, v8
	s_waitcnt lgkmcnt(12)
	v_fmac_f32_e32 v10, v24, v30
	v_fmac_f32_e32 v36, v47, v9
	v_fmac_f32_e32 v11, v25, v30
	v_add_f32_e32 v124, v124, v128
	v_fmac_f32_e32 v36, v48, v10
	v_fmac_f32_e32 v12, v26, v30
	v_fmac_f32_e32 v36, v49, v11
	v_add_f32_e32 v125, v125, v129
	v_fmac_f32_e32 v13, v27, v30
	v_fmac_f32_e32 v36, v50, v12
	v_fmac_f32_e32 v14, v28, v30
	v_add_f32_e32 v126, v126, v130
	v_fmac_f32_e32 v36, v51, v13
	v_fmac_f32_e32 v15, v29, v30
	v_fmac_f32_e32 v36, v52, v14
	v_add_f32_e32 v127, v127, v131
	v_fmac_f32_e32 v36, v53, v15
	ds_write_b32 v118, v36 offset:10240
	v_add_f32_e32 v124, v124, v125
	v_add_f32_e32 v126, v126, v127
	v_add_f32_e32 v124, v124, v126
	v_mul_f32_e32 v124, v108, v124
	v_cvt_pk_bf16_f32 v21, v124, v124
	ds_write_b16 v112, v21 offset:13440
	s_waitcnt lgkmcnt(2)
	ds_read_b128 v[22:25], v0 offset:4352
	ds_read_b128 v[26:29], v0 offset:4368
	ds_read_b128 v[46:49], v0 offset:6400
	ds_read_b128 v[50:53], v0 offset:6416
	ds_read_b32 v30, v1 offset:8448
	v_fmac_f32_e32 v8, v38, v32
	v_fmac_f32_e32 v9, v39, v32
	v_mul_f32_e32 v102, v54, v8
	v_fmac_f32_e32 v10, v40, v32
	v_fmac_f32_e32 v102, v55, v9
	v_fmac_f32_e32 v11, v41, v32
	v_fmac_f32_e32 v102, v56, v10
	v_fmac_f32_e32 v12, v42, v32
	v_fmac_f32_e32 v102, v57, v11
	v_fmac_f32_e32 v13, v43, v32
	v_fmac_f32_e32 v102, v58, v12
	v_fmac_f32_e32 v14, v44, v32
	v_fmac_f32_e32 v102, v59, v13
	v_fmac_f32_e32 v15, v45, v32
	v_fmac_f32_e32 v102, v60, v14
	v_fmac_f32_e32 v102, v61, v15
	ds_write_b32 v118, v102 offset:10496
	s_waitcnt lgkmcnt(1)
	ds_read_b128 v[38:41], v0 offset:4608
	ds_read_b128 v[42:45], v0 offset:4624
	ds_read_b128 v[54:57], v0 offset:6656
	ds_read_b128 v[58:61], v0 offset:6672
	ds_read_b32 v32, v1 offset:8480
	v_fmac_f32_e32 v8, v22, v30
	v_fmac_f32_e32 v9, v23, v30
	v_mul_f32_e32 v36, v46, v8
	s_waitcnt vmcnt(10)
	v_fmac_f32_e32 v10, v24, v30
	v_fmac_f32_e32 v36, v47, v9
	v_fmac_f32_e32 v11, v25, v30
	v_lshlrev_b32_e32 v94, 16, v66
	v_fmac_f32_e32 v36, v48, v10
	v_fmac_f32_e32 v12, v26, v30
	v_fmac_f32_e32 v36, v49, v11
	v_and_b32_e32 v95, 0xffff0000, v66
	v_fmac_f32_e32 v13, v27, v30
	v_fmac_f32_e32 v36, v50, v12
	v_fmac_f32_e32 v14, v28, v30
	v_lshlrev_b32_e32 v96, 16, v67
	v_fmac_f32_e32 v36, v51, v13
	v_fmac_f32_e32 v15, v29, v30
	v_fmac_f32_e32 v36, v52, v14
	v_and_b32_e32 v97, 0xffff0000, v67
	v_fmac_f32_e32 v36, v53, v15
	ds_write_b32 v118, v36 offset:10752
	ds_write_b128 v2, v[94:97] offset:0
	v_lshlrev_b32_e32 v98, 16, v68
	s_waitcnt lgkmcnt(2)
	ds_read_b128 v[22:25], v0 offset:4864
	ds_read_b128 v[26:29], v0 offset:4880
	ds_read_b128 v[46:49], v0 offset:6912
	ds_read_b128 v[50:53], v0 offset:6928
	ds_read_b32 v30, v1 offset:8512
	v_fmac_f32_e32 v8, v38, v32
	v_fmac_f32_e32 v9, v39, v32
	v_mul_f32_e32 v102, v54, v8
	v_and_b32_e32 v99, 0xffff0000, v68
	v_fmac_f32_e32 v10, v40, v32
	v_fmac_f32_e32 v102, v55, v9
	v_fmac_f32_e32 v11, v41, v32
	v_lshlrev_b32_e32 v100, 16, v69
	v_fmac_f32_e32 v102, v56, v10
	v_fmac_f32_e32 v12, v42, v32
	v_fmac_f32_e32 v102, v57, v11
	v_and_b32_e32 v101, 0xffff0000, v69
	v_fmac_f32_e32 v13, v43, v32
	v_fmac_f32_e32 v102, v58, v12
	v_fmac_f32_e32 v14, v44, v32
	ds_write_b128 v2, v[98:101] offset:16
	v_fmac_f32_e32 v102, v59, v13
	v_fmac_f32_e32 v15, v45, v32
	v_fmac_f32_e32 v102, v60, v14
	v_lshlrev_b32_e32 v94, 16, v62
	v_fmac_f32_e32 v102, v61, v15
	ds_write_b32 v118, v102 offset:11008
	v_and_b32_e32 v95, 0xffff0000, v62
	v_lshlrev_b32_e32 v96, 16, v63
	s_waitcnt lgkmcnt(2)
	ds_read_b128 v[38:41], v0 offset:5120
	ds_read_b128 v[42:45], v0 offset:5136
	ds_read_b128 v[54:57], v0 offset:7168
	ds_read_b128 v[58:61], v0 offset:7184
	ds_read_b32 v32, v1 offset:8544
	v_fmac_f32_e32 v8, v22, v30
	v_fmac_f32_e32 v9, v23, v30
	v_mul_f32_e32 v36, v46, v8
	v_and_b32_e32 v97, 0xffff0000, v63
	v_fmac_f32_e32 v10, v24, v30
	v_fmac_f32_e32 v36, v47, v9
	v_fmac_f32_e32 v11, v25, v30
	ds_write_b128 v2, v[94:97] offset:2048
	v_fmac_f32_e32 v36, v48, v10
	v_fmac_f32_e32 v12, v26, v30
	v_fmac_f32_e32 v36, v49, v11
	v_lshlrev_b32_e32 v98, 16, v64
	v_fmac_f32_e32 v13, v27, v30
	v_fmac_f32_e32 v36, v50, v12
	v_fmac_f32_e32 v14, v28, v30
	v_and_b32_e32 v99, 0xffff0000, v64
	v_fmac_f32_e32 v36, v51, v13
	v_fmac_f32_e32 v15, v29, v30
	v_fmac_f32_e32 v36, v52, v14
	v_lshlrev_b32_e32 v100, 16, v65
	v_fmac_f32_e32 v36, v53, v15
	ds_write_b32 v118, v36 offset:11264
	v_and_b32_e32 v101, 0xffff0000, v65
	ds_write_b128 v2, v[98:101] offset:2064
	s_waitcnt lgkmcnt(3)
	ds_read_b128 v[22:25], v0 offset:5376
	ds_read_b128 v[26:29], v0 offset:5392
	ds_read_b128 v[46:49], v0 offset:7424
	ds_read_b128 v[50:53], v0 offset:7440
	ds_read_b32 v30, v1 offset:8576
	v_fmac_f32_e32 v8, v38, v32
	v_fmac_f32_e32 v9, v39, v32
	v_mul_f32_e32 v102, v54, v8
	s_waitcnt vmcnt(9)
	v_fmac_f32_e32 v10, v40, v32
	v_fmac_f32_e32 v102, v55, v9
	v_fmac_f32_e32 v11, v41, v32
	v_lshlrev_b32_e32 v31, 16, v31
	v_fmac_f32_e32 v102, v56, v10
	v_fmac_f32_e32 v12, v42, v32
	v_fmac_f32_e32 v102, v57, v11
	v_mul_f32_e32 v31, v103, v31
	v_fmac_f32_e32 v13, v43, v32
	v_fmac_f32_e32 v102, v58, v12
	v_fmac_f32_e32 v14, v44, v32
	s_nop 0
	v_fmac_f32_e32 v102, v59, v13
	v_fmac_f32_e32 v15, v45, v32
	v_fmac_f32_e32 v102, v60, v14
	ds_write_b32 v4, v31 offset:4096
	v_fmac_f32_e32 v102, v61, v15
	ds_write_b32 v118, v102 offset:11520
	s_waitcnt lgkmcnt(2)
	ds_read_b128 v[38:41], v0 offset:5632
	ds_read_b128 v[42:45], v0 offset:5648
	ds_read_b128 v[54:57], v0 offset:7680
	ds_read_b128 v[58:61], v0 offset:7696
	ds_read_b32 v32, v1 offset:8608
	v_fmac_f32_e32 v8, v22, v30
	v_fmac_f32_e32 v9, v23, v30
	v_mul_f32_e32 v36, v46, v8
	global_load_dwordx4 v[62:65], v5, s[94:95]
	global_load_dwordx4 v[66:69], v5, s[94:95] offset:512
	global_load_ushort v31, v6, s[94:95]
	v_add_u32_e32 v5, 0x6800, v5
	v_add_u32_e32 v6, 0x10000, v6
	v_fmac_f32_e32 v10, v24, v30
	v_fmac_f32_e32 v36, v47, v9
	v_fmac_f32_e32 v11, v25, v30
	ds_read_b128 v[124:127], v119 offset:8704
	v_fmac_f32_e32 v36, v48, v10
	v_fmac_f32_e32 v12, v26, v30
	v_fmac_f32_e32 v36, v49, v11
	ds_read_b128 v[128:131], v120 offset:8704
	v_fmac_f32_e32 v13, v27, v30
	v_fmac_f32_e32 v36, v50, v12
	v_fmac_f32_e32 v14, v28, v30
	v_fmac_f32_e32 v36, v51, v13
	v_fmac_f32_e32 v15, v29, v30
	v_fmac_f32_e32 v36, v52, v14
	v_fmac_f32_e32 v36, v53, v15
	ds_write_b32 v118, v36 offset:11776
	s_waitcnt lgkmcnt(3)
	ds_read_b128 v[22:25], v0 offset:5888
	ds_read_b128 v[26:29], v0 offset:5904
	ds_read_b128 v[46:49], v0 offset:7936
	ds_read_b128 v[50:53], v0 offset:7952
	ds_read_b32 v30, v1 offset:8640
	v_fmac_f32_e32 v8, v38, v32
	v_fmac_f32_e32 v9, v39, v32
	v_mul_f32_e32 v102, v54, v8
	v_fmac_f32_e32 v10, v40, v32
	v_fmac_f32_e32 v102, v55, v9
	v_fmac_f32_e32 v11, v41, v32
	v_fmac_f32_e32 v102, v56, v10
	v_fmac_f32_e32 v12, v42, v32
	v_fmac_f32_e32 v102, v57, v11
	v_fmac_f32_e32 v13, v43, v32
	v_fmac_f32_e32 v102, v58, v12
	v_fmac_f32_e32 v14, v44, v32
	v_fmac_f32_e32 v102, v59, v13
	v_fmac_f32_e32 v15, v45, v32
	v_fmac_f32_e32 v102, v60, v14
	v_fmac_f32_e32 v102, v61, v15
	ds_write_b32 v118, v102 offset:12032
	s_waitcnt lgkmcnt(1)
	ds_read_b128 v[38:41], v0 offset:6144
	ds_read_b128 v[42:45], v0 offset:6160
	ds_read_b128 v[54:57], v0 offset:8192
	ds_read_b128 v[58:61], v0 offset:8208
	ds_read_b32 v32, v1 offset:8672
	v_fmac_f32_e32 v8, v22, v30
	v_fmac_f32_e32 v9, v23, v30
	v_mul_f32_e32 v36, v46, v8
	s_waitcnt lgkmcnt(12)
	v_fmac_f32_e32 v10, v24, v30
	v_fmac_f32_e32 v36, v47, v9
	v_fmac_f32_e32 v11, v25, v30
	v_add_f32_e32 v124, v124, v128
	v_fmac_f32_e32 v36, v48, v10
	v_fmac_f32_e32 v12, v26, v30
	v_fmac_f32_e32 v36, v49, v11
	v_add_f32_e32 v125, v125, v129
	v_fmac_f32_e32 v13, v27, v30
	v_fmac_f32_e32 v36, v50, v12
	v_fmac_f32_e32 v14, v28, v30
	v_add_f32_e32 v126, v126, v130
	v_fmac_f32_e32 v36, v51, v13
	v_fmac_f32_e32 v15, v29, v30
	v_fmac_f32_e32 v36, v52, v14
	v_add_f32_e32 v127, v127, v131
	v_fmac_f32_e32 v36, v53, v15
	ds_write_b32 v118, v36 offset:12288
	v_add_f32_e32 v124, v124, v125
	v_add_f32_e32 v126, v126, v127
	v_add_f32_e32 v124, v124, v126
	v_mul_f32_e32 v124, v109, v124
	v_cvt_pk_bf16_f32 v21, v124, v124
	ds_write_b16 v112, v21 offset:13568
	s_waitcnt lgkmcnt(2)
	ds_read_b128 v[22:25], v0 offset:0
	ds_read_b128 v[26:29], v0 offset:16
	ds_read_b128 v[46:49], v0 offset:2048
	ds_read_b128 v[50:53], v0 offset:2064
	ds_read_b32 v30, v1 offset:4096
	v_fmac_f32_e32 v8, v38, v32
	v_fmac_f32_e32 v9, v39, v32
	v_mul_f32_e32 v102, v54, v8
	v_fmac_f32_e32 v10, v40, v32
	v_fmac_f32_e32 v102, v55, v9
	v_fmac_f32_e32 v11, v41, v32
	v_fmac_f32_e32 v102, v56, v10
	v_fmac_f32_e32 v12, v42, v32
	v_fmac_f32_e32 v102, v57, v11
	v_fmac_f32_e32 v13, v43, v32
	v_fmac_f32_e32 v102, v58, v12
	v_fmac_f32_e32 v14, v44, v32
	v_fmac_f32_e32 v102, v59, v13
	v_fmac_f32_e32 v15, v45, v32
	v_fmac_f32_e32 v102, v60, v14
	v_fmac_f32_e32 v102, v61, v15
	ds_write_b32 v118, v102 offset:12544
	v_mul_f32_e32 v8, s44, v8
	v_mul_f32_e32 v9, s44, v9
	v_mul_f32_e32 v10, s44, v10
	v_mul_f32_e32 v11, s44, v11
	v_mul_f32_e32 v12, s44, v12
	v_mul_f32_e32 v13, s44, v13
	v_mul_f32_e32 v14, s44, v14
	v_mul_f32_e32 v15, s44, v15
	s_sub_u32 s12, s12, 1
	s_cmp_lg_u32 s12, 0
	s_cbranch_scc1 .Lls0_8_loop
	ds_read_b128 v[124:127], v119 offset:10752
	ds_read_b128 v[128:131], v120 offset:10752
	s_waitcnt lgkmcnt(0)
	v_add_f32_e32 v124, v124, v128
	v_add_f32_e32 v125, v125, v129
	v_add_f32_e32 v126, v126, v130
	v_add_f32_e32 v127, v127, v131
	v_add_f32_e32 v124, v124, v125
	v_add_f32_e32 v126, v126, v127
	v_add_f32_e32 v124, v124, v126
	v_mul_f32_e32 v124, v110, v124
	v_cvt_pk_bf16_f32 v21, v124, v124
	ds_write_b16 v112, v21 offset:13696
	s_waitcnt lgkmcnt(0)
	ds_read_b128 v[114:117], v113 offset:13312
	s_waitcnt lgkmcnt(0)
	global_store_dwordx4 v7, v[114:117], s[94:95]
	v_add_u32_e32 v7, 0x20000, v7
	s_nop 0
	ds_read_b128 v[114:117], v113 offset:14336
	s_waitcnt lgkmcnt(0)
	global_store_dwordx4 v7, v[114:117], s[94:95]
	v_add_u32_e32 v7, 0x20000, v7
	s_nop 0
	ds_read_b128 v[114:117], v113 offset:15360
	s_waitcnt lgkmcnt(0)
	global_store_dwordx4 v7, v[114:117], s[94:95]
	v_add_u32_e32 v7, 0x20000, v7
	s_nop 0
	ds_read_b128 v[114:117], v113 offset:16384
	s_waitcnt lgkmcnt(0)
	global_store_dwordx4 v7, v[114:117], s[94:95]
	v_add_u32_e32 v7, 0x20000, v7
	s_nop 0
	ds_read_b128 v[114:117], v113 offset:17408
	s_waitcnt lgkmcnt(0)
	global_store_dwordx4 v7, v[114:117], s[94:95]
	v_add_u32_e32 v7, 0x20000, v7
	s_nop 0
	ds_read_b128 v[114:117], v113 offset:18432
	s_waitcnt lgkmcnt(0)
	global_store_dwordx4 v7, v[114:117], s[94:95]
	v_add_u32_e32 v7, 0x20000, v7
	s_nop 0
	ds_read_b128 v[114:117], v113 offset:19456
	s_waitcnt lgkmcnt(0)
	global_store_dwordx4 v7, v[114:117], s[94:95]
	v_add_u32_e32 v7, 0x20000, v7
	s_nop 0
	ds_read_b128 v[114:117], v113 offset:20480
	s_waitcnt lgkmcnt(0)
	global_store_dwordx4 v7, v[114:117], s[94:95]
	v_add_u32_e32 v7, 0x20000, v7
	s_nop 0
	global_store_dword v111, v8, s[26:27] offset:0
	global_store_dword v111, v9, s[26:27] offset:256
	global_store_dword v111, v10, s[26:27] offset:512
	global_store_dword v111, v11, s[26:27] offset:768
	global_store_dword v111, v12, s[26:27] offset:1024
	global_store_dword v111, v13, s[26:27] offset:1280
	global_store_dword v111, v14, s[26:27] offset:1536
	global_store_dword v111, v15, s[26:27] offset:1792
	s_waitcnt vmcnt(0) lgkmcnt(0)
	s_branch .Lls_done
.Lls2_8_entry:
	v_and_b32_e32 v82, 63, v196
	v_and_b32_e32 v83, 7, v82
	v_lshrrev_b32_e32 v84, 3, v82
	s_min_u32 s29, s0, 4
	s_mul_i32 s29, s29, 0x5600
	v_and_b32_e32 v85, 3, v83
	v_cmp_eq_u32_e64 s[6:7], 1, v85
	v_cmp_eq_u32_e64 s[8:9], 2, v85
	v_cmp_eq_u32_e64 s[10:11], 3, v85
	v_lshl_add_u32 v0, v83, 5, s29
	v_lshl_add_u32 v1, v84, 2, s29
	s_lshl_b32 s37, s16, 11
	v_lshrrev_b32_e32 v83, 3, v82
	v_and_b32_e32 v84, 7, v82
	v_add_u32_e32 v85, s37, v83
	s_lshl_b32 s21, s17, 7
	s_add_u32 s21, s21, 0x10800500
	v_mul_u32_u24_e32 v5, 0xd00, v85
	v_lshl_add_u32 v5, v84, 4, v5
	v_add_u32_e32 v5, s21, v5
	v_lshlrev_b32_e32 v2, 8, v83
	v_lshl_add_u32 v2, v84, 5, v2
	v_add_u32_e32 v2, s29, v2
	s_lshl_b32 s21, s17, 8
	s_add_u32 s21, s21, 0x13e00200
	v_lshrrev_b32_e32 v8, 4, v82
	v_add_u32_e32 v8, s37, v8
	v_mul_u32_u24_e32 v8, 0x630, v8
	v_and_b32_e32 v88, 15, v82
	v_lshl_add_u32 v8, v88, 4, v8
	v_add_u32_e32 v8, s21, v8
	v_add_u32_e32 v88, 0x18c0, v8
	v_lshrrev_b32_e32 v84, 3, v82
	v_and_b32_e32 v83, 7, v82
	v_add_u32_e32 v85, s37, v84
	s_lshl_b32 s22, s14, 3
	s_lshl_b32 s21, s17, 6
	s_add_u32 s21, s21, s22
	s_lshl_b32 s44, s21, 1
	s_add_u32 s44, s44, 0x8401220
	v_lshlrev_b32_e32 v6, 13, v85
	v_lshlrev_b32_e32 v4, 5, v84
	v_lshl_add_u32 v4, v83, 2, v4
	v_lshl_add_u32 v6, v83, 1, v6
	v_add_u32_e32 v6, s44, v6
	v_add_u32_e32 v4, s29, v4
	v_and_b32_e32 v83, 7, v82
	v_lshrrev_b32_e32 v84, 3, v82
	v_add_u32_e32 v85, s37, v82
	v_lshlrev_b32_e32 v7, 11, v85
	s_lshl_b32 s44, s21, 1
	s_add_u32 s44, s44, 0x6300400
	v_add_u32_e32 v7, s44, v7
	s_lshl_b32 s44, s28, 3
	s_add_u32 s44, s44, s16
	s_lshl_b32 s44, s44, 2
	s_add_u32 s44, s44, s17
	s_mul_i32 s44, s44, 0x4000
	s_add_u32 s44, s44, 0x4380000
	s_lshl_b32 s24, s22, 2
	s_add_u32 s44, s44, s24
	v_lshlrev_b32_e32 v89, 11, v83
	v_lshl_add_u32 v89, v84, 2, v89
	v_add_u32_e32 v89, s44, v89
	v_readlane_b32 s26, v253, 29
	v_readlane_b32 s27, v253, 30
	v_lshlrev_b32_e32 v90, 4, v83
	v_lshl_add_u32 v90, v84, 1, v90
	v_add_u32_e32 v90, s29, v90
	v_lshl_add_u32 v91, v82, 4, s29
	v_lshl_add_u32 v96, v82, 2, s29
	v_lshl_add_u32 v90, v82, 1, s29
	v_subrev_u32_e32 v90, 0x200, v90
	v_lshrrev_b32_e32 v83, 3, v82
	v_and_b32_e32 v84, 7, v82
	v_lshlrev_b32_e32 v85, 8, v83
	v_lshl_add_u32 v85, v84, 5, v85
	v_add_u32_e32 v85, s29, v85
	v_bfe_u32 v83, v83, 1, 1
	v_xor_b32_e32 v84, 0, v83
	v_lshl_add_u32 v97, v84, 4, v85
	v_xor_b32_e32 v84, 1, v83
	v_lshl_add_u32 v98, v84, 4, v85
	v_mov_b32_e32 v10, 0
	v_mov_b32_e32 v11, 0
	v_mov_b32_e32 v12, 0
	v_mov_b32_e32 v13, 0
	v_mov_b32_e32 v14, 0
	v_mov_b32_e32 v15, 0
	v_mov_b32_e32 v16, 0
	v_mov_b32_e32 v17, 0
	v_mov_b32_e32 v9, 0
	v_mov_b32_e32 v18, 0
	v_mov_b32_e32 v19, 0
	v_mov_b32_e32 v20, 0
	v_mov_b32_e32 v86, 0
	v_mov_b32_e32 v87, 0
	s_movk_i32 s12, 64
	s_nop 0
	global_load_dwordx4 v[62:65], v5, s[94:95]
	global_load_ushort v23, v6, s[94:95]
	v_add_u32_e32 v5, 0x6800, v5
	v_add_u32_e32 v6, 0x10000, v6
	s_waitcnt vmcnt(0)
	s_waitcnt vmcnt(1)
	v_lshlrev_b32_e32 v78, 16, v62
	v_and_b32_e32 v79, 0xffff0000, v62
	v_lshlrev_b32_e32 v80, 16, v63
	v_and_b32_e32 v81, 0xffff0000, v63
	ds_write_b128 v2, v[78:81] offset:0
	v_lshlrev_b32_e32 v82, 16, v64
	v_and_b32_e32 v83, 0xffff0000, v64
	v_lshlrev_b32_e32 v84, 16, v65
	v_and_b32_e32 v85, 0xffff0000, v65
	ds_write_b128 v2, v[82:85] offset:16
	s_waitcnt vmcnt(0)
	v_lshlrev_b32_e32 v23, 16, v23
	s_nop 0
	ds_write_b32 v4, v23 offset:2048
	global_load_dwordx4 v[66:69], v5, s[94:95]
	global_load_ushort v33, v6, s[94:95]
	v_add_u32_e32 v5, 0x6800, v5
	v_add_u32_e32 v6, 0x10000, v6
	global_load_dwordx4 v[70:73], v5, s[94:95]
	global_load_ushort v35, v6, s[94:95]
	v_add_u32_e32 v5, 0x6800, v5
	v_add_u32_e32 v6, 0x10000, v6
	s_add_i32 m0, s29, 0x1200
	s_nop 0
	global_load_lds_dwordx4 v8, s[94:95]
	s_add_i32 m0, s29, 0x1600
	v_add_u32_e32 v8, 0x3180, v8
	global_load_lds_dwordx4 v88, s[94:95]
	v_add_u32_e32 v88, 0x3180, v88
	global_load_dwordx4 v[74:77], v5, s[94:95]
	global_load_ushort v36, v6, s[94:95]
	v_add_u32_e32 v5, 0x6800, v5
	v_add_u32_e32 v6, 0x10000, v6
	s_add_i32 m0, s29, 0x1a00
	s_nop 0
	global_load_lds_dwordx4 v8, s[94:95]
	s_add_i32 m0, s29, 0x1e00
	v_add_u32_e32 v8, 0x3180, v8
	global_load_lds_dwordx4 v88, s[94:95]
	v_add_u32_e32 v88, 0x3180, v88
	global_load_dwordx4 v[62:65], v5, s[94:95]
	global_load_ushort v23, v6, s[94:95]
	v_add_u32_e32 v5, 0x6800, v5
	v_add_u32_e32 v6, 0x10000, v6
	s_add_i32 m0, s29, 0x2200
	s_nop 0
	global_load_lds_dwordx4 v8, s[94:95]
	s_add_i32 m0, s29, 0x2600
	v_add_u32_e32 v8, 0x3180, v8
	global_load_lds_dwordx4 v88, s[94:95]
	v_add_u32_e32 v88, 0x3180, v88
	ds_read_b128 v[24:27], v0 offset:0
	ds_read_b128 v[28:31], v0 offset:16
	s_waitcnt vmcnt(8)
	ds_read_b128 v[46:49], v0 offset:4608
	ds_read_b128 v[50:53], v0 offset:4624
	ds_read_b32 v32, v1 offset:2048

.Lls2_8_noflush:
	s_waitcnt lgkmcnt(2)
	ds_read_b128 v[24:27], v0 offset:2304
	ds_read_b128 v[28:31], v0 offset:2320
	s_waitcnt vmcnt(8)
	ds_read_b128 v[46:49], v0 offset:6656
	ds_read_b128 v[50:53], v0 offset:6672
	ds_read_b32 v32, v1 offset:4352
	v_sub_f32_e32 v10, v10, v34
	v_sub_f32_e32 v11, v11, v34
	v_sub_f32_e32 v12, v12, v34
	v_sub_f32_e32 v13, v13, v34
	v_sub_f32_e32 v14, v14, v34
	v_sub_f32_e32 v15, v15, v34
	v_sub_f32_e32 v16, v16, v34
	v_sub_f32_e32 v17, v17, v34
	v_fma_f32 v10, v54, v10, v34
	v_fma_f32 v11, v55, v11, v34
	v_mul_f32_e32 v87, v38, v10
	v_fma_f32 v12, v56, v12, v34
	v_fmac_f32_e32 v87, v39, v11
	v_fma_f32 v13, v57, v13, v34
	v_fmac_f32_e32 v87, v40, v12
	v_fma_f32 v14, v58, v14, v34
	v_fmac_f32_e32 v87, v41, v13
	v_fma_f32 v15, v59, v15, v34
	v_fmac_f32_e32 v87, v42, v14
	v_fma_f32 v16, v60, v16, v34
	v_fmac_f32_e32 v87, v43, v15
	v_fma_f32 v17, v61, v17, v34
	v_fmac_f32_e32 v87, v44, v16
	v_fmac_f32_e32 v87, v45, v17
	ds_write_b32 v96, v87 offset:14592
	s_waitcnt lgkmcnt(1)
	ds_read_b128 v[38:41], v0 offset:2560
	ds_read_b128 v[42:45], v0 offset:2576
	ds_read_b128 v[54:57], v0 offset:6912
	ds_read_b128 v[58:61], v0 offset:6928
	ds_read_b32 v34, v1 offset:4384
	v_sub_f32_e32 v10, v10, v32
	v_sub_f32_e32 v11, v11, v32
	v_sub_f32_e32 v12, v12, v32
	s_waitcnt vmcnt(15)
	v_sub_f32_e32 v13, v13, v32
	v_sub_f32_e32 v14, v14, v32
	v_sub_f32_e32 v15, v15, v32
	v_lshlrev_b32_e32 v78, 16, v70
	v_sub_f32_e32 v16, v16, v32
	v_sub_f32_e32 v17, v17, v32
	v_fma_f32 v10, v46, v10, v32
	v_and_b32_e32 v79, 0xffff0000, v70
	v_fma_f32 v11, v47, v11, v32
	v_mul_f32_e32 v86, v24, v10
	v_fma_f32 v12, v48, v12, v32
	v_lshlrev_b32_e32 v80, 16, v71
	v_fmac_f32_e32 v86, v25, v11
	v_fma_f32 v13, v49, v13, v32
	v_fmac_f32_e32 v86, v26, v12
	v_fma_f32 v14, v50, v14, v32
	v_fmac_f32_e32 v86, v27, v13
	v_fma_f32 v15, v51, v15, v32
	v_fmac_f32_e32 v86, v28, v14
	v_fma_f32 v16, v52, v16, v32
	v_fmac_f32_e32 v86, v29, v15
	v_fma_f32 v17, v53, v17, v32
	v_fmac_f32_e32 v86, v30, v16
	v_fmac_f32_e32 v86, v31, v17
	ds_write_b32 v96, v86 offset:14848
	s_waitcnt lgkmcnt(1)
	ds_read_b128 v[24:27], v0 offset:2816
	ds_read_b128 v[28:31], v0 offset:2832
	ds_read_b128 v[46:49], v0 offset:7168
	ds_read_b128 v[50:53], v0 offset:7184
	ds_read_b32 v32, v1 offset:4416
	v_sub_f32_e32 v10, v10, v34
	v_sub_f32_e32 v11, v11, v34
	v_sub_f32_e32 v12, v12, v34
	v_and_b32_e32 v81, 0xffff0000, v71
	v_sub_f32_e32 v13, v13, v34
	v_sub_f32_e32 v14, v14, v34
	v_sub_f32_e32 v15, v15, v34
	ds_write_b128 v2, v[78:81] offset:0
	v_sub_f32_e32 v16, v16, v34
	v_sub_f32_e32 v17, v17, v34
	v_fma_f32 v10, v54, v10, v34
	v_lshlrev_b32_e32 v82, 16, v72
	v_fma_f32 v11, v55, v11, v34
	v_mul_f32_e32 v87, v38, v10
	v_fma_f32 v12, v56, v12, v34
	v_and_b32_e32 v83, 0xffff0000, v72
	v_fmac_f32_e32 v87, v39, v11
	v_fma_f32 v13, v57, v13, v34
	v_fmac_f32_e32 v87, v40, v12
	v_fma_f32 v14, v58, v14, v34
	v_fmac_f32_e32 v87, v41, v13
	v_fma_f32 v15, v59, v15, v34
	v_fmac_f32_e32 v87, v42, v14
	v_fma_f32 v16, v60, v16, v34
	v_fmac_f32_e32 v87, v43, v15
	v_fma_f32 v17, v61, v17, v34
	v_fmac_f32_e32 v87, v44, v16
	v_fmac_f32_e32 v87, v45, v17
	ds_write_b32 v96, v87 offset:15104
	s_waitcnt lgkmcnt(2)
	ds_read_b128 v[38:41], v0 offset:3072
	ds_read_b128 v[42:45], v0 offset:3088
	ds_read_b128 v[54:57], v0 offset:7424
	ds_read_b128 v[58:61], v0 offset:7440
	ds_read_b32 v34, v1 offset:4448
	v_sub_f32_e32 v10, v10, v32
	v_sub_f32_e32 v11, v11, v32
	v_sub_f32_e32 v12, v12, v32
	v_lshlrev_b32_e32 v84, 16, v73
	v_sub_f32_e32 v13, v13, v32
	v_sub_f32_e32 v14, v14, v32
	v_sub_f32_e32 v15, v15, v32
	v_and_b32_e32 v85, 0xffff0000, v73
	v_sub_f32_e32 v16, v16, v32
	v_sub_f32_e32 v17, v17, v32
	v_fma_f32 v10, v46, v10, v32
	ds_write_b128 v2, v[82:85] offset:16
	v_fma_f32 v11, v47, v11, v32
	v_mul_f32_e32 v86, v24, v10
	v_fma_f32 v12, v48, v12, v32
	s_waitcnt vmcnt(14)
	v_fmac_f32_e32 v86, v25, v11
	v_fma_f32 v13, v49, v13, v32
	v_fmac_f32_e32 v86, v26, v12
	v_fma_f32 v14, v50, v14, v32
	v_fmac_f32_e32 v86, v27, v13
	v_fma_f32 v15, v51, v15, v32
	v_fmac_f32_e32 v86, v28, v14
	v_fma_f32 v16, v52, v16, v32
	v_fmac_f32_e32 v86, v29, v15
	v_fma_f32 v17, v53, v17, v32
	v_fmac_f32_e32 v86, v30, v16
	v_fmac_f32_e32 v86, v31, v17
	ds_write_b32 v96, v86 offset:15360
	s_waitcnt lgkmcnt(2)
	ds_read_b128 v[24:27], v0 offset:3328
	ds_read_b128 v[28:31], v0 offset:3344
	ds_read_b128 v[46:49], v0 offset:7680
	ds_read_b128 v[50:53], v0 offset:7696
	ds_read_b32 v32, v1 offset:4480
	v_sub_f32_e32 v10, v10, v34
	v_sub_f32_e32 v11, v11, v34
	v_sub_f32_e32 v12, v12, v34
	v_lshlrev_b32_e32 v35, 16, v35
	v_sub_f32_e32 v13, v13, v34
	v_sub_f32_e32 v14, v14, v34
	v_sub_f32_e32 v15, v15, v34
	s_nop 0
	v_sub_f32_e32 v16, v16, v34
	v_sub_f32_e32 v17, v17, v34
	v_fma_f32 v10, v54, v10, v34
	ds_write_b32 v4, v35 offset:2048
	v_fma_f32 v11, v55, v11, v34
	v_mul_f32_e32 v87, v38, v10
	v_fma_f32 v12, v56, v12, v34
	v_fmac_f32_e32 v87, v39, v11
	v_fma_f32 v13, v57, v13, v34
	v_fmac_f32_e32 v87, v40, v12
	v_fma_f32 v14, v58, v14, v34
	v_fmac_f32_e32 v87, v41, v13
	v_fma_f32 v15, v59, v15, v34
	v_fmac_f32_e32 v87, v42, v14
	v_fma_f32 v16, v60, v16, v34
	v_fmac_f32_e32 v87, v43, v15
	v_fma_f32 v17, v61, v17, v34
	v_fmac_f32_e32 v87, v44, v16
	v_fmac_f32_e32 v87, v45, v17
	ds_write_b32 v96, v87 offset:15616
	s_waitcnt lgkmcnt(2)
	ds_read_b128 v[38:41], v0 offset:3584
	ds_read_b128 v[42:45], v0 offset:3600
	ds_read_b128 v[54:57], v0 offset:7936
	ds_read_b128 v[58:61], v0 offset:7952
	ds_read_b32 v34, v1 offset:4512
	v_sub_f32_e32 v10, v10, v32
	v_sub_f32_e32 v11, v11, v32
	v_sub_f32_e32 v12, v12, v32
	global_load_dwordx4 v[70:73], v5, s[94:95]
	global_load_ushort v35, v6, s[94:95]
	v_add_u32_e32 v5, 0x6800, v5
	v_add_u32_e32 v6, 0x10000, v6
	v_sub_f32_e32 v13, v13, v32
	v_sub_f32_e32 v14, v14, v32
	v_sub_f32_e32 v15, v15, v32
	s_add_i32 m0, s29, 0x1200
	s_nop 0
	global_load_lds_dwordx4 v8, s[94:95]
	s_add_i32 m0, s29, 0x1600
	v_add_u32_e32 v8, 0x3180, v8
	global_load_lds_dwordx4 v88, s[94:95]
	v_add_u32_e32 v88, 0x3180, v88
	v_sub_f32_e32 v16, v16, v32
	v_sub_f32_e32 v17, v17, v32
	v_fma_f32 v10, v46, v10, v32
	ds_read_b128 v[100:103], v97 offset:12800
	v_fma_f32 v11, v47, v11, v32
	v_mul_f32_e32 v86, v24, v10
	v_fma_f32 v12, v48, v12, v32
	ds_read_b128 v[104:107], v98 offset:12800
	v_fmac_f32_e32 v86, v25, v11
	v_fma_f32 v13, v49, v13, v32
	v_fmac_f32_e32 v86, v26, v12
	v_fma_f32 v14, v50, v14, v32
	v_fmac_f32_e32 v86, v27, v13
	v_fma_f32 v15, v51, v15, v32
	v_fmac_f32_e32 v86, v28, v14
	v_fma_f32 v16, v52, v16, v32
	v_fmac_f32_e32 v86, v29, v15
	v_fma_f32 v17, v53, v17, v32
	v_fmac_f32_e32 v86, v30, v16
	v_fmac_f32_e32 v86, v31, v17
	ds_write_b32 v96, v86 offset:15872
	s_waitcnt lgkmcnt(3)
	ds_read_b128 v[24:27], v0 offset:3840
	ds_read_b128 v[28:31], v0 offset:3856
	ds_read_b128 v[46:49], v0 offset:8192
	ds_read_b128 v[50:53], v0 offset:8208
	ds_read_b32 v32, v1 offset:4544
	v_sub_f32_e32 v10, v10, v34
	v_sub_f32_e32 v11, v11, v34
	v_sub_f32_e32 v12, v12, v34
	v_sub_f32_e32 v13, v13, v34
	v_sub_f32_e32 v14, v14, v34
	v_sub_f32_e32 v15, v15, v34
	v_sub_f32_e32 v16, v16, v34
	v_sub_f32_e32 v17, v17, v34
	v_fma_f32 v10, v54, v10, v34
	v_fma_f32 v11, v55, v11, v34
	v_mul_f32_e32 v87, v38, v10
	v_fma_f32 v12, v56, v12, v34
	v_fmac_f32_e32 v87, v39, v11
	v_fma_f32 v13, v57, v13, v34
	v_fmac_f32_e32 v87, v40, v12
	v_fma_f32 v14, v58, v14, v34
	v_fmac_f32_e32 v87, v41, v13
	v_fma_f32 v15, v59, v15, v34
	v_fmac_f32_e32 v87, v42, v14
	v_fma_f32 v16, v60, v16, v34
	v_fmac_f32_e32 v87, v43, v15
	v_fma_f32 v17, v61, v17, v34
	v_fmac_f32_e32 v87, v44, v16
	v_fmac_f32_e32 v87, v45, v17
	ds_write_b32 v96, v87 offset:16128
	s_waitcnt lgkmcnt(1)
	ds_read_b128 v[38:41], v0 offset:4096
	ds_read_b128 v[42:45], v0 offset:4112
	ds_read_b128 v[54:57], v0 offset:8448
	ds_read_b128 v[58:61], v0 offset:8464
	ds_read_b32 v34, v1 offset:4576
	v_sub_f32_e32 v10, v10, v32
	v_sub_f32_e32 v11, v11, v32
	v_sub_f32_e32 v12, v12, v32
	s_waitcnt lgkmcnt(12)
	v_sub_f32_e32 v13, v13, v32
	v_sub_f32_e32 v14, v14, v32
	v_sub_f32_e32 v15, v15, v32
	v_add_f32_e32 v100, v100, v104
	v_sub_f32_e32 v16, v16, v32
	v_sub_f32_e32 v17, v17, v32
	v_fma_f32 v10, v46, v10, v32
	v_add_f32_e32 v101, v101, v105
	v_fma_f32 v11, v47, v11, v32
	v_mul_f32_e32 v86, v24, v10
	v_fma_f32 v12, v48, v12, v32
	v_add_f32_e32 v102, v102, v106
	v_fmac_f32_e32 v86, v25, v11
	v_fma_f32 v13, v49, v13, v32
	v_fmac_f32_e32 v86, v26, v12
	v_add_f32_e32 v103, v103, v107
	v_fma_f32 v14, v50, v14, v32
	v_fmac_f32_e32 v86, v27, v13
	v_fma_f32 v15, v51, v15, v32
	v_add_f32_e32 v100, v100, v101
	v_fmac_f32_e32 v86, v28, v14
	v_fma_f32 v16, v52, v16, v32
	v_fmac_f32_e32 v86, v29, v15
	v_add_f32_e32 v102, v102, v103
	v_fma_f32 v17, v53, v17, v32
	v_fmac_f32_e32 v86, v30, v16
	v_fmac_f32_e32 v86, v31, v17
	v_add_f32_e32 v100, v100, v102
	ds_write_b32 v96, v86 offset:16384
	v_cvt_pk_bf16_f32 v22, v100, v100
	ds_write_b16 v90, v22 offset:17408
	s_waitcnt lgkmcnt(2)
	ds_read_b128 v[24:27], v0 offset:0
	ds_read_b128 v[28:31], v0 offset:16
	s_waitcnt vmcnt(8)
	ds_read_b128 v[46:49], v0 offset:8704
	ds_read_b128 v[50:53], v0 offset:8720
	ds_read_b32 v32, v1 offset:2048
	v_sub_f32_e32 v10, v10, v34
	v_sub_f32_e32 v11, v11, v34
	v_sub_f32_e32 v12, v12, v34
	v_sub_f32_e32 v13, v13, v34
	v_sub_f32_e32 v14, v14, v34
	v_sub_f32_e32 v15, v15, v34
	v_sub_f32_e32 v16, v16, v34
	v_sub_f32_e32 v17, v17, v34
	v_fma_f32 v10, v54, v10, v34
	v_fma_f32 v11, v55, v11, v34
	v_mul_f32_e32 v87, v38, v10
	v_fma_f32 v12, v56, v12, v34
	v_fmac_f32_e32 v87, v39, v11
	v_fma_f32 v13, v57, v13, v34
	v_fmac_f32_e32 v87, v40, v12
	v_fma_f32 v14, v58, v14, v34
	v_fmac_f32_e32 v87, v41, v13
	v_fma_f32 v15, v59, v15, v34
	v_fmac_f32_e32 v87, v42, v14
	v_fma_f32 v16, v60, v16, v34
	v_fmac_f32_e32 v87, v43, v15
	v_fma_f32 v17, v61, v17, v34
	v_fmac_f32_e32 v87, v44, v16
	v_fmac_f32_e32 v87, v45, v17
	ds_write_b32 v96, v87 offset:16640
	s_waitcnt lgkmcnt(1)
	ds_read_b128 v[38:41], v0 offset:256
	ds_read_b128 v[42:45], v0 offset:272
	ds_read_b128 v[54:57], v0 offset:8960
	ds_read_b128 v[58:61], v0 offset:8976
	ds_read_b32 v34, v1 offset:2080
	v_sub_f32_e32 v10, v10, v32
	v_sub_f32_e32 v11, v11, v32
	v_sub_f32_e32 v12, v12, v32
	s_waitcnt vmcnt(15)
	v_sub_f32_e32 v13, v13, v32
	v_sub_f32_e32 v14, v14, v32
	v_sub_f32_e32 v15, v15, v32
	v_lshlrev_b32_e32 v78, 16, v74
	v_sub_f32_e32 v16, v16, v32
	v_sub_f32_e32 v17, v17, v32
	v_fma_f32 v10, v46, v10, v32
	v_and_b32_e32 v79, 0xffff0000, v74
	v_fma_f32 v11, v47, v11, v32
	v_mul_f32_e32 v86, v24, v10
	v_fma_f32 v12, v48, v12, v32
	v_lshlrev_b32_e32 v80, 16, v75
	v_fmac_f32_e32 v86, v25, v11
	v_fma_f32 v13, v49, v13, v32
	v_fmac_f32_e32 v86, v26, v12
	v_fma_f32 v14, v50, v14, v32
	v_fmac_f32_e32 v86, v27, v13
	v_fma_f32 v15, v51, v15, v32
	v_fmac_f32_e32 v86, v28, v14
	v_fma_f32 v16, v52, v16, v32
	v_fmac_f32_e32 v86, v29, v15
	v_fma_f32 v17, v53, v17, v32
	v_fmac_f32_e32 v86, v30, v16
	v_fmac_f32_e32 v86, v31, v17
	ds_write_b32 v96, v86 offset:12800
	s_waitcnt lgkmcnt(1)
	ds_read_b128 v[24:27], v0 offset:512
	ds_read_b128 v[28:31], v0 offset:528
	ds_read_b128 v[46:49], v0 offset:9216
	ds_read_b128 v[50:53], v0 offset:9232
	ds_read_b32 v32, v1 offset:2112
	v_sub_f32_e32 v10, v10, v34
	v_sub_f32_e32 v11, v11, v34
	v_sub_f32_e32 v12, v12, v34
	v_and_b32_e32 v81, 0xffff0000, v75
	v_sub_f32_e32 v13, v13, v34
	v_sub_f32_e32 v14, v14, v34
	v_sub_f32_e32 v15, v15, v34
	ds_write_b128 v2, v[78:81] offset:2304
	v_sub_f32_e32 v16, v16, v34
	v_sub_f32_e32 v17, v17, v34
	v_fma_f32 v10, v54, v10, v34
	v_lshlrev_b32_e32 v82, 16, v76
	v_fma_f32 v11, v55, v11, v34
	v_mul_f32_e32 v87, v38, v10
	v_fma_f32 v12, v56, v12, v34
	v_and_b32_e32 v83, 0xffff0000, v76
	v_fmac_f32_e32 v87, v39, v11
	v_fma_f32 v13, v57, v13, v34
	v_fmac_f32_e32 v87, v40, v12
	v_fma_f32 v14, v58, v14, v34
	v_fmac_f32_e32 v87, v41, v13
	v_fma_f32 v15, v59, v15, v34
	v_fmac_f32_e32 v87, v42, v14
	v_fma_f32 v16, v60, v16, v34
	v_fmac_f32_e32 v87, v43, v15
	v_fma_f32 v17, v61, v17, v34
	v_fmac_f32_e32 v87, v44, v16
	v_fmac_f32_e32 v87, v45, v17
	ds_write_b32 v96, v87 offset:13056
	s_waitcnt lgkmcnt(2)
	ds_read_b128 v[38:41], v0 offset:768
	ds_read_b128 v[42:45], v0 offset:784
	ds_read_b128 v[54:57], v0 offset:9472
	ds_read_b128 v[58:61], v0 offset:9488
	ds_read_b32 v34, v1 offset:2144
	v_sub_f32_e32 v10, v10, v32
	v_sub_f32_e32 v11, v11, v32
	v_sub_f32_e32 v12, v12, v32
	v_lshlrev_b32_e32 v84, 16, v77
	v_sub_f32_e32 v13, v13, v32
	v_sub_f32_e32 v14, v14, v32
	v_sub_f32_e32 v15, v15, v32
	v_and_b32_e32 v85, 0xffff0000, v77
	v_sub_f32_e32 v16, v16, v32
	v_sub_f32_e32 v17, v17, v32
	v_fma_f32 v10, v46, v10, v32
	ds_write_b128 v2, v[82:85] offset:2320
	v_fma_f32 v11, v47, v11, v32
	v_mul_f32_e32 v86, v24, v10
	v_fma_f32 v12, v48, v12, v32
	s_waitcnt vmcnt(14)
	v_fmac_f32_e32 v86, v25, v11
	v_fma_f32 v13, v49, v13, v32
	v_fmac_f32_e32 v86, v26, v12
	v_fma_f32 v14, v50, v14, v32
	v_fmac_f32_e32 v86, v27, v13
	v_fma_f32 v15, v51, v15, v32
	v_fmac_f32_e32 v86, v28, v14
	v_fma_f32 v16, v52, v16, v32
	v_fmac_f32_e32 v86, v29, v15
	v_fma_f32 v17, v53, v17, v32
	v_fmac_f32_e32 v86, v30, v16
	v_fmac_f32_e32 v86, v31, v17
	ds_write_b32 v96, v86 offset:13312
	s_waitcnt lgkmcnt(2)
	ds_read_b128 v[24:27], v0 offset:1024
	ds_read_b128 v[28:31], v0 offset:1040
	ds_read_b128 v[46:49], v0 offset:9728
	ds_read_b128 v[50:53], v0 offset:9744
	ds_read_b32 v32, v1 offset:2176
	v_sub_f32_e32 v10, v10, v34
	v_sub_f32_e32 v11, v11, v34
	v_sub_f32_e32 v12, v12, v34
	v_lshlrev_b32_e32 v36, 16, v36
	v_sub_f32_e32 v13, v13, v34
	v_sub_f32_e32 v14, v14, v34
	v_sub_f32_e32 v15, v15, v34
	s_nop 0
	v_sub_f32_e32 v16, v16, v34
	v_sub_f32_e32 v17, v17, v34
	v_fma_f32 v10, v54, v10, v34
	ds_write_b32 v4, v36 offset:4352
	v_fma_f32 v11, v55, v11, v34
	v_mul_f32_e32 v87, v38, v10
	v_fma_f32 v12, v56, v12, v34
	v_fmac_f32_e32 v87, v39, v11
	v_fma_f32 v13, v57, v13, v34
	v_fmac_f32_e32 v87, v40, v12
	v_fma_f32 v14, v58, v14, v34
	v_fmac_f32_e32 v87, v41, v13
	v_fma_f32 v15, v59, v15, v34
	v_fmac_f32_e32 v87, v42, v14
	v_fma_f32 v16, v60, v16, v34
	v_fmac_f32_e32 v87, v43, v15
	v_fma_f32 v17, v61, v17, v34
	v_fmac_f32_e32 v87, v44, v16
	v_fmac_f32_e32 v87, v45, v17
	ds_write_b32 v96, v87 offset:13568
	s_waitcnt lgkmcnt(2)
	ds_read_b128 v[38:41], v0 offset:1280
	ds_read_b128 v[42:45], v0 offset:1296
	ds_read_b128 v[54:57], v0 offset:9984
	ds_read_b128 v[58:61], v0 offset:10000
	ds_read_b32 v34, v1 offset:2208
	v_sub_f32_e32 v10, v10, v32
	v_sub_f32_e32 v11, v11, v32
	v_sub_f32_e32 v12, v12, v32
	global_load_dwordx4 v[74:77], v5, s[94:95]
	global_load_ushort v36, v6, s[94:95]
	v_add_u32_e32 v5, 0x6800, v5
	v_add_u32_e32 v6, 0x10000, v6
	v_sub_f32_e32 v13, v13, v32
	v_sub_f32_e32 v14, v14, v32
	v_sub_f32_e32 v15, v15, v32
	s_add_i32 m0, s29, 0x1a00
	s_nop 0
	global_load_lds_dwordx4 v8, s[94:95]
	s_add_i32 m0, s29, 0x1e00
	v_add_u32_e32 v8, 0x3180, v8
	global_load_lds_dwordx4 v88, s[94:95]
	v_add_u32_e32 v88, 0x3180, v88
	v_sub_f32_e32 v16, v16, v32
	v_sub_f32_e32 v17, v17, v32
	v_fma_f32 v10, v46, v10, v32
	ds_read_b128 v[100:103], v97 offset:14848
	v_fma_f32 v11, v47, v11, v32
	v_mul_f32_e32 v86, v24, v10
	v_fma_f32 v12, v48, v12, v32
	ds_read_b128 v[104:107], v98 offset:14848
	v_fmac_f32_e32 v86, v25, v11
	v_fma_f32 v13, v49, v13, v32
	v_fmac_f32_e32 v86, v26, v12
	v_fma_f32 v14, v50, v14, v32
	v_fmac_f32_e32 v86, v27, v13
	v_fma_f32 v15, v51, v15, v32
	v_fmac_f32_e32 v86, v28, v14
	v_fma_f32 v16, v52, v16, v32
	v_fmac_f32_e32 v86, v29, v15
	v_fma_f32 v17, v53, v17, v32
	v_fmac_f32_e32 v86, v30, v16
	v_fmac_f32_e32 v86, v31, v17
	ds_write_b32 v96, v86 offset:13824
	s_waitcnt lgkmcnt(3)
	ds_read_b128 v[24:27], v0 offset:1536
	ds_read_b128 v[28:31], v0 offset:1552
	ds_read_b128 v[46:49], v0 offset:10240
	ds_read_b128 v[50:53], v0 offset:10256
	ds_read_b32 v32, v1 offset:2240
	v_sub_f32_e32 v10, v10, v34
	v_sub_f32_e32 v11, v11, v34
	v_sub_f32_e32 v12, v12, v34
	v_sub_f32_e32 v13, v13, v34
	v_sub_f32_e32 v14, v14, v34
	v_sub_f32_e32 v15, v15, v34
	v_sub_f32_e32 v16, v16, v34
	v_sub_f32_e32 v17, v17, v34
	v_fma_f32 v10, v54, v10, v34
	v_fma_f32 v11, v55, v11, v34
	v_mul_f32_e32 v87, v38, v10
	v_fma_f32 v12, v56, v12, v34
	v_fmac_f32_e32 v87, v39, v11
	v_fma_f32 v13, v57, v13, v34
	v_fmac_f32_e32 v87, v40, v12
	v_fma_f32 v14, v58, v14, v34
	v_fmac_f32_e32 v87, v41, v13
	v_fma_f32 v15, v59, v15, v34
	v_fmac_f32_e32 v87, v42, v14
	v_fma_f32 v16, v60, v16, v34
	v_fmac_f32_e32 v87, v43, v15
	v_fma_f32 v17, v61, v17, v34
	v_fmac_f32_e32 v87, v44, v16
	v_fmac_f32_e32 v87, v45, v17
	ds_write_b32 v96, v87 offset:14080
	s_waitcnt lgkmcnt(1)
	ds_read_b128 v[38:41], v0 offset:1792
	ds_read_b128 v[42:45], v0 offset:1808
	ds_read_b128 v[54:57], v0 offset:10496
	ds_read_b128 v[58:61], v0 offset:10512
	ds_read_b32 v34, v1 offset:2272
	v_sub_f32_e32 v10, v10, v32
	v_sub_f32_e32 v11, v11, v32
	v_sub_f32_e32 v12, v12, v32
	s_waitcnt lgkmcnt(12)
	v_sub_f32_e32 v13, v13, v32
	v_sub_f32_e32 v14, v14, v32
	v_sub_f32_e32 v15, v15, v32
	v_add_f32_e32 v100, v100, v104
	v_sub_f32_e32 v16, v16, v32
	v_sub_f32_e32 v17, v17, v32
	v_fma_f32 v10, v46, v10, v32
	v_add_f32_e32 v101, v101, v105
	v_fma_f32 v11, v47, v11, v32
	v_mul_f32_e32 v86, v24, v10
	v_fma_f32 v12, v48, v12, v32
	v_add_f32_e32 v102, v102, v106
	v_fmac_f32_e32 v86, v25, v11
	v_fma_f32 v13, v49, v13, v32
	v_fmac_f32_e32 v86, v26, v12
	v_add_f32_e32 v103, v103, v107
	v_fma_f32 v14, v50, v14, v32
	v_fmac_f32_e32 v86, v27, v13
	v_fma_f32 v15, v51, v15, v32
	v_add_f32_e32 v100, v100, v101
	v_fmac_f32_e32 v86, v28, v14
	v_fma_f32 v16, v52, v16, v32
	v_fmac_f32_e32 v86, v29, v15
	v_add_f32_e32 v102, v102, v103
	v_fma_f32 v17, v53, v17, v32
	v_fmac_f32_e32 v86, v30, v16
	v_fmac_f32_e32 v86, v31, v17
	v_add_f32_e32 v100, v100, v102
	ds_write_b32 v96, v86 offset:14336
	v_cvt_pk_bf16_f32 v22, v100, v100
	ds_write_b16 v90, v22 offset:17536
	s_waitcnt lgkmcnt(2)
	ds_read_b128 v[24:27], v0 offset:2304
	ds_read_b128 v[28:31], v0 offset:2320
	s_waitcnt vmcnt(8)
	ds_read_b128 v[46:49], v0 offset:10752
	ds_read_b128 v[50:53], v0 offset:10768
	ds_read_b32 v32, v1 offset:4352
	v_sub_f32_e32 v10, v10, v34
	v_sub_f32_e32 v11, v11, v34
	v_sub_f32_e32 v12, v12, v34
	v_sub_f32_e32 v13, v13, v34
	v_sub_f32_e32 v14, v14, v34
	v_sub_f32_e32 v15, v15, v34
	v_sub_f32_e32 v16, v16, v34
	v_sub_f32_e32 v17, v17, v34
	v_fma_f32 v10, v54, v10, v34
	v_fma_f32 v11, v55, v11, v34
	v_mul_f32_e32 v87, v38, v10
	v_fma_f32 v12, v56, v12, v34
	v_fmac_f32_e32 v87, v39, v11
	v_fma_f32 v13, v57, v13, v34
	v_fmac_f32_e32 v87, v40, v12
	v_fma_f32 v14, v58, v14, v34
	v_fmac_f32_e32 v87, v41, v13
	v_fma_f32 v15, v59, v15, v34
	v_fmac_f32_e32 v87, v42, v14
	v_fma_f32 v16, v60, v16, v34
	v_fmac_f32_e32 v87, v43, v15
	v_fma_f32 v17, v61, v17, v34
	v_fmac_f32_e32 v87, v44, v16
	v_fmac_f32_e32 v87, v45, v17
	ds_write_b32 v96, v87 offset:14592
	s_waitcnt lgkmcnt(1)
	ds_read_b128 v[38:41], v0 offset:2560
	ds_read_b128 v[42:45], v0 offset:2576
	ds_read_b128 v[54:57], v0 offset:11008
	ds_read_b128 v[58:61], v0 offset:11024
	ds_read_b32 v34, v1 offset:4384
	v_sub_f32_e32 v10, v10, v32
	v_sub_f32_e32 v11, v11, v32
	v_sub_f32_e32 v12, v12, v32
	s_waitcnt vmcnt(15)
	v_sub_f32_e32 v13, v13, v32
	v_sub_f32_e32 v14, v14, v32
	v_sub_f32_e32 v15, v15, v32
	v_lshlrev_b32_e32 v78, 16, v62
	v_sub_f32_e32 v16, v16, v32
	v_sub_f32_e32 v17, v17, v32
	v_fma_f32 v10, v46, v10, v32
	v_and_b32_e32 v79, 0xffff0000, v62
	v_fma_f32 v11, v47, v11, v32
	v_mul_f32_e32 v86, v24, v10
	v_fma_f32 v12, v48, v12, v32
	v_lshlrev_b32_e32 v80, 16, v63
	v_fmac_f32_e32 v86, v25, v11
	v_fma_f32 v13, v49, v13, v32
	v_fmac_f32_e32 v86, v26, v12
	v_fma_f32 v14, v50, v14, v32
	v_fmac_f32_e32 v86, v27, v13
	v_fma_f32 v15, v51, v15, v32
	v_fmac_f32_e32 v86, v28, v14
	v_fma_f32 v16, v52, v16, v32
	v_fmac_f32_e32 v86, v29, v15
	v_fma_f32 v17, v53, v17, v32
	v_fmac_f32_e32 v86, v30, v16
	v_fmac_f32_e32 v86, v31, v17
	ds_write_b32 v96, v86 offset:14848
	s_waitcnt lgkmcnt(1)
	ds_read_b128 v[24:27], v0 offset:2816
	ds_read_b128 v[28:31], v0 offset:2832
	ds_read_b128 v[46:49], v0 offset:11264
	ds_read_b128 v[50:53], v0 offset:11280
	ds_read_b32 v32, v1 offset:4416
	v_sub_f32_e32 v10, v10, v34
	v_sub_f32_e32 v11, v11, v34
	v_sub_f32_e32 v12, v12, v34
	v_and_b32_e32 v81, 0xffff0000, v63
	v_sub_f32_e32 v13, v13, v34
	v_sub_f32_e32 v14, v14, v34
	v_sub_f32_e32 v15, v15, v34
	ds_write_b128 v2, v[78:81] offset:0
	v_sub_f32_e32 v16, v16, v34
	v_sub_f32_e32 v17, v17, v34
	v_fma_f32 v10, v54, v10, v34
	v_lshlrev_b32_e32 v82, 16, v64
	v_fma_f32 v11, v55, v11, v34
	v_mul_f32_e32 v87, v38, v10
	v_fma_f32 v12, v56, v12, v34
	v_and_b32_e32 v83, 0xffff0000, v64
	v_fmac_f32_e32 v87, v39, v11
	v_fma_f32 v13, v57, v13, v34
	v_fmac_f32_e32 v87, v40, v12
	v_fma_f32 v14, v58, v14, v34
	v_fmac_f32_e32 v87, v41, v13
	v_fma_f32 v15, v59, v15, v34
	v_fmac_f32_e32 v87, v42, v14
	v_fma_f32 v16, v60, v16, v34
	v_fmac_f32_e32 v87, v43, v15
	v_fma_f32 v17, v61, v17, v34
	v_fmac_f32_e32 v87, v44, v16
	v_fmac_f32_e32 v87, v45, v17
	ds_write_b32 v96, v87 offset:15104
	s_waitcnt lgkmcnt(2)
	ds_read_b128 v[38:41], v0 offset:3072
	ds_read_b128 v[42:45], v0 offset:3088
	ds_read_b128 v[54:57], v0 offset:11520
	ds_read_b128 v[58:61], v0 offset:11536
	ds_read_b32 v34, v1 offset:4448
	v_sub_f32_e32 v10, v10, v32
	v_sub_f32_e32 v11, v11, v32
	v_sub_f32_e32 v12, v12, v32
	v_lshlrev_b32_e32 v84, 16, v65
	v_sub_f32_e32 v13, v13, v32
	v_sub_f32_e32 v14, v14, v32
	v_sub_f32_e32 v15, v15, v32
	v_and_b32_e32 v85, 0xffff0000, v65
	v_sub_f32_e32 v16, v16, v32
	v_sub_f32_e32 v17, v17, v32
	v_fma_f32 v10, v46, v10, v32
	ds_write_b128 v2, v[82:85] offset:16
	v_fma_f32 v11, v47, v11, v32
	v_mul_f32_e32 v86, v24, v10
	v_fma_f32 v12, v48, v12, v32
	s_waitcnt vmcnt(14)
	v_fmac_f32_e32 v86, v25, v11
	v_fma_f32 v13, v49, v13, v32
	v_fmac_f32_e32 v86, v26, v12
	v_fma_f32 v14, v50, v14, v32
	v_fmac_f32_e32 v86, v27, v13
	v_fma_f32 v15, v51, v15, v32
	v_fmac_f32_e32 v86, v28, v14
	v_fma_f32 v16, v52, v16, v32
	v_fmac_f32_e32 v86, v29, v15
	v_fma_f32 v17, v53, v17, v32
	v_fmac_f32_e32 v86, v30, v16
	v_fmac_f32_e32 v86, v31, v17
	ds_write_b32 v96, v86 offset:15360
	s_waitcnt lgkmcnt(2)
	ds_read_b128 v[24:27], v0 offset:3328
	ds_read_b128 v[28:31], v0 offset:3344
	ds_read_b128 v[46:49], v0 offset:11776
	ds_read_b128 v[50:53], v0 offset:11792
	ds_read_b32 v32, v1 offset:4480
	v_sub_f32_e32 v10, v10, v34
	v_sub_f32_e32 v11, v11, v34
	v_sub_f32_e32 v12, v12, v34
	v_lshlrev_b32_e32 v23, 16, v23
	v_sub_f32_e32 v13, v13, v34
	v_sub_f32_e32 v14, v14, v34
	v_sub_f32_e32 v15, v15, v34
	s_nop 0
	v_sub_f32_e32 v16, v16, v34
	v_sub_f32_e32 v17, v17, v34
	v_fma_f32 v10, v54, v10, v34
	ds_write_b32 v4, v23 offset:2048
	v_fma_f32 v11, v55, v11, v34
	v_mul_f32_e32 v87, v38, v10
	v_fma_f32 v12, v56, v12, v34
	v_fmac_f32_e32 v87, v39, v11
	v_fma_f32 v13, v57, v13, v34
	v_fmac_f32_e32 v87, v40, v12
	v_fma_f32 v14, v58, v14, v34
	v_fmac_f32_e32 v87, v41, v13
	v_fma_f32 v15, v59, v15, v34
	v_fmac_f32_e32 v87, v42, v14
	v_fma_f32 v16, v60, v16, v34
	v_fmac_f32_e32 v87, v43, v15
	v_fma_f32 v17, v61, v17, v34
	v_fmac_f32_e32 v87, v44, v16
	v_fmac_f32_e32 v87, v45, v17
	ds_write_b32 v96, v87 offset:15616
	s_waitcnt lgkmcnt(2)
	ds_read_b128 v[38:41], v0 offset:3584
	ds_read_b128 v[42:45], v0 offset:3600
	ds_read_b128 v[54:57], v0 offset:12032
	ds_read_b128 v[58:61], v0 offset:12048
	ds_read_b32 v34, v1 offset:4512
	v_sub_f32_e32 v10, v10, v32
	v_sub_f32_e32 v11, v11, v32
	v_sub_f32_e32 v12, v12, v32
	global_load_dwordx4 v[62:65], v5, s[94:95]
	global_load_ushort v23, v6, s[94:95]
	v_add_u32_e32 v5, 0x6800, v5
	v_add_u32_e32 v6, 0x10000, v6
	v_sub_f32_e32 v13, v13, v32
	v_sub_f32_e32 v14, v14, v32
	v_sub_f32_e32 v15, v15, v32
	s_add_i32 m0, s29, 0x2200
	s_nop 0
	global_load_lds_dwordx4 v8, s[94:95]
	s_add_i32 m0, s29, 0x2600
	v_add_u32_e32 v8, 0x3180, v8
	global_load_lds_dwordx4 v88, s[94:95]
	v_add_u32_e32 v88, 0x3180, v88
	v_sub_f32_e32 v16, v16, v32
	v_sub_f32_e32 v17, v17, v32
	v_fma_f32 v10, v46, v10, v32
	ds_read_b128 v[100:103], v97 offset:12800
	v_fma_f32 v11, v47, v11, v32
	v_mul_f32_e32 v86, v24, v10
	v_fma_f32 v12, v48, v12, v32
	ds_read_b128 v[104:107], v98 offset:12800
	v_fmac_f32_e32 v86, v25, v11
	v_fma_f32 v13, v49, v13, v32
	v_fmac_f32_e32 v86, v26, v12
	v_fma_f32 v14, v50, v14, v32
	v_fmac_f32_e32 v86, v27, v13
	v_fma_f32 v15, v51, v15, v32
	v_fmac_f32_e32 v86, v28, v14
	v_fma_f32 v16, v52, v16, v32
	v_fmac_f32_e32 v86, v29, v15
	v_fma_f32 v17, v53, v17, v32
	v_fmac_f32_e32 v86, v30, v16
	v_fmac_f32_e32 v86, v31, v17
	ds_write_b32 v96, v86 offset:15872
	s_waitcnt lgkmcnt(3)
	ds_read_b128 v[24:27], v0 offset:3840
	ds_read_b128 v[28:31], v0 offset:3856
	ds_read_b128 v[46:49], v0 offset:12288
	ds_read_b128 v[50:53], v0 offset:12304
	ds_read_b32 v32, v1 offset:4544
	v_sub_f32_e32 v10, v10, v34
	v_sub_f32_e32 v11, v11, v34
	v_sub_f32_e32 v12, v12, v34
	v_sub_f32_e32 v13, v13, v34
	v_sub_f32_e32 v14, v14, v34
	v_sub_f32_e32 v15, v15, v34
	v_sub_f32_e32 v16, v16, v34
	v_sub_f32_e32 v17, v17, v34
	v_fma_f32 v10, v54, v10, v34
	v_fma_f32 v11, v55, v11, v34
	v_mul_f32_e32 v87, v38, v10
	v_fma_f32 v12, v56, v12, v34
	v_fmac_f32_e32 v87, v39, v11
	v_fma_f32 v13, v57, v13, v34
	v_fmac_f32_e32 v87, v40, v12
	v_fma_f32 v14, v58, v14, v34
	v_fmac_f32_e32 v87, v41, v13
	v_fma_f32 v15, v59, v15, v34
	v_fmac_f32_e32 v87, v42, v14
	v_fma_f32 v16, v60, v16, v34
	v_fmac_f32_e32 v87, v43, v15
	v_fma_f32 v17, v61, v17, v34
	v_fmac_f32_e32 v87, v44, v16
	v_fmac_f32_e32 v87, v45, v17
	ds_write_b32 v96, v87 offset:16128
	s_waitcnt lgkmcnt(1)
	ds_read_b128 v[38:41], v0 offset:4096
	ds_read_b128 v[42:45], v0 offset:4112
	ds_read_b128 v[54:57], v0 offset:12544
	ds_read_b128 v[58:61], v0 offset:12560
	ds_read_b32 v34, v1 offset:4576
	v_sub_f32_e32 v10, v10, v32
	v_sub_f32_e32 v11, v11, v32
	v_sub_f32_e32 v12, v12, v32
	s_waitcnt lgkmcnt(12)
	v_sub_f32_e32 v13, v13, v32
	v_sub_f32_e32 v14, v14, v32
	v_sub_f32_e32 v15, v15, v32
	v_add_f32_e32 v100, v100, v104
	v_sub_f32_e32 v16, v16, v32
	v_sub_f32_e32 v17, v17, v32
	v_fma_f32 v10, v46, v10, v32
	v_add_f32_e32 v101, v101, v105
	v_fma_f32 v11, v47, v11, v32
	v_mul_f32_e32 v86, v24, v10
	v_fma_f32 v12, v48, v12, v32
	v_add_f32_e32 v102, v102, v106
	v_fmac_f32_e32 v86, v25, v11
	v_fma_f32 v13, v49, v13, v32
	v_fmac_f32_e32 v86, v26, v12
	v_add_f32_e32 v103, v103, v107
	v_fma_f32 v14, v50, v14, v32
	v_fmac_f32_e32 v86, v27, v13
	v_fma_f32 v15, v51, v15, v32
	v_add_f32_e32 v100, v100, v101
	v_fmac_f32_e32 v86, v28, v14
	v_fma_f32 v16, v52, v16, v32
	v_fmac_f32_e32 v86, v29, v15
	v_add_f32_e32 v102, v102, v103
	v_fma_f32 v17, v53, v17, v32
	v_fmac_f32_e32 v86, v30, v16
	v_fmac_f32_e32 v86, v31, v17
	v_add_f32_e32 v100, v100, v102
	ds_write_b32 v96, v86 offset:16384
	v_cvt_pk_bf16_f32 v22, v100, v100
	ds_write_b16 v90, v22 offset:17664
	s_waitcnt lgkmcnt(2)
	ds_read_b128 v[24:27], v0 offset:0
	ds_read_b128 v[28:31], v0 offset:16
	s_waitcnt vmcnt(8)
	ds_read_b128 v[46:49], v0 offset:4608
	ds_read_b128 v[50:53], v0 offset:4624
	ds_read_b32 v32, v1 offset:2048
	v_sub_f32_e32 v10, v10, v34
	v_sub_f32_e32 v11, v11, v34
	v_sub_f32_e32 v12, v12, v34
	v_sub_f32_e32 v13, v13, v34
	v_sub_f32_e32 v14, v14, v34
	v_sub_f32_e32 v15, v15, v34
	v_sub_f32_e32 v16, v16, v34
	v_sub_f32_e32 v17, v17, v34
	v_fma_f32 v10, v54, v10, v34
	v_fma_f32 v11, v55, v11, v34
	v_mul_f32_e32 v87, v38, v10
	v_fma_f32 v12, v56, v12, v34
	v_fmac_f32_e32 v87, v39, v11
	v_fma_f32 v13, v57, v13, v34
	v_fmac_f32_e32 v87, v40, v12
	v_fma_f32 v14, v58, v14, v34
	v_fmac_f32_e32 v87, v41, v13
	v_fma_f32 v15, v59, v15, v34
	v_fmac_f32_e32 v87, v42, v14
	v_fma_f32 v16, v60, v16, v34
	v_fmac_f32_e32 v87, v43, v15
	v_fma_f32 v17, v61, v17, v34
	v_fmac_f32_e32 v87, v44, v16
	v_fmac_f32_e32 v87, v45, v17
	ds_write_b32 v96, v87 offset:16640
	s_sub_u32 s12, s12, 1
	s_cmp_lg_u32 s12, 0
	s_cbranch_scc1 .Lls2_8_loop
	ds_read_b128 v[100:103], v97 offset:14848
	ds_read_b128 v[104:107], v98 offset:14848
	s_waitcnt lgkmcnt(0)
	v_add_f32_e32 v100, v100, v104
	v_add_f32_e32 v101, v101, v105
	v_add_f32_e32 v102, v102, v106
	v_add_f32_e32 v103, v103, v107
	v_add_f32_e32 v100, v100, v101
	v_add_f32_e32 v102, v102, v103
	v_add_f32_e32 v100, v100, v102
	v_cvt_pk_bf16_f32 v22, v100, v100
	ds_write_b16 v90, v22 offset:17792
	s_waitcnt lgkmcnt(0)
	ds_read_b128 v[92:95], v91 offset:17408
	s_waitcnt lgkmcnt(0)
	global_store_dwordx4 v7, v[92:95], s[94:95]
	v_add_u32_e32 v7, 0x20000, v7
	s_nop 0
	ds_read_b128 v[92:95], v91 offset:18432
	s_waitcnt lgkmcnt(0)
	global_store_dwordx4 v7, v[92:95], s[94:95]
	v_add_u32_e32 v7, 0x20000, v7
	s_nop 0
	ds_read_b128 v[92:95], v91 offset:19456
	s_waitcnt lgkmcnt(0)
	global_store_dwordx4 v7, v[92:95], s[94:95]
	v_add_u32_e32 v7, 0x20000, v7
	s_nop 0
	ds_read_b128 v[92:95], v91 offset:20480
	s_waitcnt lgkmcnt(0)
	global_store_dwordx4 v7, v[92:95], s[94:95]
	v_add_u32_e32 v7, 0x20000, v7
	s_nop 0
	global_store_dword v89, v10, s[26:27] offset:0
	global_store_dword v89, v11, s[26:27] offset:256
	global_store_dword v89, v12, s[26:27] offset:512
	global_store_dword v89, v13, s[26:27] offset:768
	global_store_dword v89, v14, s[26:27] offset:1024
	global_store_dword v89, v15, s[26:27] offset:1280
	global_store_dword v89, v16, s[26:27] offset:1536
	global_store_dword v89, v17, s[26:27] offset:1792
	s_waitcnt vmcnt(0) lgkmcnt(0)
	s_branch .Lls_done
.Lls1_8_entry:
	v_and_b32_e32 v98, 63, v196
	v_and_b32_e32 v99, 7, v98
	v_lshrrev_b32_e32 v100, 3, v98
	s_min_u32 s29, s0, 4
	s_mul_i32 s29, s29, 0x5600
	v_and_b32_e32 v101, 3, v99
	v_cmp_eq_u32_e64 s[6:7], 1, v101
	v_cmp_eq_u32_e64 s[8:9], 2, v101
	v_cmp_eq_u32_e64 s[10:11], 3, v101
	v_lshl_add_u32 v0, v99, 4, s29
	v_lshl_add_u32 v1, v100, 2, s29
	s_lshl_b32 s37, s16, 11
	v_lshrrev_b32_e32 v99, 3, v98
	v_and_b32_e32 v100, 7, v98
	v_add_u32_e32 v101, s37, v99
	s_lshl_b32 s21, s17, 7
	s_add_u32 s21, s21, 0x13e00000
	v_mul_u32_u24_e32 v8, 0x630, v101
	v_lshl_add_u32 v8, v100, 4, v8
	v_add_u32_e32 v8, s21, v8
	v_lshlrev_b32_e32 v103, 7, v99
	v_lshl_add_u32 v103, v100, 4, v103
	v_add_u32_e32 v103, s29, v103
	v_and_b32_e32 v99, 31, v98
	v_lshrrev_b32_e32 v100, 2, v99
	v_and_b32_e32 v99, 3, v99
	v_add_u32_e32 v101, s37, v100
	v_cmp_gt_u32_e32 vcc, 32, v98
	s_lshl_b32 s21, s17, 6
	s_add_u32 s22, s21, 0x10800400
	s_add_u32 s44, s21, 0x8400900
	v_mov_b32_e32 v9, 0x2000
	v_mov_b32_e32 v18, 0xd00
	v_cndmask_b32_e32 v9, v9, v18, vcc
	v_mov_b32_e32 v5, s44
	v_mov_b32_e32 v18, s22
	v_cndmask_b32_e32 v5, v5, v18, vcc
	v_mul_lo_u32 v18, v101, v9
	v_add_u32_e32 v5, v5, v18
	v_lshl_add_u32 v5, v99, 4, v5
	v_lshlrev_b32_e32 v9, 3, v9
	v_mov_b32_e32 v2, 0
	v_mov_b32_e32 v18, 1024
	v_cndmask_b32_e32 v2, v2, v18, vcc
	v_lshl_add_u32 v2, v100, 7, v2
	v_lshl_add_u32 v2, v99, 5, v2
	v_add_u32_e32 v2, s29, v2
	v_lshrrev_b32_e32 v100, 3, v98
	v_and_b32_e32 v99, 7, v98
	v_add_u32_e32 v101, s37, v100
	s_lshl_b32 s22, s14, 3
	s_lshl_b32 s21, s17, 6
	s_add_u32 s21, s21, s22
	s_lshl_b32 s44, s21, 1
	s_add_u32 s44, s44, 0x8400a00
	v_lshlrev_b32_e32 v6, 13, v101
	v_lshlrev_b32_e32 v4, 5, v100
	v_lshl_add_u32 v4, v99, 2, v4
	v_lshl_add_u32 v6, v99, 1, v6
	v_add_u32_e32 v6, s44, v6
	v_add_u32_e32 v4, s29, v4
	v_and_b32_e32 v99, 7, v98
	v_lshrrev_b32_e32 v100, 3, v98
	v_add_u32_e32 v101, s37, v98
	v_lshlrev_b32_e32 v7, 11, v101
	s_lshl_b32 s44, s21, 1
	s_add_u32 s44, s44, 0x6300200
	v_add_u32_e32 v7, s44, v7
	s_lshl_b32 s44, s28, 3
	s_add_u32 s44, s44, s16
	s_lshl_b32 s44, s44, 2
	s_add_u32 s44, s44, s17
	s_mul_i32 s44, s44, 0x2000
	s_add_u32 s44, s44, 0x4300000
	s_lshl_b32 s24, s22, 2
	s_add_u32 s44, s44, s24
	v_lshlrev_b32_e32 v104, 10, v99
	v_lshl_add_u32 v104, v100, 2, v104
	v_add_u32_e32 v104, s44, v104
	v_readlane_b32 s26, v253, 29
	v_readlane_b32 s27, v253, 30
	v_lshlrev_b32_e32 v105, 4, v99
	v_lshl_add_u32 v105, v100, 1, v105
	v_add_u32_e32 v105, s29, v105
	v_lshl_add_u32 v106, v98, 4, s29
	v_lshl_add_u32 v107, v98, 2, s29
	v_lshl_add_u32 v105, v98, 1, s29
	v_subrev_u32_e32 v105, 0x200, v105
	v_lshrrev_b32_e32 v99, 3, v98
	v_and_b32_e32 v100, 7, v98
	v_lshlrev_b32_e32 v101, 8, v99
	v_lshl_add_u32 v101, v100, 5, v101
	v_add_u32_e32 v101, s29, v101
	v_bfe_u32 v99, v99, 1, 1
	v_xor_b32_e32 v100, 0, v99
	v_lshl_add_u32 v112, v100, 4, v101
	v_xor_b32_e32 v100, 1, v99
	v_lshl_add_u32 v113, v100, 4, v101
	v_mov_b32_e32 v10, 0
	v_mov_b32_e32 v11, 0
	v_mov_b32_e32 v12, 0
	v_mov_b32_e32 v13, 0
	v_mov_b32_e32 v14, 0
	v_mov_b32_e32 v15, 0
	v_mov_b32_e32 v16, 0
	v_mov_b32_e32 v17, 0
	v_mov_b32_e32 v61, 0
	v_mov_b32_e32 v102, 0
	s_movk_i32 s12, 64
	s_nop 0
	global_load_dwordx4 v[78:81], v5, s[94:95]
	global_load_ushort v36, v6, s[94:95]
	v_add_u32_e32 v5, v5, v9
	v_add_u32_e32 v6, 0x10000, v6
	s_waitcnt vmcnt(0)
	s_waitcnt vmcnt(1)
	v_lshlrev_b32_e32 v94, 16, v78
	v_and_b32_e32 v95, 0xffff0000, v78
	v_lshlrev_b32_e32 v96, 16, v79
	v_and_b32_e32 v97, 0xffff0000, v79
	ds_write_b128 v2, v[94:97] offset:0
	v_lshlrev_b32_e32 v98, 16, v80
	v_and_b32_e32 v99, 0xffff0000, v80
	v_lshlrev_b32_e32 v100, 16, v81
	v_and_b32_e32 v101, 0xffff0000, v81
	ds_write_b128 v2, v[98:101] offset:16
	s_waitcnt vmcnt(0)
	v_lshlrev_b32_e32 v36, 16, v36
	s_nop 0
	ds_write_b32 v4, v36 offset:2048
	global_load_dwordx4 v[82:85], v5, s[94:95]
	global_load_ushort v55, v6, s[94:95]
	v_add_u32_e32 v5, v5, v9
	v_add_u32_e32 v6, 0x10000, v6
	global_load_dwordx4 v[86:89], v5, s[94:95]
	global_load_ushort v57, v6, s[94:95]
	v_add_u32_e32 v5, v5, v9
	v_add_u32_e32 v6, 0x10000, v6
	s_add_i32 m0, s29, 0x1200
	s_nop 0
	global_load_lds_dwordx4 v8, s[94:95]
	v_add_u32_e32 v8, 0x3180, v8
	global_load_dwordx4 v[90:93], v5, s[94:95]
	global_load_ushort v59, v6, s[94:95]
	v_add_u32_e32 v5, v5, v9
	v_add_u32_e32 v6, 0x10000, v6
	s_add_i32 m0, s29, 0x1600
	s_nop 0
	global_load_lds_dwordx4 v8, s[94:95]
	v_add_u32_e32 v8, 0x3180, v8
	global_load_dwordx4 v[78:81], v5, s[94:95]
	global_load_ushort v36, v6, s[94:95]
	v_add_u32_e32 v5, v5, v9
	v_add_u32_e32 v6, 0x10000, v6
	s_add_i32 m0, s29, 0x1a00
	s_nop 0
	global_load_lds_dwordx4 v8, s[94:95]
	v_add_u32_e32 v8, 0x3180, v8
	ds_read_b128 v[20:23], v0 offset:0
	ds_read_b128 v[38:41], v0 offset:1024
	s_waitcnt vmcnt(6)
	ds_read_b128 v[62:65], v0 offset:4608
	ds_read_b32 v54, v1 offset:2048
	ds_read_b128 v[24:27], v0 offset:128
	ds_read_b128 v[42:45], v0 offset:1152
	ds_read_b128 v[66:69], v0 offset:4736
	ds_read_b32 v56, v1 offset:2080
	ds_read_b128 v[28:31], v0 offset:256
	ds_read_b128 v[46:49], v0 offset:1280
	ds_read_b128 v[70:73], v0 offset:4864
	ds_read_b32 v58, v1 offset:2112

.Lls1_8_noflush:
	s_waitcnt lgkmcnt(11)
	v_mul_f32_e32 v10, v74, v10
	v_mul_f32_e32 v11, v75, v11
	v_mul_f32_e32 v12, v76, v12
	ds_read_b128 v[28:31], v0 offset:2560
	v_mul_f32_e32 v13, v77, v13
	v_fmac_f32_e32 v10, v32, v60
	v_fmac_f32_e32 v11, v33, v60
	ds_read_b128 v[46:49], v0 offset:3584
	v_mul_f32_e32 v102, v50, v10
	v_fmac_f32_e32 v12, v34, v60
	v_fmac_f32_e32 v102, v51, v11
	ds_read_b128 v[70:73], v0 offset:5888
	v_fmac_f32_e32 v13, v35, v60
	v_fmac_f32_e32 v102, v52, v12
	v_fmac_f32_e32 v102, v53, v13
	ds_read_b32 v58, v1 offset:4416
	ds_write_b32 v107, v102 offset:10496
	s_waitcnt lgkmcnt(11)
	v_mul_f32_e32 v10, v62, v10
	v_mul_f32_e32 v11, v63, v11
	v_mul_f32_e32 v12, v64, v12
	s_waitcnt vmcnt(11)
	v_mul_f32_e32 v13, v65, v13
	v_fmac_f32_e32 v10, v20, v54
	v_fmac_f32_e32 v11, v21, v54
	v_lshlrev_b32_e32 v94, 16, v86
	v_mul_f32_e32 v61, v38, v10
	v_fmac_f32_e32 v12, v22, v54
	v_fmac_f32_e32 v61, v39, v11
	v_and_b32_e32 v95, 0xffff0000, v86
	v_fmac_f32_e32 v13, v23, v54
	v_fmac_f32_e32 v61, v40, v12
	v_fmac_f32_e32 v61, v41, v13
	v_lshlrev_b32_e32 v96, 16, v87
	ds_write_b32 v107, v61 offset:10752
	ds_read_b128 v[32:35], v0 offset:2688
	ds_read_b128 v[50:53], v0 offset:3712
	ds_read_b128 v[74:77], v0 offset:6016
	ds_read_b32 v60, v1 offset:4448
	s_waitcnt lgkmcnt(11)
	v_mul_f32_e32 v10, v66, v10
	v_mul_f32_e32 v11, v67, v11
	v_mul_f32_e32 v12, v68, v12
	v_and_b32_e32 v97, 0xffff0000, v87
	v_mul_f32_e32 v13, v69, v13
	v_fmac_f32_e32 v10, v24, v56
	v_fmac_f32_e32 v11, v25, v56
	ds_write_b128 v2, v[94:97] offset:0
	v_mul_f32_e32 v102, v42, v10
	v_fmac_f32_e32 v12, v26, v56
	v_fmac_f32_e32 v102, v43, v11
	v_lshlrev_b32_e32 v98, 16, v88
	v_fmac_f32_e32 v13, v27, v56
	v_fmac_f32_e32 v102, v44, v12
	v_fmac_f32_e32 v102, v45, v13
	v_and_b32_e32 v99, 0xffff0000, v88
	ds_write_b32 v107, v102 offset:11008
	ds_read_b128 v[20:23], v0 offset:2816
	ds_read_b128 v[38:41], v0 offset:3840
	ds_read_b128 v[62:65], v0 offset:6144
	ds_read_b32 v54, v1 offset:4480
	s_waitcnt lgkmcnt(12)
	v_mul_f32_e32 v10, v70, v10
	v_mul_f32_e32 v11, v71, v11
	v_mul_f32_e32 v12, v72, v12
	v_lshlrev_b32_e32 v100, 16, v89
	v_mul_f32_e32 v13, v73, v13
	v_fmac_f32_e32 v10, v28, v58
	v_fmac_f32_e32 v11, v29, v58
	v_and_b32_e32 v101, 0xffff0000, v89
	v_mul_f32_e32 v61, v46, v10
	v_fmac_f32_e32 v12, v30, v58
	v_fmac_f32_e32 v61, v47, v11
	ds_write_b128 v2, v[98:101] offset:16
	v_fmac_f32_e32 v13, v31, v58
	v_fmac_f32_e32 v61, v48, v12
	v_fmac_f32_e32 v61, v49, v13
	s_waitcnt vmcnt(10)
	ds_write_b32 v107, v61 offset:11264
	ds_read_b128 v[24:27], v0 offset:2944
	ds_read_b128 v[42:45], v0 offset:3968
	ds_read_b128 v[66:69], v0 offset:6272
	ds_read_b32 v56, v1 offset:4512
	s_waitcnt lgkmcnt(12)
	v_mul_f32_e32 v10, v74, v10
	v_mul_f32_e32 v11, v75, v11
	v_mul_f32_e32 v12, v76, v12
	v_lshlrev_b32_e32 v57, 16, v57
	v_mul_f32_e32 v13, v77, v13
	v_fmac_f32_e32 v10, v32, v60
	v_fmac_f32_e32 v11, v33, v60
	s_nop 0
	v_mul_f32_e32 v102, v50, v10
	v_fmac_f32_e32 v12, v34, v60
	v_fmac_f32_e32 v102, v51, v11
	ds_write_b32 v4, v57 offset:2048
	v_fmac_f32_e32 v13, v35, v60
	v_fmac_f32_e32 v102, v52, v12
	v_fmac_f32_e32 v102, v53, v13
	ds_read_b128 v[28:31], v0 offset:3072
	ds_write_b32 v107, v102 offset:11520
	ds_read_b128 v[46:49], v0 offset:4096
	ds_read_b128 v[70:73], v0 offset:6400
	ds_read_b32 v58, v1 offset:4544
	s_waitcnt lgkmcnt(12)
	v_mul_f32_e32 v10, v62, v10
	v_mul_f32_e32 v11, v63, v11
	v_mul_f32_e32 v12, v64, v12
	global_load_dwordx4 v[86:89], v5, s[94:95]
	global_load_ushort v57, v6, s[94:95]
	v_add_u32_e32 v5, v5, v9
	v_add_u32_e32 v6, 0x10000, v6
	v_mul_f32_e32 v13, v65, v13
	v_fmac_f32_e32 v10, v20, v54
	v_fmac_f32_e32 v11, v21, v54
	s_add_i32 m0, s29, 0x1200
	s_nop 0
	global_load_lds_dwordx4 v8, s[94:95]
	v_add_u32_e32 v8, 0x3180, v8
	v_mul_f32_e32 v61, v38, v10
	v_fmac_f32_e32 v12, v22, v54
	v_fmac_f32_e32 v61, v39, v11
	ds_read_b128 v[114:117], v112 offset:8704
	v_fmac_f32_e32 v13, v23, v54
	v_fmac_f32_e32 v61, v40, v12
	v_fmac_f32_e32 v61, v41, v13
	ds_read_b128 v[118:121], v113 offset:8704
	ds_write_b32 v107, v61 offset:11776
	ds_read_b128 v[32:35], v0 offset:3200
	ds_read_b128 v[50:53], v0 offset:4224
	ds_read_b128 v[74:77], v0 offset:6528
	ds_read_b32 v60, v1 offset:4576
	s_waitcnt lgkmcnt(13)
	v_mul_f32_e32 v10, v66, v10
	v_mul_f32_e32 v11, v67, v11
	v_mul_f32_e32 v12, v68, v12
	ds_read_b128 v[20:23], v0 offset:0
	v_mul_f32_e32 v13, v69, v13
	v_fmac_f32_e32 v10, v24, v56
	v_fmac_f32_e32 v11, v25, v56
	ds_read_b128 v[38:41], v0 offset:1024
	v_mul_f32_e32 v102, v42, v10
	v_fmac_f32_e32 v12, v26, v56
	v_fmac_f32_e32 v102, v43, v11
	s_waitcnt vmcnt(6)
	v_fmac_f32_e32 v13, v27, v56
	v_fmac_f32_e32 v102, v44, v12
	v_fmac_f32_e32 v102, v45, v13
	ds_read_b128 v[62:65], v0 offset:6656
	ds_write_b32 v107, v102 offset:12032
	ds_read_b32 v54, v1 offset:2048
	s_waitcnt lgkmcnt(12)
	v_mul_f32_e32 v10, v70, v10
	v_mul_f32_e32 v11, v71, v11
	v_mul_f32_e32 v12, v72, v12
	s_waitcnt lgkmcnt(10)
	v_mul_f32_e32 v13, v73, v13
	v_fmac_f32_e32 v10, v28, v58
	v_fmac_f32_e32 v11, v29, v58
	v_add_f32_e32 v114, v114, v118
	v_mul_f32_e32 v61, v46, v10
	v_fmac_f32_e32 v12, v30, v58
	v_fmac_f32_e32 v61, v47, v11
	v_add_f32_e32 v115, v115, v119
	v_fmac_f32_e32 v13, v31, v58
	v_fmac_f32_e32 v61, v48, v12
	v_fmac_f32_e32 v61, v49, v13
	v_add_f32_e32 v116, v116, v120
	ds_write_b32 v107, v61 offset:12288
	ds_read_b128 v[24:27], v0 offset:128
	ds_read_b128 v[42:45], v0 offset:1152
	ds_read_b128 v[66:69], v0 offset:6784
	ds_read_b32 v56, v1 offset:2080
	v_add_f32_e32 v117, v117, v121
	v_add_f32_e32 v114, v114, v115
	v_add_f32_e32 v116, v116, v117
	v_add_f32_e32 v114, v114, v116
	v_cvt_pk_bf16_f32 v19, v114, v114
	ds_write_b16 v105, v19 offset:13312
	s_waitcnt lgkmcnt(11)
	v_mul_f32_e32 v10, v74, v10
	v_mul_f32_e32 v11, v75, v11
	v_mul_f32_e32 v12, v76, v12
	ds_read_b128 v[28:31], v0 offset:256
	v_mul_f32_e32 v13, v77, v13
	v_fmac_f32_e32 v10, v32, v60
	v_fmac_f32_e32 v11, v33, v60
	ds_read_b128 v[46:49], v0 offset:1280
	v_mul_f32_e32 v102, v50, v10
	v_fmac_f32_e32 v12, v34, v60
	v_fmac_f32_e32 v102, v51, v11
	ds_read_b128 v[70:73], v0 offset:6912
	v_fmac_f32_e32 v13, v35, v60
	v_fmac_f32_e32 v102, v52, v12
	v_fmac_f32_e32 v102, v53, v13
	ds_read_b32 v58, v1 offset:2112
	ds_write_b32 v107, v102 offset:12544
	s_waitcnt lgkmcnt(11)
	v_mul_f32_e32 v10, v62, v10
	v_mul_f32_e32 v11, v63, v11
	v_mul_f32_e32 v12, v64, v12
	s_waitcnt vmcnt(11)
	v_mul_f32_e32 v13, v65, v13
	v_fmac_f32_e32 v10, v20, v54
	v_fmac_f32_e32 v11, v21, v54
	v_lshlrev_b32_e32 v94, 16, v90
	v_mul_f32_e32 v61, v38, v10
	v_fmac_f32_e32 v12, v22, v54
	v_fmac_f32_e32 v61, v39, v11
	v_and_b32_e32 v95, 0xffff0000, v90
	v_fmac_f32_e32 v13, v23, v54
	v_fmac_f32_e32 v61, v40, v12
	v_fmac_f32_e32 v61, v41, v13
	v_lshlrev_b32_e32 v96, 16, v91
	ds_write_b32 v107, v61 offset:8704
	ds_read_b128 v[32:35], v0 offset:384
	ds_read_b128 v[50:53], v0 offset:1408
	ds_read_b128 v[74:77], v0 offset:7040
	ds_read_b32 v60, v1 offset:2144
	s_waitcnt lgkmcnt(11)
	v_mul_f32_e32 v10, v66, v10
	v_mul_f32_e32 v11, v67, v11
	v_mul_f32_e32 v12, v68, v12
	v_and_b32_e32 v97, 0xffff0000, v91
	v_mul_f32_e32 v13, v69, v13
	v_fmac_f32_e32 v10, v24, v56
	v_fmac_f32_e32 v11, v25, v56
	ds_write_b128 v2, v[94:97] offset:2304
	v_mul_f32_e32 v102, v42, v10
	v_fmac_f32_e32 v12, v26, v56
	v_fmac_f32_e32 v102, v43, v11
	v_lshlrev_b32_e32 v98, 16, v92
	v_fmac_f32_e32 v13, v27, v56
	v_fmac_f32_e32 v102, v44, v12
	v_fmac_f32_e32 v102, v45, v13
	v_and_b32_e32 v99, 0xffff0000, v92
	ds_write_b32 v107, v102 offset:8960
	ds_read_b128 v[20:23], v0 offset:512
	ds_read_b128 v[38:41], v0 offset:1536
	ds_read_b128 v[62:65], v0 offset:7168
	ds_read_b32 v54, v1 offset:2176
	s_waitcnt lgkmcnt(12)
	v_mul_f32_e32 v10, v70, v10
	v_mul_f32_e32 v11, v71, v11
	v_mul_f32_e32 v12, v72, v12
	v_lshlrev_b32_e32 v100, 16, v93
	v_mul_f32_e32 v13, v73, v13
	v_fmac_f32_e32 v10, v28, v58
	v_fmac_f32_e32 v11, v29, v58
	v_and_b32_e32 v101, 0xffff0000, v93
	v_mul_f32_e32 v61, v46, v10
	v_fmac_f32_e32 v12, v30, v58
	v_fmac_f32_e32 v61, v47, v11
	ds_write_b128 v2, v[98:101] offset:2320
	v_fmac_f32_e32 v13, v31, v58
	v_fmac_f32_e32 v61, v48, v12
	v_fmac_f32_e32 v61, v49, v13
	s_waitcnt vmcnt(10)
	ds_write_b32 v107, v61 offset:9216
	ds_read_b128 v[24:27], v0 offset:640
	ds_read_b128 v[42:45], v0 offset:1664
	ds_read_b128 v[66:69], v0 offset:7296
	ds_read_b32 v56, v1 offset:2208
	s_waitcnt lgkmcnt(12)
	v_mul_f32_e32 v10, v74, v10
	v_mul_f32_e32 v11, v75, v11
	v_mul_f32_e32 v12, v76, v12
	v_lshlrev_b32_e32 v59, 16, v59
	v_mul_f32_e32 v13, v77, v13
	v_fmac_f32_e32 v10, v32, v60
	v_fmac_f32_e32 v11, v33, v60
	s_nop 0
	v_mul_f32_e32 v102, v50, v10
	v_fmac_f32_e32 v12, v34, v60
	v_fmac_f32_e32 v102, v51, v11
	ds_write_b32 v4, v59 offset:4352
	v_fmac_f32_e32 v13, v35, v60
	v_fmac_f32_e32 v102, v52, v12
	v_fmac_f32_e32 v102, v53, v13
	ds_read_b128 v[28:31], v0 offset:768
	ds_write_b32 v107, v102 offset:9472
	ds_read_b128 v[46:49], v0 offset:1792
	ds_read_b128 v[70:73], v0 offset:7424
	ds_read_b32 v58, v1 offset:2240
	s_waitcnt lgkmcnt(12)
	v_mul_f32_e32 v10, v62, v10
	v_mul_f32_e32 v11, v63, v11
	v_mul_f32_e32 v12, v64, v12
	global_load_dwordx4 v[90:93], v5, s[94:95]
	global_load_ushort v59, v6, s[94:95]
	v_add_u32_e32 v5, v5, v9
	v_add_u32_e32 v6, 0x10000, v6
	v_mul_f32_e32 v13, v65, v13
	v_fmac_f32_e32 v10, v20, v54
	v_fmac_f32_e32 v11, v21, v54
	s_add_i32 m0, s29, 0x1600
	s_nop 0
	global_load_lds_dwordx4 v8, s[94:95]
	v_add_u32_e32 v8, 0x3180, v8
	v_mul_f32_e32 v61, v38, v10
	v_fmac_f32_e32 v12, v22, v54
	v_fmac_f32_e32 v61, v39, v11
	ds_read_b128 v[114:117], v112 offset:10752
	v_fmac_f32_e32 v13, v23, v54
	v_fmac_f32_e32 v61, v40, v12
	v_fmac_f32_e32 v61, v41, v13
	ds_read_b128 v[118:121], v113 offset:10752
	ds_write_b32 v107, v61 offset:9728
	ds_read_b128 v[32:35], v0 offset:896
	ds_read_b128 v[50:53], v0 offset:1920
	ds_read_b128 v[74:77], v0 offset:7552
	ds_read_b32 v60, v1 offset:2272
	s_waitcnt lgkmcnt(13)
	v_mul_f32_e32 v10, v66, v10
	v_mul_f32_e32 v11, v67, v11
	v_mul_f32_e32 v12, v68, v12
	ds_read_b128 v[20:23], v0 offset:2304
	v_mul_f32_e32 v13, v69, v13
	v_fmac_f32_e32 v10, v24, v56
	v_fmac_f32_e32 v11, v25, v56
	ds_read_b128 v[38:41], v0 offset:3328
	v_mul_f32_e32 v102, v42, v10
	v_fmac_f32_e32 v12, v26, v56
	v_fmac_f32_e32 v102, v43, v11
	s_waitcnt vmcnt(6)
	v_fmac_f32_e32 v13, v27, v56
	v_fmac_f32_e32 v102, v44, v12
	v_fmac_f32_e32 v102, v45, v13
	ds_read_b128 v[62:65], v0 offset:7680
	ds_write_b32 v107, v102 offset:9984
	ds_read_b32 v54, v1 offset:4352
	s_waitcnt lgkmcnt(12)
	v_mul_f32_e32 v10, v70, v10
	v_mul_f32_e32 v11, v71, v11
	v_mul_f32_e32 v12, v72, v12
	s_waitcnt lgkmcnt(10)
	v_mul_f32_e32 v13, v73, v13
	v_fmac_f32_e32 v10, v28, v58
	v_fmac_f32_e32 v11, v29, v58
	v_add_f32_e32 v114, v114, v118
	v_mul_f32_e32 v61, v46, v10
	v_fmac_f32_e32 v12, v30, v58
	v_fmac_f32_e32 v61, v47, v11
	v_add_f32_e32 v115, v115, v119
	v_fmac_f32_e32 v13, v31, v58
	v_fmac_f32_e32 v61, v48, v12
	v_fmac_f32_e32 v61, v49, v13
	v_add_f32_e32 v116, v116, v120
	ds_write_b32 v107, v61 offset:10240
	ds_read_b128 v[24:27], v0 offset:2432
	ds_read_b128 v[42:45], v0 offset:3456
	ds_read_b128 v[66:69], v0 offset:7808
	ds_read_b32 v56, v1 offset:4384
	v_add_f32_e32 v117, v117, v121
	v_add_f32_e32 v114, v114, v115
	v_add_f32_e32 v116, v116, v117
	v_add_f32_e32 v114, v114, v116
	v_cvt_pk_bf16_f32 v19, v114, v114
	ds_write_b16 v105, v19 offset:13440
	s_waitcnt lgkmcnt(11)
	v_mul_f32_e32 v10, v74, v10
	v_mul_f32_e32 v11, v75, v11
	v_mul_f32_e32 v12, v76, v12
	ds_read_b128 v[28:31], v0 offset:2560
	v_mul_f32_e32 v13, v77, v13
	v_fmac_f32_e32 v10, v32, v60
	v_fmac_f32_e32 v11, v33, v60
	ds_read_b128 v[46:49], v0 offset:3584
	v_mul_f32_e32 v102, v50, v10
	v_fmac_f32_e32 v12, v34, v60
	v_fmac_f32_e32 v102, v51, v11
	ds_read_b128 v[70:73], v0 offset:7936
	v_fmac_f32_e32 v13, v35, v60
	v_fmac_f32_e32 v102, v52, v12
	v_fmac_f32_e32 v102, v53, v13
	ds_read_b32 v58, v1 offset:4416
	ds_write_b32 v107, v102 offset:10496
	s_waitcnt lgkmcnt(11)
	v_mul_f32_e32 v10, v62, v10
	v_mul_f32_e32 v11, v63, v11
	v_mul_f32_e32 v12, v64, v12
	s_waitcnt vmcnt(11)
	v_mul_f32_e32 v13, v65, v13
	v_fmac_f32_e32 v10, v20, v54
	v_fmac_f32_e32 v11, v21, v54
	v_lshlrev_b32_e32 v94, 16, v78
	v_mul_f32_e32 v61, v38, v10
	v_fmac_f32_e32 v12, v22, v54
	v_fmac_f32_e32 v61, v39, v11
	v_and_b32_e32 v95, 0xffff0000, v78
	v_fmac_f32_e32 v13, v23, v54
	v_fmac_f32_e32 v61, v40, v12
	v_fmac_f32_e32 v61, v41, v13
	v_lshlrev_b32_e32 v96, 16, v79
	ds_write_b32 v107, v61 offset:10752
	ds_read_b128 v[32:35], v0 offset:2688
	ds_read_b128 v[50:53], v0 offset:3712
	ds_read_b128 v[74:77], v0 offset:8064
	ds_read_b32 v60, v1 offset:4448
	s_waitcnt lgkmcnt(11)
	v_mul_f32_e32 v10, v66, v10
	v_mul_f32_e32 v11, v67, v11
	v_mul_f32_e32 v12, v68, v12
	v_and_b32_e32 v97, 0xffff0000, v79
	v_mul_f32_e32 v13, v69, v13
	v_fmac_f32_e32 v10, v24, v56
	v_fmac_f32_e32 v11, v25, v56
	ds_write_b128 v2, v[94:97] offset:0
	v_mul_f32_e32 v102, v42, v10
	v_fmac_f32_e32 v12, v26, v56
	v_fmac_f32_e32 v102, v43, v11
	v_lshlrev_b32_e32 v98, 16, v80
	v_fmac_f32_e32 v13, v27, v56
	v_fmac_f32_e32 v102, v44, v12
	v_fmac_f32_e32 v102, v45, v13
	v_and_b32_e32 v99, 0xffff0000, v80
	ds_write_b32 v107, v102 offset:11008
	ds_read_b128 v[20:23], v0 offset:2816
	ds_read_b128 v[38:41], v0 offset:3840
	ds_read_b128 v[62:65], v0 offset:8192
	ds_read_b32 v54, v1 offset:4480
	s_waitcnt lgkmcnt(12)
	v_mul_f32_e32 v10, v70, v10
	v_mul_f32_e32 v11, v71, v11
	v_mul_f32_e32 v12, v72, v12
	v_lshlrev_b32_e32 v100, 16, v81
	v_mul_f32_e32 v13, v73, v13
	v_fmac_f32_e32 v10, v28, v58
	v_fmac_f32_e32 v11, v29, v58
	v_and_b32_e32 v101, 0xffff0000, v81
	v_mul_f32_e32 v61, v46, v10
	v_fmac_f32_e32 v12, v30, v58
	v_fmac_f32_e32 v61, v47, v11
	ds_write_b128 v2, v[98:101] offset:16
	v_fmac_f32_e32 v13, v31, v58
	v_fmac_f32_e32 v61, v48, v12
	v_fmac_f32_e32 v61, v49, v13
	s_waitcnt vmcnt(10)
	ds_write_b32 v107, v61 offset:11264
	ds_read_b128 v[24:27], v0 offset:2944
	ds_read_b128 v[42:45], v0 offset:3968
	ds_read_b128 v[66:69], v0 offset:8320
	ds_read_b32 v56, v1 offset:4512
	s_waitcnt lgkmcnt(12)
	v_mul_f32_e32 v10, v74, v10
	v_mul_f32_e32 v11, v75, v11
	v_mul_f32_e32 v12, v76, v12
	v_lshlrev_b32_e32 v36, 16, v36
	v_mul_f32_e32 v13, v77, v13
	v_fmac_f32_e32 v10, v32, v60
	v_fmac_f32_e32 v11, v33, v60
	s_nop 0
	v_mul_f32_e32 v102, v50, v10
	v_fmac_f32_e32 v12, v34, v60
	v_fmac_f32_e32 v102, v51, v11
	ds_write_b32 v4, v36 offset:2048
	v_fmac_f32_e32 v13, v35, v60
	v_fmac_f32_e32 v102, v52, v12
	v_fmac_f32_e32 v102, v53, v13
	ds_read_b128 v[28:31], v0 offset:3072
	ds_write_b32 v107, v102 offset:11520
	ds_read_b128 v[46:49], v0 offset:4096
	ds_read_b128 v[70:73], v0 offset:8448
	ds_read_b32 v58, v1 offset:4544
	s_waitcnt lgkmcnt(12)
	v_mul_f32_e32 v10, v62, v10
	v_mul_f32_e32 v11, v63, v11
	v_mul_f32_e32 v12, v64, v12
	global_load_dwordx4 v[78:81], v5, s[94:95]
	global_load_ushort v36, v6, s[94:95]
	v_add_u32_e32 v5, v5, v9
	v_add_u32_e32 v6, 0x10000, v6
	v_mul_f32_e32 v13, v65, v13
	v_fmac_f32_e32 v10, v20, v54
	v_fmac_f32_e32 v11, v21, v54
	s_add_i32 m0, s29, 0x1a00
	s_nop 0
	global_load_lds_dwordx4 v8, s[94:95]
	v_add_u32_e32 v8, 0x3180, v8
	v_mul_f32_e32 v61, v38, v10
	v_fmac_f32_e32 v12, v22, v54
	v_fmac_f32_e32 v61, v39, v11
	ds_read_b128 v[114:117], v112 offset:8704
	v_fmac_f32_e32 v13, v23, v54
	v_fmac_f32_e32 v61, v40, v12
	v_fmac_f32_e32 v61, v41, v13
	ds_read_b128 v[118:121], v113 offset:8704
	ds_write_b32 v107, v61 offset:11776
	ds_read_b128 v[32:35], v0 offset:3200
	ds_read_b128 v[50:53], v0 offset:4224
	ds_read_b128 v[74:77], v0 offset:8576
	ds_read_b32 v60, v1 offset:4576
	s_waitcnt lgkmcnt(13)
	v_mul_f32_e32 v10, v66, v10
	v_mul_f32_e32 v11, v67, v11
	v_mul_f32_e32 v12, v68, v12
	ds_read_b128 v[20:23], v0 offset:0
	v_mul_f32_e32 v13, v69, v13
	v_fmac_f32_e32 v10, v24, v56
	v_fmac_f32_e32 v11, v25, v56
	ds_read_b128 v[38:41], v0 offset:1024
	v_mul_f32_e32 v102, v42, v10
	v_fmac_f32_e32 v12, v26, v56
	v_fmac_f32_e32 v102, v43, v11
	s_waitcnt vmcnt(6)
	v_fmac_f32_e32 v13, v27, v56
	v_fmac_f32_e32 v102, v44, v12
	v_fmac_f32_e32 v102, v45, v13
	ds_read_b128 v[62:65], v0 offset:4608
	ds_write_b32 v107, v102 offset:12032
	ds_read_b32 v54, v1 offset:2048
	s_waitcnt lgkmcnt(12)
	v_mul_f32_e32 v10, v70, v10
	v_mul_f32_e32 v11, v71, v11
	v_mul_f32_e32 v12, v72, v12
	s_waitcnt lgkmcnt(10)
	v_mul_f32_e32 v13, v73, v13
	v_fmac_f32_e32 v10, v28, v58
	v_fmac_f32_e32 v11, v29, v58
	v_add_f32_e32 v114, v114, v118
	v_mul_f32_e32 v61, v46, v10
	v_fmac_f32_e32 v12, v30, v58
	v_fmac_f32_e32 v61, v47, v11
	v_add_f32_e32 v115, v115, v119
	v_fmac_f32_e32 v13, v31, v58
	v_fmac_f32_e32 v61, v48, v12
	v_fmac_f32_e32 v61, v49, v13
	v_add_f32_e32 v116, v116, v120
	ds_write_b32 v107, v61 offset:12288
	ds_read_b128 v[24:27], v0 offset:128
	ds_read_b128 v[42:45], v0 offset:1152
	ds_read_b128 v[66:69], v0 offset:4736
	ds_read_b32 v56, v1 offset:2080
	v_add_f32_e32 v117, v117, v121
	v_add_f32_e32 v114, v114, v115
	v_add_f32_e32 v116, v116, v117
	v_add_f32_e32 v114, v114, v116
	v_cvt_pk_bf16_f32 v19, v114, v114
	ds_write_b16 v105, v19 offset:13568
	s_waitcnt lgkmcnt(11)
	v_mul_f32_e32 v10, v74, v10
	v_mul_f32_e32 v11, v75, v11
	v_mul_f32_e32 v12, v76, v12
	ds_read_b128 v[28:31], v0 offset:256
	v_mul_f32_e32 v13, v77, v13
	v_fmac_f32_e32 v10, v32, v60
	v_fmac_f32_e32 v11, v33, v60
	ds_read_b128 v[46:49], v0 offset:1280
	v_mul_f32_e32 v102, v50, v10
	v_fmac_f32_e32 v12, v34, v60
	v_fmac_f32_e32 v102, v51, v11
	ds_read_b128 v[70:73], v0 offset:4864
	v_fmac_f32_e32 v13, v35, v60
	v_fmac_f32_e32 v102, v52, v12
	v_fmac_f32_e32 v102, v53, v13
	ds_read_b32 v58, v1 offset:2112
	ds_write_b32 v107, v102 offset:12544
	s_sub_u32 s12, s12, 1
	s_cmp_lg_u32 s12, 0
	s_cbranch_scc1 .Lls1_8_loop
	ds_read_b128 v[114:117], v112 offset:10752
	ds_read_b128 v[118:121], v113 offset:10752
	s_waitcnt lgkmcnt(0)
	v_add_f32_e32 v114, v114, v118
	v_add_f32_e32 v115, v115, v119
	v_add_f32_e32 v116, v116, v120
	v_add_f32_e32 v117, v117, v121
	v_add_f32_e32 v114, v114, v115
	v_add_f32_e32 v116, v116, v117
	v_add_f32_e32 v114, v114, v116
	v_cvt_pk_bf16_f32 v19, v114, v114
	ds_write_b16 v105, v19 offset:13696
	s_waitcnt lgkmcnt(0)
	ds_read_b128 v[108:111], v106 offset:13312
	s_waitcnt lgkmcnt(0)
	global_store_dwordx4 v7, v[108:111], s[94:95]
	v_add_u32_e32 v7, 0x20000, v7
	s_nop 0
	ds_read_b128 v[108:111], v106 offset:14336
	s_waitcnt lgkmcnt(0)
	global_store_dwordx4 v7, v[108:111], s[94:95]
	v_add_u32_e32 v7, 0x20000, v7
	s_nop 0
	ds_read_b128 v[108:111], v106 offset:15360
	s_waitcnt lgkmcnt(0)
	global_store_dwordx4 v7, v[108:111], s[94:95]
	v_add_u32_e32 v7, 0x20000, v7
	s_nop 0
	ds_read_b128 v[108:111], v106 offset:16384
	s_waitcnt lgkmcnt(0)
	global_store_dwordx4 v7, v[108:111], s[94:95]
	v_add_u32_e32 v7, 0x20000, v7
	s_nop 0
	ds_read_b128 v[108:111], v106 offset:17408
	s_waitcnt lgkmcnt(0)
	global_store_dwordx4 v7, v[108:111], s[94:95]
	v_add_u32_e32 v7, 0x20000, v7
	s_nop 0
	ds_read_b128 v[108:111], v106 offset:18432
	s_waitcnt lgkmcnt(0)
	global_store_dwordx4 v7, v[108:111], s[94:95]
	v_add_u32_e32 v7, 0x20000, v7
	s_nop 0
	ds_read_b128 v[108:111], v106 offset:19456
	s_waitcnt lgkmcnt(0)
	global_store_dwordx4 v7, v[108:111], s[94:95]
	v_add_u32_e32 v7, 0x20000, v7
	s_nop 0
	ds_read_b128 v[108:111], v106 offset:20480
	s_waitcnt lgkmcnt(0)
	global_store_dwordx4 v7, v[108:111], s[94:95]
	v_add_u32_e32 v7, 0x20000, v7
	s_nop 0
	global_store_dword v104, v10, s[26:27] offset:0
	global_store_dword v104, v11, s[26:27] offset:256
	global_store_dword v104, v12, s[26:27] offset:512
	global_store_dword v104, v13, s[26:27] offset:768
	s_waitcnt vmcnt(0) lgkmcnt(0)
	s_branch .Lls_done
